# v23 + shorten the critical MFMA part of all 56 GEMM K-loop segments: priority toggles moved outside the segment barriers, mid-segment toggle pair and the redundant post-barrier lgkmcnt(0) removed
# speedup vs baseline: 1.0036x; 1.0036x over previous
.LBB0_91:
	ds_read_b128 v[150:153], v158
	ds_read_b128 v[162:165], v158 offset:1024
	ds_read_b128 v[166:169], v158 offset:2048
	ds_read_b128 v[170:173], v158 offset:3072
	ds_read_b128 v[174:177], v159
	ds_read_b128 v[178:181], v159 offset:1024
	ds_read_b128 v[182:185], v159 offset:2048
	ds_read_b128 v[186:189], v159 offset:3072
	s_add_u32 s36, s34, 0xfff00080
	s_addc_u32 s37, s35, -1
	s_cmp_eq_u32 s57, 60
	s_cselect_b32 s39, s2, s37
	s_cselect_b32 s38, s25, s36
	s_cselect_b32 s37, s23, s56
	s_cselect_b32 s36, s54, s55
	v_lshl_add_u64 v[146:147], s[34:35], 0, v[138:139]
	s_add_i32 m0, s43, 0xc000
	ds_read_b128 v[190:193], v160
	ds_read_b128 v[194:197], v160 offset:1024
	ds_read_b128 v[198:201], v160 offset:2048
	ds_read_b128 v[202:205], v160 offset:3072
	ds_read_b128 v[206:209], v160 offset:4096
	ds_read_b128 v[210:213], v160 offset:5120
	ds_read_b128 v[214:217], v160 offset:6144
	ds_read_b128 v[218:221], v160 offset:7168
	global_load_lds_dwordx4 v[146:147], off
	v_lshl_add_u64 v[146:147], s[34:35], 0, v[140:141]
	s_add_i32 m0, s43, 0xe000
	s_nop 0
	global_load_lds_dwordx4 v[146:147], off
	s_waitcnt vmcnt(8)
	s_waitcnt lgkmcnt(0)
	s_setprio 1
	s_barrier
	v_mfma_f32_16x16x32_bf16 v[78:81], v[150:153], v[190:193], v[78:81]
	v_mfma_f32_16x16x32_bf16 v[70:73], v[166:169], v[190:193], v[70:73]
	v_mfma_f32_16x16x32_bf16 v[62:65], v[150:153], v[198:201], v[62:65]
	v_mfma_f32_16x16x32_bf16 v[58:61], v[166:169], v[198:201], v[58:61]
	v_mfma_f32_16x16x32_bf16 v[54:57], v[150:153], v[206:209], v[54:57]
	v_mfma_f32_16x16x32_bf16 v[50:53], v[166:169], v[206:209], v[50:53]
	v_mfma_f32_16x16x32_bf16 v[46:49], v[150:153], v[214:217], v[46:49]
	v_mfma_f32_16x16x32_bf16 v[42:45], v[166:169], v[214:217], v[42:45]
	v_mfma_f32_16x16x32_bf16 v[78:81], v[162:165], v[194:197], v[78:81]
	v_mfma_f32_16x16x32_bf16 v[70:73], v[170:173], v[194:197], v[70:73]
	v_mfma_f32_16x16x32_bf16 v[62:65], v[162:165], v[202:205], v[62:65]
	v_mfma_f32_16x16x32_bf16 v[58:61], v[170:173], v[202:205], v[58:61]
	v_mfma_f32_16x16x32_bf16 v[54:57], v[162:165], v[210:213], v[54:57]
	v_mfma_f32_16x16x32_bf16 v[50:53], v[170:173], v[210:213], v[50:53]
	v_mfma_f32_16x16x32_bf16 v[46:49], v[162:165], v[218:221], v[46:49]
	v_mfma_f32_16x16x32_bf16 v[42:45], v[170:173], v[218:221], v[42:45]
	v_mfma_f32_16x16x32_bf16 v[126:129], v[174:177], v[190:193], v[126:129]
	v_mfma_f32_16x16x32_bf16 v[122:125], v[182:185], v[190:193], v[122:125]
	v_mfma_f32_16x16x32_bf16 v[118:121], v[174:177], v[198:201], v[118:121]
	v_mfma_f32_16x16x32_bf16 v[114:117], v[182:185], v[198:201], v[114:117]
	v_mfma_f32_16x16x32_bf16 v[110:113], v[174:177], v[206:209], v[110:113]
	v_mfma_f32_16x16x32_bf16 v[106:109], v[182:185], v[206:209], v[106:109]
	v_mfma_f32_16x16x32_bf16 v[102:105], v[174:177], v[214:217], v[102:105]
	v_mfma_f32_16x16x32_bf16 v[98:101], v[182:185], v[214:217], v[98:101]
	v_mfma_f32_16x16x32_bf16 v[126:129], v[178:181], v[194:197], v[126:129]
	v_mfma_f32_16x16x32_bf16 v[122:125], v[186:189], v[194:197], v[122:125]
	v_mfma_f32_16x16x32_bf16 v[118:121], v[178:181], v[202:205], v[118:121]
	v_mfma_f32_16x16x32_bf16 v[114:117], v[186:189], v[202:205], v[114:117]
	v_mfma_f32_16x16x32_bf16 v[110:113], v[178:181], v[210:213], v[110:113]
	v_mfma_f32_16x16x32_bf16 v[106:109], v[186:189], v[210:213], v[106:109]
	v_mfma_f32_16x16x32_bf16 v[102:105], v[178:181], v[218:221], v[102:105]
	v_mfma_f32_16x16x32_bf16 v[98:101], v[186:189], v[218:221], v[98:101]
	s_barrier
	s_setprio 0
	s_add_i32 s58, s51, s40
	v_lshl_add_u64 v[146:147], s[36:37], 0, v[134:135]
	s_mov_b32 m0, s58
	ds_read_b128 v[190:193], v160 offset:16384
	ds_read_b128 v[194:197], v160 offset:17408
	ds_read_b128 v[198:201], v160 offset:18432
	ds_read_b128 v[202:205], v160 offset:19456
	ds_read_b128 v[206:209], v160 offset:20480
	ds_read_b128 v[210:213], v160 offset:21504
	ds_read_b128 v[214:217], v160 offset:22528
	ds_read_b128 v[218:221], v160 offset:23552
	global_load_lds_dwordx4 v[146:147], off
	s_add_i32 m0, s58, 0x2000
	s_add_u32 s58, s36, 0x100000
	v_lshl_add_u64 v[222:223], s[36:37], 0, v[130:131]
	s_addc_u32 s59, s37, 0
	s_add_i32 s60, s52, s40
	global_load_lds_dwordx4 v[222:223], off
	v_lshl_add_u64 v[224:225], s[58:59], 0, v[134:135]
	s_mov_b32 m0, s60
	v_lshl_add_u64 v[226:227], s[38:39], 0, v[132:133]
	global_load_lds_dwordx4 v[224:225], off
	v_lshl_add_u64 v[224:225], s[58:59], 0, v[130:131]
	s_add_i32 m0, s60, 0x2000
	s_nop 0
	global_load_lds_dwordx4 v[224:225], off
	v_lshl_add_u64 v[224:225], s[38:39], 0, v[136:137]
	s_mov_b32 m0, s43
	s_nop 0
	global_load_lds_dwordx4 v[224:225], off
	s_mov_b32 m0, s44
	s_nop 0
	global_load_lds_dwordx4 v[226:227], off
	s_waitcnt vmcnt(8)
	s_waitcnt lgkmcnt(0)
	s_setprio 1
	s_barrier
	v_mfma_f32_16x16x32_bf16 v[30:33], v[150:153], v[190:193], v[30:33]
	v_mfma_f32_16x16x32_bf16 v[26:29], v[166:169], v[190:193], v[26:29]
	v_mfma_f32_16x16x32_bf16 v[22:25], v[150:153], v[198:201], v[22:25]
	v_mfma_f32_16x16x32_bf16 v[18:21], v[166:169], v[198:201], v[18:21]
	v_mfma_f32_16x16x32_bf16 v[14:17], v[150:153], v[206:209], v[14:17]
	v_mfma_f32_16x16x32_bf16 v[10:13], v[166:169], v[206:209], v[10:13]
	v_mfma_f32_16x16x32_bf16 v[6:9], v[150:153], v[214:217], v[6:9]
	v_mfma_f32_16x16x32_bf16 v[2:5], v[166:169], v[214:217], v[2:5]
	v_mfma_f32_16x16x32_bf16 v[30:33], v[162:165], v[194:197], v[30:33]
	v_mfma_f32_16x16x32_bf16 v[26:29], v[170:173], v[194:197], v[26:29]
	v_mfma_f32_16x16x32_bf16 v[22:25], v[162:165], v[202:205], v[22:25]
	v_mfma_f32_16x16x32_bf16 v[18:21], v[170:173], v[202:205], v[18:21]
	v_mfma_f32_16x16x32_bf16 v[14:17], v[162:165], v[210:213], v[14:17]
	v_mfma_f32_16x16x32_bf16 v[10:13], v[170:173], v[210:213], v[10:13]
	v_mfma_f32_16x16x32_bf16 v[6:9], v[162:165], v[218:221], v[6:9]
	v_mfma_f32_16x16x32_bf16 v[2:5], v[170:173], v[218:221], v[2:5]
	v_mfma_f32_16x16x32_bf16 v[94:97], v[174:177], v[190:193], v[94:97]
	v_mfma_f32_16x16x32_bf16 v[90:93], v[182:185], v[190:193], v[90:93]
	v_mfma_f32_16x16x32_bf16 v[86:89], v[174:177], v[198:201], v[86:89]
	v_mfma_f32_16x16x32_bf16 v[82:85], v[182:185], v[198:201], v[82:85]
	v_mfma_f32_16x16x32_bf16 v[74:77], v[174:177], v[206:209], v[74:77]
	v_mfma_f32_16x16x32_bf16 v[66:69], v[182:185], v[206:209], v[66:69]
	v_mfma_f32_16x16x32_bf16 v[38:41], v[174:177], v[214:217], v[38:41]
	v_mfma_f32_16x16x32_bf16 v[34:37], v[182:185], v[214:217], v[34:37]
	v_mfma_f32_16x16x32_bf16 v[94:97], v[178:181], v[194:197], v[94:97]
	v_mfma_f32_16x16x32_bf16 v[90:93], v[186:189], v[194:197], v[90:93]
	v_mfma_f32_16x16x32_bf16 v[86:89], v[178:181], v[202:205], v[86:89]
	v_mfma_f32_16x16x32_bf16 v[82:85], v[186:189], v[202:205], v[82:85]
	v_mfma_f32_16x16x32_bf16 v[74:77], v[178:181], v[210:213], v[74:77]
	v_mfma_f32_16x16x32_bf16 v[66:69], v[186:189], v[210:213], v[66:69]
	v_mfma_f32_16x16x32_bf16 v[38:41], v[178:181], v[218:221], v[38:41]
	v_mfma_f32_16x16x32_bf16 v[34:37], v[186:189], v[218:221], v[34:37]
	s_barrier
	s_setprio 0
	s_add_i32 s58, 0, 0x18000
	v_add_u32_e32 v148, s58, v156
	s_add_i32 s59, 0, 0x1c000
	ds_read_b128 v[150:153], v148
	ds_read_b128 v[162:165], v148 offset:1024
	ds_read_b128 v[166:169], v148 offset:2048
	ds_read_b128 v[170:173], v148 offset:3072
	v_add_u32_e32 v148, s59, v156
	ds_read_b128 v[174:177], v148
	ds_read_b128 v[178:181], v148 offset:1024
	ds_read_b128 v[182:185], v148 offset:2048
	ds_read_b128 v[186:189], v148 offset:3072
	s_add_u32 s38, s38, 0x100000
	s_addc_u32 s39, s39, 0
	s_mov_b32 m0, s45
	v_lshl_add_u64 v[228:229], s[38:39], 0, v[136:137]
	ds_read_b128 v[190:193], v160 offset:32768
	ds_read_b128 v[194:197], v160 offset:33792
	ds_read_b128 v[198:201], v160 offset:34816
	ds_read_b128 v[202:205], v160 offset:35840
	ds_read_b128 v[206:209], v160 offset:36864
	ds_read_b128 v[210:213], v160 offset:37888
	ds_read_b128 v[214:217], v160 offset:38912
	ds_read_b128 v[218:221], v160 offset:39936
	global_load_lds_dwordx4 v[228:229], off
	v_lshl_add_u64 v[228:229], s[38:39], 0, v[132:133]
	s_mov_b32 m0, s46
	s_nop 0
	global_load_lds_dwordx4 v[228:229], off
	s_waitcnt vmcnt(8)
	s_waitcnt lgkmcnt(0)
	s_setprio 1
	s_barrier
	v_mfma_f32_16x16x32_bf16 v[78:81], v[150:153], v[190:193], v[78:81]
	v_mfma_f32_16x16x32_bf16 v[70:73], v[166:169], v[190:193], v[70:73]
	v_mfma_f32_16x16x32_bf16 v[62:65], v[150:153], v[198:201], v[62:65]
	v_mfma_f32_16x16x32_bf16 v[58:61], v[166:169], v[198:201], v[58:61]
	v_mfma_f32_16x16x32_bf16 v[54:57], v[150:153], v[206:209], v[54:57]
	v_mfma_f32_16x16x32_bf16 v[50:53], v[166:169], v[206:209], v[50:53]
	v_mfma_f32_16x16x32_bf16 v[46:49], v[150:153], v[214:217], v[46:49]
	v_mfma_f32_16x16x32_bf16 v[42:45], v[166:169], v[214:217], v[42:45]
	v_mfma_f32_16x16x32_bf16 v[78:81], v[162:165], v[194:197], v[78:81]
	v_mfma_f32_16x16x32_bf16 v[70:73], v[170:173], v[194:197], v[70:73]
	v_mfma_f32_16x16x32_bf16 v[62:65], v[162:165], v[202:205], v[62:65]
	v_mfma_f32_16x16x32_bf16 v[58:61], v[170:173], v[202:205], v[58:61]
	v_mfma_f32_16x16x32_bf16 v[54:57], v[162:165], v[210:213], v[54:57]
	v_mfma_f32_16x16x32_bf16 v[50:53], v[170:173], v[210:213], v[50:53]
	v_mfma_f32_16x16x32_bf16 v[46:49], v[162:165], v[218:221], v[46:49]
	v_mfma_f32_16x16x32_bf16 v[42:45], v[170:173], v[218:221], v[42:45]
	v_mfma_f32_16x16x32_bf16 v[126:129], v[174:177], v[190:193], v[126:129]
	v_mfma_f32_16x16x32_bf16 v[122:125], v[182:185], v[190:193], v[122:125]
	v_mfma_f32_16x16x32_bf16 v[118:121], v[174:177], v[198:201], v[118:121]
	v_mfma_f32_16x16x32_bf16 v[114:117], v[182:185], v[198:201], v[114:117]
	v_mfma_f32_16x16x32_bf16 v[110:113], v[174:177], v[206:209], v[110:113]
	v_mfma_f32_16x16x32_bf16 v[106:109], v[182:185], v[206:209], v[106:109]
	v_mfma_f32_16x16x32_bf16 v[102:105], v[174:177], v[214:217], v[102:105]
	v_mfma_f32_16x16x32_bf16 v[98:101], v[182:185], v[214:217], v[98:101]
	v_mfma_f32_16x16x32_bf16 v[126:129], v[178:181], v[194:197], v[126:129]
	v_mfma_f32_16x16x32_bf16 v[122:125], v[186:189], v[194:197], v[122:125]
	v_mfma_f32_16x16x32_bf16 v[118:121], v[178:181], v[202:205], v[118:121]
	v_mfma_f32_16x16x32_bf16 v[114:117], v[186:189], v[202:205], v[114:117]
	v_mfma_f32_16x16x32_bf16 v[110:113], v[178:181], v[210:213], v[110:113]
	v_mfma_f32_16x16x32_bf16 v[106:109], v[186:189], v[210:213], v[106:109]
	v_mfma_f32_16x16x32_bf16 v[102:105], v[178:181], v[218:221], v[102:105]
	v_mfma_f32_16x16x32_bf16 v[98:101], v[186:189], v[218:221], v[98:101]
	s_barrier
	s_setprio 0
	s_add_i32 s38, s58, s40
	v_lshl_add_u64 v[146:147], v[146:147], 0, s[18:19]
	s_mov_b32 m0, s38
	ds_read_b128 v[190:193], v160 offset:49152
	ds_read_b128 v[194:197], v160 offset:50176
	ds_read_b128 v[198:201], v160 offset:51200
	ds_read_b128 v[202:205], v160 offset:52224
	ds_read_b128 v[206:209], v160 offset:53248
	ds_read_b128 v[210:213], v160 offset:54272
	ds_read_b128 v[214:217], v160 offset:55296
	ds_read_b128 v[218:221], v160 offset:56320
	global_load_lds_dwordx4 v[146:147], off
	s_add_i32 m0, s38, 0x2000
	s_add_u32 s36, s36, 0x100080
	v_lshl_add_u64 v[146:147], v[222:223], 0, s[18:19]
	s_addc_u32 s37, s37, 0
	s_add_i32 s38, s59, s40
	global_load_lds_dwordx4 v[146:147], off
	v_lshl_add_u64 v[146:147], s[36:37], 0, v[134:135]
	s_mov_b32 m0, s38
	s_nop 0
	global_load_lds_dwordx4 v[146:147], off
	v_lshl_add_u64 v[146:147], s[36:37], 0, v[130:131]
	s_add_i32 m0, s38, 0x2000
	s_nop 0
	global_load_lds_dwordx4 v[146:147], off
	v_lshl_add_u64 v[146:147], v[224:225], 0, s[18:19]
	s_mov_b32 m0, s48
	s_nop 0
	global_load_lds_dwordx4 v[146:147], off
	v_lshl_add_u64 v[146:147], v[226:227], 0, s[18:19]
	s_mov_b32 m0, s49
	s_nop 0
	global_load_lds_dwordx4 v[146:147], off
	s_waitcnt vmcnt(8)
	s_waitcnt lgkmcnt(0)
	s_setprio 1
	s_barrier
	v_mfma_f32_16x16x32_bf16 v[30:33], v[150:153], v[190:193], v[30:33]
	v_mfma_f32_16x16x32_bf16 v[26:29], v[166:169], v[190:193], v[26:29]
	v_mfma_f32_16x16x32_bf16 v[22:25], v[150:153], v[198:201], v[22:25]
	v_mfma_f32_16x16x32_bf16 v[18:21], v[166:169], v[198:201], v[18:21]
	v_mfma_f32_16x16x32_bf16 v[14:17], v[150:153], v[206:209], v[14:17]
	v_mfma_f32_16x16x32_bf16 v[10:13], v[166:169], v[206:209], v[10:13]
	v_mfma_f32_16x16x32_bf16 v[6:9], v[150:153], v[214:217], v[6:9]
	v_mfma_f32_16x16x32_bf16 v[2:5], v[166:169], v[214:217], v[2:5]
	v_mfma_f32_16x16x32_bf16 v[30:33], v[162:165], v[194:197], v[30:33]
	v_mfma_f32_16x16x32_bf16 v[26:29], v[170:173], v[194:197], v[26:29]
	v_mfma_f32_16x16x32_bf16 v[22:25], v[162:165], v[202:205], v[22:25]
	v_mfma_f32_16x16x32_bf16 v[18:21], v[170:173], v[202:205], v[18:21]
	v_mfma_f32_16x16x32_bf16 v[14:17], v[162:165], v[210:213], v[14:17]
	v_mfma_f32_16x16x32_bf16 v[10:13], v[170:173], v[210:213], v[10:13]
	v_mfma_f32_16x16x32_bf16 v[6:9], v[162:165], v[218:221], v[6:9]
	v_mfma_f32_16x16x32_bf16 v[2:5], v[170:173], v[218:221], v[2:5]
	v_mfma_f32_16x16x32_bf16 v[94:97], v[174:177], v[190:193], v[94:97]
	v_mfma_f32_16x16x32_bf16 v[90:93], v[182:185], v[190:193], v[90:93]
	v_mfma_f32_16x16x32_bf16 v[86:89], v[174:177], v[198:201], v[86:89]
	v_mfma_f32_16x16x32_bf16 v[82:85], v[182:185], v[198:201], v[82:85]
	v_mfma_f32_16x16x32_bf16 v[74:77], v[174:177], v[206:209], v[74:77]
	v_mfma_f32_16x16x32_bf16 v[66:69], v[182:185], v[206:209], v[66:69]
	v_mfma_f32_16x16x32_bf16 v[38:41], v[174:177], v[214:217], v[38:41]
	v_mfma_f32_16x16x32_bf16 v[34:37], v[182:185], v[214:217], v[34:37]
	v_mfma_f32_16x16x32_bf16 v[94:97], v[178:181], v[194:197], v[94:97]
	v_mfma_f32_16x16x32_bf16 v[90:93], v[186:189], v[194:197], v[90:93]
	v_mfma_f32_16x16x32_bf16 v[86:89], v[178:181], v[202:205], v[86:89]
	v_mfma_f32_16x16x32_bf16 v[82:85], v[186:189], v[202:205], v[82:85]
	v_mfma_f32_16x16x32_bf16 v[74:77], v[178:181], v[210:213], v[74:77]
	v_mfma_f32_16x16x32_bf16 v[66:69], v[186:189], v[210:213], v[66:69]
	v_mfma_f32_16x16x32_bf16 v[38:41], v[178:181], v[218:221], v[38:41]
	v_mfma_f32_16x16x32_bf16 v[34:37], v[186:189], v[218:221], v[34:37]
	s_barrier
	s_setprio 0
	s_add_i32 s57, s57, 2
	s_add_u32 s34, s34, 0x100
	s_addc_u32 s35, s35, 0
	s_add_u32 s55, s55, 0x100
	s_addc_u32 s56, s56, 0
	s_cmp_gt_u32 s57, 61
	s_cbranch_scc0 .LBB0_91
	s_and_b64 vcc, exec, s[20:21]
	s_cbranch_vccz .LBB0_94
	s_barrier

.LBB0_317:
	ds_read_b128 v[148:151], v166
	ds_read_b128 v[170:173], v166 offset:1024
	ds_read_b128 v[174:177], v166 offset:2048
	ds_read_b128 v[178:181], v166 offset:3072
	ds_read_b128 v[182:185], v167
	ds_read_b128 v[186:189], v167 offset:1024
	ds_read_b128 v[190:193], v167 offset:2048
	ds_read_b128 v[194:197], v167 offset:3072
	s_add_u32 s28, s26, 0xfffc0080
	s_addc_u32 s29, s27, -1
	s_cmp_eq_u32 s53, 12
	s_cselect_b32 s31, s19, s29
	s_cselect_b32 s30, s49, s28
	s_cselect_b32 s29, s17, s52
	s_cselect_b32 s28, s50, s51
	v_lshl_add_u64 v[230:231], s[26:27], 0, v[138:139]
	s_add_i32 m0, s25, 0xc000
	ds_read_b128 v[198:201], v168
	ds_read_b128 v[202:205], v168 offset:1024
	ds_read_b128 v[206:209], v168 offset:2048
	ds_read_b128 v[210:213], v168 offset:3072
	ds_read_b128 v[214:217], v168 offset:4096
	ds_read_b128 v[218:221], v168 offset:5120
	ds_read_b128 v[222:225], v168 offset:6144
	ds_read_b128 v[226:229], v168 offset:7168
	global_load_lds_dwordx4 v[230:231], off
	v_lshl_add_u64 v[230:231], s[26:27], 0, v[140:141]
	s_add_i32 m0, s25, 0xe000
	s_nop 0
	global_load_lds_dwordx4 v[230:231], off
	s_waitcnt vmcnt(8)
	s_waitcnt lgkmcnt(0)
	s_setprio 1
	s_barrier
	v_mfma_f32_16x16x32_bf16 v[126:129], v[148:151], v[198:201], v[126:129]
	v_mfma_f32_16x16x32_bf16 v[122:125], v[174:177], v[198:201], v[122:125]
	v_mfma_f32_16x16x32_bf16 v[114:117], v[148:151], v[206:209], v[114:117]
	v_mfma_f32_16x16x32_bf16 v[106:109], v[174:177], v[206:209], v[106:109]
	v_mfma_f32_16x16x32_bf16 v[98:101], v[148:151], v[214:217], v[98:101]
	v_mfma_f32_16x16x32_bf16 v[90:93], v[174:177], v[214:217], v[90:93]
	v_mfma_f32_16x16x32_bf16 v[82:85], v[148:151], v[222:225], v[82:85]
	v_mfma_f32_16x16x32_bf16 v[74:77], v[174:177], v[222:225], v[74:77]
	v_mfma_f32_16x16x32_bf16 v[126:129], v[170:173], v[202:205], v[126:129]
	v_mfma_f32_16x16x32_bf16 v[122:125], v[178:181], v[202:205], v[122:125]
	v_mfma_f32_16x16x32_bf16 v[114:117], v[170:173], v[210:213], v[114:117]
	v_mfma_f32_16x16x32_bf16 v[106:109], v[178:181], v[210:213], v[106:109]
	v_mfma_f32_16x16x32_bf16 v[98:101], v[170:173], v[218:221], v[98:101]
	v_mfma_f32_16x16x32_bf16 v[90:93], v[178:181], v[218:221], v[90:93]
	v_mfma_f32_16x16x32_bf16 v[82:85], v[170:173], v[226:229], v[82:85]
	v_mfma_f32_16x16x32_bf16 v[74:77], v[178:181], v[226:229], v[74:77]
	v_mfma_f32_16x16x32_bf16 v[118:121], v[182:185], v[198:201], v[118:121]
	v_mfma_f32_16x16x32_bf16 v[110:113], v[190:193], v[198:201], v[110:113]
	v_mfma_f32_16x16x32_bf16 v[102:105], v[182:185], v[206:209], v[102:105]
	v_mfma_f32_16x16x32_bf16 v[94:97], v[190:193], v[206:209], v[94:97]
	v_mfma_f32_16x16x32_bf16 v[86:89], v[182:185], v[214:217], v[86:89]
	v_mfma_f32_16x16x32_bf16 v[78:81], v[190:193], v[214:217], v[78:81]
	v_mfma_f32_16x16x32_bf16 v[70:73], v[182:185], v[222:225], v[70:73]
	v_mfma_f32_16x16x32_bf16 v[66:69], v[190:193], v[222:225], v[66:69]
	v_mfma_f32_16x16x32_bf16 v[118:121], v[186:189], v[202:205], v[118:121]
	v_mfma_f32_16x16x32_bf16 v[110:113], v[194:197], v[202:205], v[110:113]
	v_mfma_f32_16x16x32_bf16 v[102:105], v[186:189], v[210:213], v[102:105]
	v_mfma_f32_16x16x32_bf16 v[94:97], v[194:197], v[210:213], v[94:97]
	v_mfma_f32_16x16x32_bf16 v[86:89], v[186:189], v[218:221], v[86:89]
	v_mfma_f32_16x16x32_bf16 v[78:81], v[194:197], v[218:221], v[78:81]
	v_mfma_f32_16x16x32_bf16 v[70:73], v[186:189], v[226:229], v[70:73]
	v_mfma_f32_16x16x32_bf16 v[66:69], v[194:197], v[226:229], v[66:69]
	s_barrier
	s_setprio 0
	s_add_i32 s54, s46, s36
	v_lshl_add_u64 v[230:231], s[28:29], 0, v[134:135]
	s_mov_b32 m0, s54
	ds_read_b128 v[198:201], v168 offset:16384
	ds_read_b128 v[202:205], v168 offset:17408
	ds_read_b128 v[206:209], v168 offset:18432
	ds_read_b128 v[210:213], v168 offset:19456
	ds_read_b128 v[214:217], v168 offset:20480
	ds_read_b128 v[218:221], v168 offset:21504
	ds_read_b128 v[222:225], v168 offset:22528
	ds_read_b128 v[226:229], v168 offset:23552
	global_load_lds_dwordx4 v[230:231], off
	s_add_i32 m0, s54, 0x2000
	s_add_u32 s54, s28, 0x40000
	v_lshl_add_u64 v[232:233], s[28:29], 0, v[130:131]
	s_addc_u32 s55, s29, 0
	s_add_i32 s56, s47, s36
	global_load_lds_dwordx4 v[232:233], off
	v_lshl_add_u64 v[234:235], s[54:55], 0, v[134:135]
	s_mov_b32 m0, s56
	v_lshl_add_u64 v[236:237], s[30:31], 0, v[132:133]
	global_load_lds_dwordx4 v[234:235], off
	v_lshl_add_u64 v[234:235], s[54:55], 0, v[130:131]
	s_add_i32 m0, s56, 0x2000
	s_nop 0
	global_load_lds_dwordx4 v[234:235], off
	v_lshl_add_u64 v[234:235], s[30:31], 0, v[136:137]
	s_mov_b32 m0, s25
	s_nop 0
	global_load_lds_dwordx4 v[234:235], off
	s_mov_b32 m0, s38
	s_nop 0
	global_load_lds_dwordx4 v[236:237], off
	s_waitcnt vmcnt(8)
	s_waitcnt lgkmcnt(0)
	s_setprio 1
	s_barrier
	v_mfma_f32_16x16x32_bf16 v[62:65], v[148:151], v[198:201], v[62:65]
	v_mfma_f32_16x16x32_bf16 v[58:61], v[174:177], v[198:201], v[58:61]
	v_mfma_f32_16x16x32_bf16 v[50:53], v[148:151], v[206:209], v[50:53]
	v_mfma_f32_16x16x32_bf16 v[42:45], v[174:177], v[206:209], v[42:45]
	v_mfma_f32_16x16x32_bf16 v[34:37], v[148:151], v[214:217], v[34:37]
	v_mfma_f32_16x16x32_bf16 v[26:29], v[174:177], v[214:217], v[26:29]
	v_mfma_f32_16x16x32_bf16 v[18:21], v[148:151], v[222:225], v[18:21]
	v_mfma_f32_16x16x32_bf16 v[10:13], v[174:177], v[222:225], v[10:13]
	v_mfma_f32_16x16x32_bf16 v[62:65], v[170:173], v[202:205], v[62:65]
	v_mfma_f32_16x16x32_bf16 v[58:61], v[178:181], v[202:205], v[58:61]
	v_mfma_f32_16x16x32_bf16 v[50:53], v[170:173], v[210:213], v[50:53]
	v_mfma_f32_16x16x32_bf16 v[42:45], v[178:181], v[210:213], v[42:45]
	v_mfma_f32_16x16x32_bf16 v[34:37], v[170:173], v[218:221], v[34:37]
	v_mfma_f32_16x16x32_bf16 v[26:29], v[178:181], v[218:221], v[26:29]
	v_mfma_f32_16x16x32_bf16 v[18:21], v[170:173], v[226:229], v[18:21]
	v_mfma_f32_16x16x32_bf16 v[10:13], v[178:181], v[226:229], v[10:13]
	v_mfma_f32_16x16x32_bf16 v[54:57], v[182:185], v[198:201], v[54:57]
	v_mfma_f32_16x16x32_bf16 v[46:49], v[190:193], v[198:201], v[46:49]
	v_mfma_f32_16x16x32_bf16 v[38:41], v[182:185], v[206:209], v[38:41]
	v_mfma_f32_16x16x32_bf16 v[30:33], v[190:193], v[206:209], v[30:33]
	v_mfma_f32_16x16x32_bf16 v[22:25], v[182:185], v[214:217], v[22:25]
	v_mfma_f32_16x16x32_bf16 v[14:17], v[190:193], v[214:217], v[14:17]
	v_mfma_f32_16x16x32_bf16 v[6:9], v[182:185], v[222:225], v[6:9]
	v_mfma_f32_16x16x32_bf16 v[2:5], v[190:193], v[222:225], v[2:5]
	v_mfma_f32_16x16x32_bf16 v[54:57], v[186:189], v[202:205], v[54:57]
	v_mfma_f32_16x16x32_bf16 v[46:49], v[194:197], v[202:205], v[46:49]
	v_mfma_f32_16x16x32_bf16 v[38:41], v[186:189], v[210:213], v[38:41]
	v_mfma_f32_16x16x32_bf16 v[30:33], v[194:197], v[210:213], v[30:33]
	v_mfma_f32_16x16x32_bf16 v[22:25], v[186:189], v[218:221], v[22:25]
	v_mfma_f32_16x16x32_bf16 v[14:17], v[194:197], v[218:221], v[14:17]
	v_mfma_f32_16x16x32_bf16 v[6:9], v[186:189], v[226:229], v[6:9]
	v_mfma_f32_16x16x32_bf16 v[2:5], v[194:197], v[226:229], v[2:5]
	s_barrier
	s_setprio 0
	s_add_i32 s54, 0, 0x18000
	v_add_u32_e32 v146, s54, v164
	s_add_i32 s55, 0, 0x1c000
	ds_read_b128 v[148:151], v146
	ds_read_b128 v[170:173], v146 offset:1024
	ds_read_b128 v[174:177], v146 offset:2048
	ds_read_b128 v[178:181], v146 offset:3072
	v_add_u32_e32 v146, s55, v164
	ds_read_b128 v[182:185], v146
	ds_read_b128 v[186:189], v146 offset:1024
	ds_read_b128 v[190:193], v146 offset:2048
	ds_read_b128 v[194:197], v146 offset:3072
	s_add_u32 s30, s30, 0x40000
	s_addc_u32 s31, s31, 0
	s_mov_b32 m0, s39
	v_lshl_add_u64 v[238:239], s[30:31], 0, v[136:137]
	ds_read_b128 v[198:201], v168 offset:32768
	ds_read_b128 v[202:205], v168 offset:33792
	ds_read_b128 v[206:209], v168 offset:34816
	ds_read_b128 v[210:213], v168 offset:35840
	ds_read_b128 v[214:217], v168 offset:36864
	ds_read_b128 v[218:221], v168 offset:37888
	ds_read_b128 v[222:225], v168 offset:38912
	ds_read_b128 v[226:229], v168 offset:39936
	global_load_lds_dwordx4 v[238:239], off
	v_lshl_add_u64 v[238:239], s[30:31], 0, v[132:133]
	s_mov_b32 m0, s40
	s_nop 0
	global_load_lds_dwordx4 v[238:239], off
	s_waitcnt vmcnt(8)
	s_waitcnt lgkmcnt(0)
	s_setprio 1
	s_barrier
	v_mfma_f32_16x16x32_bf16 v[126:129], v[148:151], v[198:201], v[126:129]
	v_mfma_f32_16x16x32_bf16 v[122:125], v[174:177], v[198:201], v[122:125]
	v_mfma_f32_16x16x32_bf16 v[114:117], v[148:151], v[206:209], v[114:117]
	v_mfma_f32_16x16x32_bf16 v[106:109], v[174:177], v[206:209], v[106:109]
	v_mfma_f32_16x16x32_bf16 v[98:101], v[148:151], v[214:217], v[98:101]
	v_mfma_f32_16x16x32_bf16 v[90:93], v[174:177], v[214:217], v[90:93]
	v_mfma_f32_16x16x32_bf16 v[82:85], v[148:151], v[222:225], v[82:85]
	v_mfma_f32_16x16x32_bf16 v[74:77], v[174:177], v[222:225], v[74:77]
	v_mfma_f32_16x16x32_bf16 v[126:129], v[170:173], v[202:205], v[126:129]
	v_mfma_f32_16x16x32_bf16 v[122:125], v[178:181], v[202:205], v[122:125]
	v_mfma_f32_16x16x32_bf16 v[114:117], v[170:173], v[210:213], v[114:117]
	v_mfma_f32_16x16x32_bf16 v[106:109], v[178:181], v[210:213], v[106:109]
	v_mfma_f32_16x16x32_bf16 v[98:101], v[170:173], v[218:221], v[98:101]
	v_mfma_f32_16x16x32_bf16 v[90:93], v[178:181], v[218:221], v[90:93]
	v_mfma_f32_16x16x32_bf16 v[82:85], v[170:173], v[226:229], v[82:85]
	v_mfma_f32_16x16x32_bf16 v[74:77], v[178:181], v[226:229], v[74:77]
	v_mfma_f32_16x16x32_bf16 v[118:121], v[182:185], v[198:201], v[118:121]
	v_mfma_f32_16x16x32_bf16 v[110:113], v[190:193], v[198:201], v[110:113]
	v_mfma_f32_16x16x32_bf16 v[102:105], v[182:185], v[206:209], v[102:105]
	v_mfma_f32_16x16x32_bf16 v[94:97], v[190:193], v[206:209], v[94:97]
	v_mfma_f32_16x16x32_bf16 v[86:89], v[182:185], v[214:217], v[86:89]
	v_mfma_f32_16x16x32_bf16 v[78:81], v[190:193], v[214:217], v[78:81]
	v_mfma_f32_16x16x32_bf16 v[70:73], v[182:185], v[222:225], v[70:73]
	v_mfma_f32_16x16x32_bf16 v[66:69], v[190:193], v[222:225], v[66:69]
	v_mfma_f32_16x16x32_bf16 v[118:121], v[186:189], v[202:205], v[118:121]
	v_mfma_f32_16x16x32_bf16 v[110:113], v[194:197], v[202:205], v[110:113]
	v_mfma_f32_16x16x32_bf16 v[102:105], v[186:189], v[210:213], v[102:105]
	v_mfma_f32_16x16x32_bf16 v[94:97], v[194:197], v[210:213], v[94:97]
	v_mfma_f32_16x16x32_bf16 v[86:89], v[186:189], v[218:221], v[86:89]
	v_mfma_f32_16x16x32_bf16 v[78:81], v[194:197], v[218:221], v[78:81]
	v_mfma_f32_16x16x32_bf16 v[70:73], v[186:189], v[226:229], v[70:73]
	v_mfma_f32_16x16x32_bf16 v[66:69], v[194:197], v[226:229], v[66:69]
	s_barrier
	s_setprio 0
	s_add_i32 s30, s54, s36
	v_lshl_add_u64 v[230:231], v[230:231], 0, s[12:13]
	s_mov_b32 m0, s30
	ds_read_b128 v[198:201], v168 offset:49152
	ds_read_b128 v[202:205], v168 offset:50176
	ds_read_b128 v[206:209], v168 offset:51200
	ds_read_b128 v[210:213], v168 offset:52224
	ds_read_b128 v[214:217], v168 offset:53248
	ds_read_b128 v[218:221], v168 offset:54272
	ds_read_b128 v[222:225], v168 offset:55296
	ds_read_b128 v[226:229], v168 offset:56320
	global_load_lds_dwordx4 v[230:231], off
	s_add_i32 m0, s30, 0x2000
	s_add_u32 s28, s28, 0x40080
	v_lshl_add_u64 v[230:231], v[232:233], 0, s[12:13]
	s_addc_u32 s29, s29, 0
	s_add_i32 s30, s55, s36
	global_load_lds_dwordx4 v[230:231], off
	v_lshl_add_u64 v[230:231], s[28:29], 0, v[134:135]
	s_mov_b32 m0, s30
	s_nop 0
	global_load_lds_dwordx4 v[230:231], off
	v_lshl_add_u64 v[230:231], s[28:29], 0, v[130:131]
	s_add_i32 m0, s30, 0x2000
	s_nop 0
	global_load_lds_dwordx4 v[230:231], off
	v_lshl_add_u64 v[230:231], v[234:235], 0, s[12:13]
	s_mov_b32 m0, s42
	s_nop 0
	global_load_lds_dwordx4 v[230:231], off
	v_lshl_add_u64 v[230:231], v[236:237], 0, s[12:13]
	s_mov_b32 m0, s43
	s_nop 0
	global_load_lds_dwordx4 v[230:231], off
	s_waitcnt vmcnt(8)
	s_waitcnt lgkmcnt(0)
	s_setprio 1
	s_barrier
	v_mfma_f32_16x16x32_bf16 v[62:65], v[148:151], v[198:201], v[62:65]
	v_mfma_f32_16x16x32_bf16 v[58:61], v[174:177], v[198:201], v[58:61]
	v_mfma_f32_16x16x32_bf16 v[50:53], v[148:151], v[206:209], v[50:53]
	v_mfma_f32_16x16x32_bf16 v[42:45], v[174:177], v[206:209], v[42:45]
	v_mfma_f32_16x16x32_bf16 v[34:37], v[148:151], v[214:217], v[34:37]
	v_mfma_f32_16x16x32_bf16 v[26:29], v[174:177], v[214:217], v[26:29]
	v_mfma_f32_16x16x32_bf16 v[18:21], v[148:151], v[222:225], v[18:21]
	v_mfma_f32_16x16x32_bf16 v[10:13], v[174:177], v[222:225], v[10:13]
	v_mfma_f32_16x16x32_bf16 v[62:65], v[170:173], v[202:205], v[62:65]
	v_mfma_f32_16x16x32_bf16 v[58:61], v[178:181], v[202:205], v[58:61]
	v_mfma_f32_16x16x32_bf16 v[50:53], v[170:173], v[210:213], v[50:53]
	v_mfma_f32_16x16x32_bf16 v[42:45], v[178:181], v[210:213], v[42:45]
	v_mfma_f32_16x16x32_bf16 v[34:37], v[170:173], v[218:221], v[34:37]
	v_mfma_f32_16x16x32_bf16 v[26:29], v[178:181], v[218:221], v[26:29]
	v_mfma_f32_16x16x32_bf16 v[18:21], v[170:173], v[226:229], v[18:21]
	v_mfma_f32_16x16x32_bf16 v[10:13], v[178:181], v[226:229], v[10:13]
	v_mfma_f32_16x16x32_bf16 v[54:57], v[182:185], v[198:201], v[54:57]
	v_mfma_f32_16x16x32_bf16 v[46:49], v[190:193], v[198:201], v[46:49]
	v_mfma_f32_16x16x32_bf16 v[38:41], v[182:185], v[206:209], v[38:41]
	v_mfma_f32_16x16x32_bf16 v[30:33], v[190:193], v[206:209], v[30:33]
	v_mfma_f32_16x16x32_bf16 v[22:25], v[182:185], v[214:217], v[22:25]
	v_mfma_f32_16x16x32_bf16 v[14:17], v[190:193], v[214:217], v[14:17]
	v_mfma_f32_16x16x32_bf16 v[6:9], v[182:185], v[222:225], v[6:9]
	v_mfma_f32_16x16x32_bf16 v[2:5], v[190:193], v[222:225], v[2:5]
	v_mfma_f32_16x16x32_bf16 v[54:57], v[186:189], v[202:205], v[54:57]
	v_mfma_f32_16x16x32_bf16 v[46:49], v[194:197], v[202:205], v[46:49]
	v_mfma_f32_16x16x32_bf16 v[38:41], v[186:189], v[210:213], v[38:41]
	v_mfma_f32_16x16x32_bf16 v[30:33], v[194:197], v[210:213], v[30:33]
	v_mfma_f32_16x16x32_bf16 v[22:25], v[186:189], v[218:221], v[22:25]
	v_mfma_f32_16x16x32_bf16 v[14:17], v[194:197], v[218:221], v[14:17]
	v_mfma_f32_16x16x32_bf16 v[6:9], v[186:189], v[226:229], v[6:9]
	v_mfma_f32_16x16x32_bf16 v[2:5], v[194:197], v[226:229], v[2:5]
	s_barrier
	s_setprio 0
	s_add_i32 s53, s53, 2
	s_add_u32 s26, s26, 0x100
	s_addc_u32 s27, s27, 0
	s_add_u32 s51, s51, 0x100
	s_addc_u32 s52, s52, 0
	s_cmp_gt_u32 s53, 13
	s_cbranch_scc0 .LBB0_317
	s_and_b64 vcc, exec, s[14:15]
	s_cbranch_vccz .LBB0_320
	s_barrier

.LBB0_341:
	ds_read_b128 v[156:159], v1
	ds_read_b128 v[160:163], v1 offset:1024
	ds_read_b128 v[164:167], v1 offset:2048
	ds_read_b128 v[168:171], v1 offset:3072
	ds_read_b128 v[172:175], v147
	ds_read_b128 v[176:179], v147 offset:1024
	ds_read_b128 v[180:183], v147 offset:2048
	ds_read_b128 v[184:187], v147 offset:3072
	s_add_u32 s38, s36, 0xfffe0080
	s_addc_u32 s39, s37, -1
	s_cmp_eq_u32 s63, 4
	s_cselect_b32 s41, s27, s39
	s_cselect_b32 s40, s59, s38
	s_cselect_b32 s39, s25, s62
	s_cselect_b32 s38, s60, s61
	v_lshl_add_u64 v[148:149], s[36:37], 0, v[138:139]
	s_add_i32 m0, s35, 0xc000
	ds_read_b128 v[188:191], v152
	ds_read_b128 v[192:195], v152 offset:1024
	ds_read_b128 v[196:199], v152 offset:2048
	ds_read_b128 v[200:203], v152 offset:3072
	ds_read_b128 v[204:207], v152 offset:4096
	ds_read_b128 v[208:211], v152 offset:5120
	ds_read_b128 v[212:215], v152 offset:6144
	ds_read_b128 v[216:219], v152 offset:7168
	global_load_lds_dwordx4 v[148:149], off
	v_lshl_add_u64 v[148:149], s[36:37], 0, v[140:141]
	s_add_i32 m0, s35, 0xe000
	s_nop 0
	global_load_lds_dwordx4 v[148:149], off
	s_waitcnt vmcnt(8)
	s_waitcnt lgkmcnt(0)
	s_setprio 1
	s_barrier
	v_mfma_f32_16x16x32_bf16 v[126:129], v[156:159], v[188:191], v[126:129]
	v_mfma_f32_16x16x32_bf16 v[122:125], v[164:167], v[188:191], v[122:125]
	v_mfma_f32_16x16x32_bf16 v[114:117], v[156:159], v[196:199], v[114:117]
	v_mfma_f32_16x16x32_bf16 v[106:109], v[164:167], v[196:199], v[106:109]
	v_mfma_f32_16x16x32_bf16 v[98:101], v[156:159], v[204:207], v[98:101]
	v_mfma_f32_16x16x32_bf16 v[90:93], v[164:167], v[204:207], v[90:93]
	v_mfma_f32_16x16x32_bf16 v[82:85], v[156:159], v[212:215], v[82:85]
	v_mfma_f32_16x16x32_bf16 v[74:77], v[164:167], v[212:215], v[74:77]
	v_mfma_f32_16x16x32_bf16 v[126:129], v[160:163], v[192:195], v[126:129]
	v_mfma_f32_16x16x32_bf16 v[122:125], v[168:171], v[192:195], v[122:125]
	v_mfma_f32_16x16x32_bf16 v[114:117], v[160:163], v[200:203], v[114:117]
	v_mfma_f32_16x16x32_bf16 v[106:109], v[168:171], v[200:203], v[106:109]
	v_mfma_f32_16x16x32_bf16 v[98:101], v[160:163], v[208:211], v[98:101]
	v_mfma_f32_16x16x32_bf16 v[90:93], v[168:171], v[208:211], v[90:93]
	v_mfma_f32_16x16x32_bf16 v[82:85], v[160:163], v[216:219], v[82:85]
	v_mfma_f32_16x16x32_bf16 v[74:77], v[168:171], v[216:219], v[74:77]
	v_mfma_f32_16x16x32_bf16 v[118:121], v[172:175], v[188:191], v[118:121]
	v_mfma_f32_16x16x32_bf16 v[110:113], v[180:183], v[188:191], v[110:113]
	v_mfma_f32_16x16x32_bf16 v[102:105], v[172:175], v[196:199], v[102:105]
	v_mfma_f32_16x16x32_bf16 v[94:97], v[180:183], v[196:199], v[94:97]
	v_mfma_f32_16x16x32_bf16 v[86:89], v[172:175], v[204:207], v[86:89]
	v_mfma_f32_16x16x32_bf16 v[78:81], v[180:183], v[204:207], v[78:81]
	v_mfma_f32_16x16x32_bf16 v[70:73], v[172:175], v[212:215], v[70:73]
	v_mfma_f32_16x16x32_bf16 v[66:69], v[180:183], v[212:215], v[66:69]
	v_mfma_f32_16x16x32_bf16 v[118:121], v[176:179], v[192:195], v[118:121]
	v_mfma_f32_16x16x32_bf16 v[110:113], v[184:187], v[192:195], v[110:113]
	v_mfma_f32_16x16x32_bf16 v[102:105], v[176:179], v[200:203], v[102:105]
	v_mfma_f32_16x16x32_bf16 v[94:97], v[184:187], v[200:203], v[94:97]
	v_mfma_f32_16x16x32_bf16 v[86:89], v[176:179], v[208:211], v[86:89]
	v_mfma_f32_16x16x32_bf16 v[78:81], v[184:187], v[208:211], v[78:81]
	v_mfma_f32_16x16x32_bf16 v[70:73], v[176:179], v[216:219], v[70:73]
	v_mfma_f32_16x16x32_bf16 v[66:69], v[184:187], v[216:219], v[66:69]
	s_barrier
	s_setprio 0
	s_add_i32 s64, s53, s45
	v_lshl_add_u64 v[148:149], s[38:39], 0, v[132:133]
	s_mov_b32 m0, s64
	ds_read_b128 v[188:191], v152 offset:16384
	ds_read_b128 v[192:195], v152 offset:17408
	ds_read_b128 v[196:199], v152 offset:18432
	ds_read_b128 v[200:203], v152 offset:19456
	ds_read_b128 v[204:207], v152 offset:20480
	ds_read_b128 v[208:211], v152 offset:21504
	ds_read_b128 v[212:215], v152 offset:22528
	ds_read_b128 v[216:219], v152 offset:23552
	global_load_lds_dwordx4 v[148:149], off
	s_add_i32 m0, s64, 0x2000
	s_add_u32 s64, s38, 0x20000
	v_lshl_add_u64 v[220:221], s[38:39], 0, v[136:137]
	s_addc_u32 s65, s39, 0
	s_add_i32 s66, s54, s45
	global_load_lds_dwordx4 v[220:221], off
	v_lshl_add_u64 v[222:223], s[64:65], 0, v[132:133]
	s_mov_b32 m0, s66
	v_lshl_add_u64 v[224:225], s[40:41], 0, v[134:135]
	global_load_lds_dwordx4 v[222:223], off
	v_lshl_add_u64 v[222:223], s[64:65], 0, v[136:137]
	s_add_i32 m0, s66, 0x2000
	s_nop 0
	global_load_lds_dwordx4 v[222:223], off
	v_lshl_add_u64 v[222:223], s[40:41], 0, v[130:131]
	s_mov_b32 m0, s35
	s_nop 0
	global_load_lds_dwordx4 v[222:223], off
	s_mov_b32 m0, s46
	s_nop 0
	global_load_lds_dwordx4 v[224:225], off
	s_waitcnt vmcnt(8)
	s_waitcnt lgkmcnt(0)
	s_setprio 1
	s_barrier
	v_mfma_f32_16x16x32_bf16 v[62:65], v[156:159], v[188:191], v[62:65]
	v_mfma_f32_16x16x32_bf16 v[58:61], v[164:167], v[188:191], v[58:61]
	v_mfma_f32_16x16x32_bf16 v[50:53], v[156:159], v[196:199], v[50:53]
	v_mfma_f32_16x16x32_bf16 v[42:45], v[164:167], v[196:199], v[42:45]
	v_mfma_f32_16x16x32_bf16 v[34:37], v[156:159], v[204:207], v[34:37]
	v_mfma_f32_16x16x32_bf16 v[26:29], v[164:167], v[204:207], v[26:29]
	v_mfma_f32_16x16x32_bf16 v[18:21], v[156:159], v[212:215], v[18:21]
	v_mfma_f32_16x16x32_bf16 v[10:13], v[164:167], v[212:215], v[10:13]
	v_mfma_f32_16x16x32_bf16 v[62:65], v[160:163], v[192:195], v[62:65]
	v_mfma_f32_16x16x32_bf16 v[58:61], v[168:171], v[192:195], v[58:61]
	v_mfma_f32_16x16x32_bf16 v[50:53], v[160:163], v[200:203], v[50:53]
	v_mfma_f32_16x16x32_bf16 v[42:45], v[168:171], v[200:203], v[42:45]
	v_mfma_f32_16x16x32_bf16 v[34:37], v[160:163], v[208:211], v[34:37]
	v_mfma_f32_16x16x32_bf16 v[26:29], v[168:171], v[208:211], v[26:29]
	v_mfma_f32_16x16x32_bf16 v[18:21], v[160:163], v[216:219], v[18:21]
	v_mfma_f32_16x16x32_bf16 v[10:13], v[168:171], v[216:219], v[10:13]
	v_mfma_f32_16x16x32_bf16 v[54:57], v[172:175], v[188:191], v[54:57]
	v_mfma_f32_16x16x32_bf16 v[46:49], v[180:183], v[188:191], v[46:49]
	v_mfma_f32_16x16x32_bf16 v[38:41], v[172:175], v[196:199], v[38:41]
	v_mfma_f32_16x16x32_bf16 v[30:33], v[180:183], v[196:199], v[30:33]
	v_mfma_f32_16x16x32_bf16 v[22:25], v[172:175], v[204:207], v[22:25]
	v_mfma_f32_16x16x32_bf16 v[14:17], v[180:183], v[204:207], v[14:17]
	v_mfma_f32_16x16x32_bf16 v[6:9], v[172:175], v[212:215], v[6:9]
	v_mfma_f32_16x16x32_bf16 v[2:5], v[180:183], v[212:215], v[2:5]
	v_mfma_f32_16x16x32_bf16 v[54:57], v[176:179], v[192:195], v[54:57]
	v_mfma_f32_16x16x32_bf16 v[46:49], v[184:187], v[192:195], v[46:49]
	v_mfma_f32_16x16x32_bf16 v[38:41], v[176:179], v[200:203], v[38:41]
	v_mfma_f32_16x16x32_bf16 v[30:33], v[184:187], v[200:203], v[30:33]
	v_mfma_f32_16x16x32_bf16 v[22:25], v[176:179], v[208:211], v[22:25]
	v_mfma_f32_16x16x32_bf16 v[14:17], v[184:187], v[208:211], v[14:17]
	v_mfma_f32_16x16x32_bf16 v[6:9], v[176:179], v[216:219], v[6:9]
	v_mfma_f32_16x16x32_bf16 v[2:5], v[184:187], v[216:219], v[2:5]
	s_barrier
	s_setprio 0
	s_add_i32 s64, 0, 0x18000
	v_add_u32_e32 v146, s64, v151
	s_add_i32 s65, 0, 0x1c000
	ds_read_b128 v[156:159], v146
	ds_read_b128 v[160:163], v146 offset:1024
	ds_read_b128 v[164:167], v146 offset:2048
	ds_read_b128 v[168:171], v146 offset:3072
	v_add_u32_e32 v146, s65, v151
	ds_read_b128 v[172:175], v146
	ds_read_b128 v[176:179], v146 offset:1024
	ds_read_b128 v[180:183], v146 offset:2048
	ds_read_b128 v[184:187], v146 offset:3072
	s_add_u32 s40, s40, 0x20000
	s_addc_u32 s41, s41, 0
	s_mov_b32 m0, s47
	v_lshl_add_u64 v[226:227], s[40:41], 0, v[130:131]
	ds_read_b128 v[188:191], v152 offset:32768
	ds_read_b128 v[192:195], v152 offset:33792
	ds_read_b128 v[196:199], v152 offset:34816
	ds_read_b128 v[200:203], v152 offset:35840
	ds_read_b128 v[204:207], v152 offset:36864
	ds_read_b128 v[208:211], v152 offset:37888
	ds_read_b128 v[212:215], v152 offset:38912
	ds_read_b128 v[216:219], v152 offset:39936
	global_load_lds_dwordx4 v[226:227], off
	v_lshl_add_u64 v[226:227], s[40:41], 0, v[134:135]
	s_mov_b32 m0, s48
	s_nop 0
	global_load_lds_dwordx4 v[226:227], off
	s_waitcnt vmcnt(8)
	s_waitcnt lgkmcnt(0)
	s_setprio 1
	s_barrier
	v_mfma_f32_16x16x32_bf16 v[126:129], v[156:159], v[188:191], v[126:129]
	v_mfma_f32_16x16x32_bf16 v[122:125], v[164:167], v[188:191], v[122:125]
	v_mfma_f32_16x16x32_bf16 v[114:117], v[156:159], v[196:199], v[114:117]
	v_mfma_f32_16x16x32_bf16 v[106:109], v[164:167], v[196:199], v[106:109]
	v_mfma_f32_16x16x32_bf16 v[98:101], v[156:159], v[204:207], v[98:101]
	v_mfma_f32_16x16x32_bf16 v[90:93], v[164:167], v[204:207], v[90:93]
	v_mfma_f32_16x16x32_bf16 v[82:85], v[156:159], v[212:215], v[82:85]
	v_mfma_f32_16x16x32_bf16 v[74:77], v[164:167], v[212:215], v[74:77]
	v_mfma_f32_16x16x32_bf16 v[126:129], v[160:163], v[192:195], v[126:129]
	v_mfma_f32_16x16x32_bf16 v[122:125], v[168:171], v[192:195], v[122:125]
	v_mfma_f32_16x16x32_bf16 v[114:117], v[160:163], v[200:203], v[114:117]
	v_mfma_f32_16x16x32_bf16 v[106:109], v[168:171], v[200:203], v[106:109]
	v_mfma_f32_16x16x32_bf16 v[98:101], v[160:163], v[208:211], v[98:101]
	v_mfma_f32_16x16x32_bf16 v[90:93], v[168:171], v[208:211], v[90:93]
	v_mfma_f32_16x16x32_bf16 v[82:85], v[160:163], v[216:219], v[82:85]
	v_mfma_f32_16x16x32_bf16 v[74:77], v[168:171], v[216:219], v[74:77]
	v_mfma_f32_16x16x32_bf16 v[118:121], v[172:175], v[188:191], v[118:121]
	v_mfma_f32_16x16x32_bf16 v[110:113], v[180:183], v[188:191], v[110:113]
	v_mfma_f32_16x16x32_bf16 v[102:105], v[172:175], v[196:199], v[102:105]
	v_mfma_f32_16x16x32_bf16 v[94:97], v[180:183], v[196:199], v[94:97]
	v_mfma_f32_16x16x32_bf16 v[86:89], v[172:175], v[204:207], v[86:89]
	v_mfma_f32_16x16x32_bf16 v[78:81], v[180:183], v[204:207], v[78:81]
	v_mfma_f32_16x16x32_bf16 v[70:73], v[172:175], v[212:215], v[70:73]
	v_mfma_f32_16x16x32_bf16 v[66:69], v[180:183], v[212:215], v[66:69]
	v_mfma_f32_16x16x32_bf16 v[118:121], v[176:179], v[192:195], v[118:121]
	v_mfma_f32_16x16x32_bf16 v[110:113], v[184:187], v[192:195], v[110:113]
	v_mfma_f32_16x16x32_bf16 v[102:105], v[176:179], v[200:203], v[102:105]
	v_mfma_f32_16x16x32_bf16 v[94:97], v[184:187], v[200:203], v[94:97]
	v_mfma_f32_16x16x32_bf16 v[86:89], v[176:179], v[208:211], v[86:89]
	v_mfma_f32_16x16x32_bf16 v[78:81], v[184:187], v[208:211], v[78:81]
	v_mfma_f32_16x16x32_bf16 v[70:73], v[176:179], v[216:219], v[70:73]
	v_mfma_f32_16x16x32_bf16 v[66:69], v[184:187], v[216:219], v[66:69]
	s_barrier
	s_setprio 0
	s_add_i32 s40, s64, s45
	v_lshl_add_u64 v[148:149], v[148:149], 0, s[12:13]
	s_mov_b32 m0, s40
	ds_read_b128 v[188:191], v152 offset:49152
	ds_read_b128 v[192:195], v152 offset:50176
	ds_read_b128 v[196:199], v152 offset:51200
	ds_read_b128 v[200:203], v152 offset:52224
	ds_read_b128 v[204:207], v152 offset:53248
	ds_read_b128 v[208:211], v152 offset:54272
	ds_read_b128 v[212:215], v152 offset:55296
	ds_read_b128 v[216:219], v152 offset:56320
	global_load_lds_dwordx4 v[148:149], off
	s_add_i32 m0, s40, 0x2000
	s_add_u32 s38, s38, 0x20080
	v_lshl_add_u64 v[148:149], v[220:221], 0, s[12:13]
	s_addc_u32 s39, s39, 0
	s_add_i32 s40, s65, s45
	global_load_lds_dwordx4 v[148:149], off
	v_lshl_add_u64 v[148:149], s[38:39], 0, v[132:133]
	s_mov_b32 m0, s40
	s_nop 0
	global_load_lds_dwordx4 v[148:149], off
	v_lshl_add_u64 v[148:149], s[38:39], 0, v[136:137]
	s_add_i32 m0, s40, 0x2000
	s_nop 0
	global_load_lds_dwordx4 v[148:149], off
	v_lshl_add_u64 v[148:149], v[222:223], 0, s[12:13]
	s_mov_b32 m0, s50
	s_nop 0
	global_load_lds_dwordx4 v[148:149], off
	v_lshl_add_u64 v[148:149], v[224:225], 0, s[12:13]
	s_mov_b32 m0, s51
	s_nop 0
	global_load_lds_dwordx4 v[148:149], off
	s_waitcnt vmcnt(8)
	s_waitcnt lgkmcnt(0)
	s_setprio 1
	s_barrier
	v_mfma_f32_16x16x32_bf16 v[62:65], v[156:159], v[188:191], v[62:65]
	v_mfma_f32_16x16x32_bf16 v[58:61], v[164:167], v[188:191], v[58:61]
	v_mfma_f32_16x16x32_bf16 v[50:53], v[156:159], v[196:199], v[50:53]
	v_mfma_f32_16x16x32_bf16 v[42:45], v[164:167], v[196:199], v[42:45]
	v_mfma_f32_16x16x32_bf16 v[34:37], v[156:159], v[204:207], v[34:37]
	v_mfma_f32_16x16x32_bf16 v[26:29], v[164:167], v[204:207], v[26:29]
	v_mfma_f32_16x16x32_bf16 v[18:21], v[156:159], v[212:215], v[18:21]
	v_mfma_f32_16x16x32_bf16 v[10:13], v[164:167], v[212:215], v[10:13]
	v_mfma_f32_16x16x32_bf16 v[62:65], v[160:163], v[192:195], v[62:65]
	v_mfma_f32_16x16x32_bf16 v[58:61], v[168:171], v[192:195], v[58:61]
	v_mfma_f32_16x16x32_bf16 v[50:53], v[160:163], v[200:203], v[50:53]
	v_mfma_f32_16x16x32_bf16 v[42:45], v[168:171], v[200:203], v[42:45]
	v_mfma_f32_16x16x32_bf16 v[34:37], v[160:163], v[208:211], v[34:37]
	v_mfma_f32_16x16x32_bf16 v[26:29], v[168:171], v[208:211], v[26:29]
	v_mfma_f32_16x16x32_bf16 v[18:21], v[160:163], v[216:219], v[18:21]
	v_mfma_f32_16x16x32_bf16 v[10:13], v[168:171], v[216:219], v[10:13]
	v_mfma_f32_16x16x32_bf16 v[54:57], v[172:175], v[188:191], v[54:57]
	v_mfma_f32_16x16x32_bf16 v[46:49], v[180:183], v[188:191], v[46:49]
	v_mfma_f32_16x16x32_bf16 v[38:41], v[172:175], v[196:199], v[38:41]
	v_mfma_f32_16x16x32_bf16 v[30:33], v[180:183], v[196:199], v[30:33]
	v_mfma_f32_16x16x32_bf16 v[22:25], v[172:175], v[204:207], v[22:25]
	v_mfma_f32_16x16x32_bf16 v[14:17], v[180:183], v[204:207], v[14:17]
	v_mfma_f32_16x16x32_bf16 v[6:9], v[172:175], v[212:215], v[6:9]
	v_mfma_f32_16x16x32_bf16 v[2:5], v[180:183], v[212:215], v[2:5]
	v_mfma_f32_16x16x32_bf16 v[54:57], v[176:179], v[192:195], v[54:57]
	v_mfma_f32_16x16x32_bf16 v[46:49], v[184:187], v[192:195], v[46:49]
	v_mfma_f32_16x16x32_bf16 v[38:41], v[176:179], v[200:203], v[38:41]
	v_mfma_f32_16x16x32_bf16 v[30:33], v[184:187], v[200:203], v[30:33]
	v_mfma_f32_16x16x32_bf16 v[22:25], v[176:179], v[208:211], v[22:25]
	v_mfma_f32_16x16x32_bf16 v[14:17], v[184:187], v[208:211], v[14:17]
	v_mfma_f32_16x16x32_bf16 v[6:9], v[176:179], v[216:219], v[6:9]
	v_mfma_f32_16x16x32_bf16 v[2:5], v[184:187], v[216:219], v[2:5]
	s_barrier
	s_setprio 0
	s_add_i32 s63, s63, 2
	s_add_u32 s36, s36, 0x100
	s_addc_u32 s37, s37, 0
	s_add_u32 s61, s61, 0x100
	s_addc_u32 s62, s62, 0
	s_cmp_gt_u32 s63, 5
	s_cbranch_scc0 .LBB0_341
	s_and_b64 vcc, exec, s[14:15]
	s_cbranch_vccz .LBB0_344
	s_barrier

.LBB0_728:
	ds_read_b128 v[130:133], v156
	ds_read_b128 v[134:137], v156 offset:1024
	ds_read_b128 v[160:163], v156 offset:2048
	ds_read_b128 v[164:167], v156 offset:3072
	ds_read_b128 v[168:171], v157
	ds_read_b128 v[172:175], v157 offset:1024
	ds_read_b128 v[176:179], v157 offset:2048
	ds_read_b128 v[180:183], v157 offset:3072
	s_add_u32 s28, s26, 0xfff00080
	s_addc_u32 s29, s27, -1
	s_cmp_eq_u32 s48, 60
	s_cselect_b32 s31, s19, s29
	s_cselect_b32 s30, s44, s28
	s_cselect_b32 s29, s17, s47
	s_cselect_b32 s28, s45, s46
	v_lshl_add_u64 v[216:217], s[26:27], 0, v[146:147]
	s_add_i32 m0, s25, 0xc000
	ds_read_b128 v[184:187], v158
	ds_read_b128 v[188:191], v158 offset:1024
	ds_read_b128 v[192:195], v158 offset:2048
	ds_read_b128 v[196:199], v158 offset:3072
	ds_read_b128 v[200:203], v158 offset:4096
	ds_read_b128 v[204:207], v158 offset:5120
	ds_read_b128 v[208:211], v158 offset:6144
	ds_read_b128 v[212:215], v158 offset:7168
	global_load_lds_dwordx4 v[216:217], off
	v_lshl_add_u64 v[216:217], s[26:27], 0, v[148:149]
	s_add_i32 m0, s25, 0xe000
	s_nop 0
	global_load_lds_dwordx4 v[216:217], off
	s_waitcnt vmcnt(8)
	s_waitcnt lgkmcnt(0)
	s_setprio 1
	s_barrier
	v_mfma_f32_16x16x32_bf16 v[126:129], v[130:133], v[184:187], v[126:129]
	v_mfma_f32_16x16x32_bf16 v[122:125], v[160:163], v[184:187], v[122:125]
	v_mfma_f32_16x16x32_bf16 v[118:121], v[130:133], v[192:195], v[118:121]
	v_mfma_f32_16x16x32_bf16 v[114:117], v[160:163], v[192:195], v[114:117]
	v_mfma_f32_16x16x32_bf16 v[94:97], v[130:133], v[200:203], v[94:97]
	v_mfma_f32_16x16x32_bf16 v[90:93], v[160:163], v[200:203], v[90:93]
	v_mfma_f32_16x16x32_bf16 v[82:85], v[130:133], v[208:211], v[82:85]
	v_mfma_f32_16x16x32_bf16 v[74:77], v[160:163], v[208:211], v[74:77]
	v_mfma_f32_16x16x32_bf16 v[126:129], v[134:137], v[188:191], v[126:129]
	v_mfma_f32_16x16x32_bf16 v[122:125], v[164:167], v[188:191], v[122:125]
	v_mfma_f32_16x16x32_bf16 v[118:121], v[134:137], v[196:199], v[118:121]
	v_mfma_f32_16x16x32_bf16 v[114:117], v[164:167], v[196:199], v[114:117]
	v_mfma_f32_16x16x32_bf16 v[94:97], v[134:137], v[204:207], v[94:97]
	v_mfma_f32_16x16x32_bf16 v[90:93], v[164:167], v[204:207], v[90:93]
	v_mfma_f32_16x16x32_bf16 v[82:85], v[134:137], v[212:215], v[82:85]
	v_mfma_f32_16x16x32_bf16 v[74:77], v[164:167], v[212:215], v[74:77]
	v_mfma_f32_16x16x32_bf16 v[110:113], v[168:171], v[184:187], v[110:113]
	v_mfma_f32_16x16x32_bf16 v[106:109], v[176:179], v[184:187], v[106:109]
	v_mfma_f32_16x16x32_bf16 v[102:105], v[168:171], v[192:195], v[102:105]
	v_mfma_f32_16x16x32_bf16 v[98:101], v[176:179], v[192:195], v[98:101]
	v_mfma_f32_16x16x32_bf16 v[86:89], v[168:171], v[200:203], v[86:89]
	v_mfma_f32_16x16x32_bf16 v[78:81], v[176:179], v[200:203], v[78:81]
	v_mfma_f32_16x16x32_bf16 v[70:73], v[168:171], v[208:211], v[70:73]
	v_mfma_f32_16x16x32_bf16 v[66:69], v[176:179], v[208:211], v[66:69]
	v_mfma_f32_16x16x32_bf16 v[110:113], v[172:175], v[188:191], v[110:113]
	v_mfma_f32_16x16x32_bf16 v[106:109], v[180:183], v[188:191], v[106:109]
	v_mfma_f32_16x16x32_bf16 v[102:105], v[172:175], v[196:199], v[102:105]
	v_mfma_f32_16x16x32_bf16 v[98:101], v[180:183], v[196:199], v[98:101]
	v_mfma_f32_16x16x32_bf16 v[86:89], v[172:175], v[204:207], v[86:89]
	v_mfma_f32_16x16x32_bf16 v[78:81], v[180:183], v[204:207], v[78:81]
	v_mfma_f32_16x16x32_bf16 v[70:73], v[172:175], v[212:215], v[70:73]
	v_mfma_f32_16x16x32_bf16 v[66:69], v[180:183], v[212:215], v[66:69]
	s_barrier
	s_setprio 0
	s_add_i32 s49, s42, s34
	v_lshl_add_u64 v[216:217], s[28:29], 0, v[140:141]
	s_mov_b32 m0, s49
	ds_read_b128 v[184:187], v158 offset:16384
	ds_read_b128 v[188:191], v158 offset:17408
	ds_read_b128 v[192:195], v158 offset:18432
	ds_read_b128 v[196:199], v158 offset:19456
	ds_read_b128 v[200:203], v158 offset:20480
	ds_read_b128 v[204:207], v158 offset:21504
	ds_read_b128 v[208:211], v158 offset:22528
	ds_read_b128 v[212:215], v158 offset:23552
	global_load_lds_dwordx4 v[216:217], off
	s_add_i32 m0, s49, 0x2000
	s_add_u32 s50, s28, 0x100000
	v_lshl_add_u64 v[218:219], s[28:29], 0, v[144:145]
	s_addc_u32 s51, s29, 0
	s_add_i32 s49, s43, s34
	global_load_lds_dwordx4 v[218:219], off
	v_lshl_add_u64 v[220:221], s[50:51], 0, v[140:141]
	s_mov_b32 m0, s49
	v_lshl_add_u64 v[222:223], s[30:31], 0, v[142:143]
	global_load_lds_dwordx4 v[220:221], off
	v_lshl_add_u64 v[220:221], s[50:51], 0, v[144:145]
	s_add_i32 m0, s49, 0x2000
	s_nop 0
	global_load_lds_dwordx4 v[220:221], off
	v_lshl_add_u64 v[220:221], s[30:31], 0, v[138:139]
	s_mov_b32 m0, s25
	s_nop 0
	global_load_lds_dwordx4 v[220:221], off
	s_mov_b32 m0, s35
	s_nop 0
	global_load_lds_dwordx4 v[222:223], off
	s_waitcnt vmcnt(8)
	s_waitcnt lgkmcnt(0)
	s_setprio 1
	s_barrier
	v_mfma_f32_16x16x32_bf16 v[62:65], v[130:133], v[184:187], v[62:65]
	v_mfma_f32_16x16x32_bf16 v[58:61], v[160:163], v[184:187], v[58:61]
	v_mfma_f32_16x16x32_bf16 v[50:53], v[130:133], v[192:195], v[50:53]
	v_mfma_f32_16x16x32_bf16 v[42:45], v[160:163], v[192:195], v[42:45]
	v_mfma_f32_16x16x32_bf16 v[34:37], v[130:133], v[200:203], v[34:37]
	v_mfma_f32_16x16x32_bf16 v[26:29], v[160:163], v[200:203], v[26:29]
	v_mfma_f32_16x16x32_bf16 v[18:21], v[130:133], v[208:211], v[18:21]
	v_mfma_f32_16x16x32_bf16 v[10:13], v[160:163], v[208:211], v[10:13]
	v_mfma_f32_16x16x32_bf16 v[62:65], v[134:137], v[188:191], v[62:65]
	v_mfma_f32_16x16x32_bf16 v[58:61], v[164:167], v[188:191], v[58:61]
	v_mfma_f32_16x16x32_bf16 v[50:53], v[134:137], v[196:199], v[50:53]
	v_mfma_f32_16x16x32_bf16 v[42:45], v[164:167], v[196:199], v[42:45]
	v_mfma_f32_16x16x32_bf16 v[34:37], v[134:137], v[204:207], v[34:37]
	v_mfma_f32_16x16x32_bf16 v[26:29], v[164:167], v[204:207], v[26:29]
	v_mfma_f32_16x16x32_bf16 v[18:21], v[134:137], v[212:215], v[18:21]
	v_mfma_f32_16x16x32_bf16 v[10:13], v[164:167], v[212:215], v[10:13]
	v_mfma_f32_16x16x32_bf16 v[54:57], v[168:171], v[184:187], v[54:57]
	v_mfma_f32_16x16x32_bf16 v[46:49], v[176:179], v[184:187], v[46:49]
	v_mfma_f32_16x16x32_bf16 v[38:41], v[168:171], v[192:195], v[38:41]
	v_mfma_f32_16x16x32_bf16 v[30:33], v[176:179], v[192:195], v[30:33]
	v_mfma_f32_16x16x32_bf16 v[22:25], v[168:171], v[200:203], v[22:25]
	v_mfma_f32_16x16x32_bf16 v[14:17], v[176:179], v[200:203], v[14:17]
	v_mfma_f32_16x16x32_bf16 v[6:9], v[168:171], v[208:211], v[6:9]
	v_mfma_f32_16x16x32_bf16 v[2:5], v[176:179], v[208:211], v[2:5]
	v_mfma_f32_16x16x32_bf16 v[54:57], v[172:175], v[188:191], v[54:57]
	v_mfma_f32_16x16x32_bf16 v[46:49], v[180:183], v[188:191], v[46:49]
	v_mfma_f32_16x16x32_bf16 v[38:41], v[172:175], v[196:199], v[38:41]
	v_mfma_f32_16x16x32_bf16 v[30:33], v[180:183], v[196:199], v[30:33]
	v_mfma_f32_16x16x32_bf16 v[22:25], v[172:175], v[204:207], v[22:25]
	v_mfma_f32_16x16x32_bf16 v[14:17], v[180:183], v[204:207], v[14:17]
	v_mfma_f32_16x16x32_bf16 v[6:9], v[172:175], v[212:215], v[6:9]
	v_mfma_f32_16x16x32_bf16 v[2:5], v[180:183], v[212:215], v[2:5]
	s_barrier
	s_setprio 0
	s_add_i32 s49, 0, 0x18000
	v_add_u32_e32 v159, s49, v154
	s_add_i32 s50, 0, 0x1c000
	ds_read_b128 v[130:133], v159
	ds_read_b128 v[134:137], v159 offset:1024
	ds_read_b128 v[160:163], v159 offset:2048
	ds_read_b128 v[164:167], v159 offset:3072
	v_add_u32_e32 v159, s50, v154
	ds_read_b128 v[168:171], v159
	ds_read_b128 v[172:175], v159 offset:1024
	ds_read_b128 v[176:179], v159 offset:2048
	ds_read_b128 v[180:183], v159 offset:3072
	s_add_u32 s30, s30, 0x100000
	s_addc_u32 s31, s31, 0
	s_mov_b32 m0, s36
	v_lshl_add_u64 v[224:225], s[30:31], 0, v[138:139]
	ds_read_b128 v[184:187], v158 offset:32768
	ds_read_b128 v[188:191], v158 offset:33792
	ds_read_b128 v[192:195], v158 offset:34816
	ds_read_b128 v[196:199], v158 offset:35840
	ds_read_b128 v[200:203], v158 offset:36864
	ds_read_b128 v[204:207], v158 offset:37888
	ds_read_b128 v[208:211], v158 offset:38912
	ds_read_b128 v[212:215], v158 offset:39936
	global_load_lds_dwordx4 v[224:225], off
	v_lshl_add_u64 v[224:225], s[30:31], 0, v[142:143]
	s_mov_b32 m0, s37
	s_nop 0
	global_load_lds_dwordx4 v[224:225], off
	s_waitcnt vmcnt(8)
	s_waitcnt lgkmcnt(0)
	s_setprio 1
	s_barrier
	v_mfma_f32_16x16x32_bf16 v[126:129], v[130:133], v[184:187], v[126:129]
	v_mfma_f32_16x16x32_bf16 v[122:125], v[160:163], v[184:187], v[122:125]
	v_mfma_f32_16x16x32_bf16 v[118:121], v[130:133], v[192:195], v[118:121]
	v_mfma_f32_16x16x32_bf16 v[114:117], v[160:163], v[192:195], v[114:117]
	v_mfma_f32_16x16x32_bf16 v[94:97], v[130:133], v[200:203], v[94:97]
	v_mfma_f32_16x16x32_bf16 v[90:93], v[160:163], v[200:203], v[90:93]
	v_mfma_f32_16x16x32_bf16 v[82:85], v[130:133], v[208:211], v[82:85]
	v_mfma_f32_16x16x32_bf16 v[74:77], v[160:163], v[208:211], v[74:77]
	v_mfma_f32_16x16x32_bf16 v[126:129], v[134:137], v[188:191], v[126:129]
	v_mfma_f32_16x16x32_bf16 v[122:125], v[164:167], v[188:191], v[122:125]
	v_mfma_f32_16x16x32_bf16 v[118:121], v[134:137], v[196:199], v[118:121]
	v_mfma_f32_16x16x32_bf16 v[114:117], v[164:167], v[196:199], v[114:117]
	v_mfma_f32_16x16x32_bf16 v[94:97], v[134:137], v[204:207], v[94:97]
	v_mfma_f32_16x16x32_bf16 v[90:93], v[164:167], v[204:207], v[90:93]
	v_mfma_f32_16x16x32_bf16 v[82:85], v[134:137], v[212:215], v[82:85]
	v_mfma_f32_16x16x32_bf16 v[74:77], v[164:167], v[212:215], v[74:77]
	v_mfma_f32_16x16x32_bf16 v[110:113], v[168:171], v[184:187], v[110:113]
	v_mfma_f32_16x16x32_bf16 v[106:109], v[176:179], v[184:187], v[106:109]
	v_mfma_f32_16x16x32_bf16 v[102:105], v[168:171], v[192:195], v[102:105]
	v_mfma_f32_16x16x32_bf16 v[98:101], v[176:179], v[192:195], v[98:101]
	v_mfma_f32_16x16x32_bf16 v[86:89], v[168:171], v[200:203], v[86:89]
	v_mfma_f32_16x16x32_bf16 v[78:81], v[176:179], v[200:203], v[78:81]
	v_mfma_f32_16x16x32_bf16 v[70:73], v[168:171], v[208:211], v[70:73]
	v_mfma_f32_16x16x32_bf16 v[66:69], v[176:179], v[208:211], v[66:69]
	v_mfma_f32_16x16x32_bf16 v[110:113], v[172:175], v[188:191], v[110:113]
	v_mfma_f32_16x16x32_bf16 v[106:109], v[180:183], v[188:191], v[106:109]
	v_mfma_f32_16x16x32_bf16 v[102:105], v[172:175], v[196:199], v[102:105]
	v_mfma_f32_16x16x32_bf16 v[98:101], v[180:183], v[196:199], v[98:101]
	v_mfma_f32_16x16x32_bf16 v[86:89], v[172:175], v[204:207], v[86:89]
	v_mfma_f32_16x16x32_bf16 v[78:81], v[180:183], v[204:207], v[78:81]
	v_mfma_f32_16x16x32_bf16 v[70:73], v[172:175], v[212:215], v[70:73]
	v_mfma_f32_16x16x32_bf16 v[66:69], v[180:183], v[212:215], v[66:69]
	s_barrier
	s_setprio 0
	s_add_i32 s30, s49, s34
	v_lshl_add_u64 v[216:217], v[216:217], 0, s[10:11]
	s_mov_b32 m0, s30
	ds_read_b128 v[184:187], v158 offset:49152
	ds_read_b128 v[188:191], v158 offset:50176
	ds_read_b128 v[192:195], v158 offset:51200
	ds_read_b128 v[196:199], v158 offset:52224
	ds_read_b128 v[200:203], v158 offset:53248
	ds_read_b128 v[204:207], v158 offset:54272
	ds_read_b128 v[208:211], v158 offset:55296
	ds_read_b128 v[212:215], v158 offset:56320
	global_load_lds_dwordx4 v[216:217], off
	s_add_i32 m0, s30, 0x2000
	s_add_u32 s28, s28, 0x100080
	v_lshl_add_u64 v[216:217], v[218:219], 0, s[10:11]
	s_addc_u32 s29, s29, 0
	s_add_i32 s30, s50, s34
	global_load_lds_dwordx4 v[216:217], off
	v_lshl_add_u64 v[216:217], s[28:29], 0, v[140:141]
	s_mov_b32 m0, s30
	s_nop 0
	global_load_lds_dwordx4 v[216:217], off
	v_lshl_add_u64 v[216:217], s[28:29], 0, v[144:145]
	s_add_i32 m0, s30, 0x2000
	s_nop 0
	global_load_lds_dwordx4 v[216:217], off
	v_lshl_add_u64 v[216:217], v[220:221], 0, s[10:11]
	s_mov_b32 m0, s39
	s_nop 0
	global_load_lds_dwordx4 v[216:217], off
	v_lshl_add_u64 v[216:217], v[222:223], 0, s[10:11]
	s_mov_b32 m0, s40
	s_nop 0
	global_load_lds_dwordx4 v[216:217], off
	s_waitcnt vmcnt(8)
	s_waitcnt lgkmcnt(0)
	s_setprio 1
	s_barrier
	v_mfma_f32_16x16x32_bf16 v[62:65], v[130:133], v[184:187], v[62:65]
	v_mfma_f32_16x16x32_bf16 v[58:61], v[160:163], v[184:187], v[58:61]
	v_mfma_f32_16x16x32_bf16 v[50:53], v[130:133], v[192:195], v[50:53]
	v_mfma_f32_16x16x32_bf16 v[42:45], v[160:163], v[192:195], v[42:45]
	v_mfma_f32_16x16x32_bf16 v[34:37], v[130:133], v[200:203], v[34:37]
	v_mfma_f32_16x16x32_bf16 v[26:29], v[160:163], v[200:203], v[26:29]
	v_mfma_f32_16x16x32_bf16 v[18:21], v[130:133], v[208:211], v[18:21]
	v_mfma_f32_16x16x32_bf16 v[10:13], v[160:163], v[208:211], v[10:13]
	v_mfma_f32_16x16x32_bf16 v[62:65], v[134:137], v[188:191], v[62:65]
	v_mfma_f32_16x16x32_bf16 v[58:61], v[164:167], v[188:191], v[58:61]
	v_mfma_f32_16x16x32_bf16 v[50:53], v[134:137], v[196:199], v[50:53]
	v_mfma_f32_16x16x32_bf16 v[42:45], v[164:167], v[196:199], v[42:45]
	v_mfma_f32_16x16x32_bf16 v[34:37], v[134:137], v[204:207], v[34:37]
	v_mfma_f32_16x16x32_bf16 v[26:29], v[164:167], v[204:207], v[26:29]
	v_mfma_f32_16x16x32_bf16 v[18:21], v[134:137], v[212:215], v[18:21]
	v_mfma_f32_16x16x32_bf16 v[10:13], v[164:167], v[212:215], v[10:13]
	v_mfma_f32_16x16x32_bf16 v[54:57], v[168:171], v[184:187], v[54:57]
	v_mfma_f32_16x16x32_bf16 v[46:49], v[176:179], v[184:187], v[46:49]
	v_mfma_f32_16x16x32_bf16 v[38:41], v[168:171], v[192:195], v[38:41]
	v_mfma_f32_16x16x32_bf16 v[30:33], v[176:179], v[192:195], v[30:33]
	v_mfma_f32_16x16x32_bf16 v[22:25], v[168:171], v[200:203], v[22:25]
	v_mfma_f32_16x16x32_bf16 v[14:17], v[176:179], v[200:203], v[14:17]
	v_mfma_f32_16x16x32_bf16 v[6:9], v[168:171], v[208:211], v[6:9]
	v_mfma_f32_16x16x32_bf16 v[2:5], v[176:179], v[208:211], v[2:5]
	v_mfma_f32_16x16x32_bf16 v[54:57], v[172:175], v[188:191], v[54:57]
	v_mfma_f32_16x16x32_bf16 v[46:49], v[180:183], v[188:191], v[46:49]
	v_mfma_f32_16x16x32_bf16 v[38:41], v[172:175], v[196:199], v[38:41]
	v_mfma_f32_16x16x32_bf16 v[30:33], v[180:183], v[196:199], v[30:33]
	v_mfma_f32_16x16x32_bf16 v[22:25], v[172:175], v[204:207], v[22:25]
	v_mfma_f32_16x16x32_bf16 v[14:17], v[180:183], v[204:207], v[14:17]
	v_mfma_f32_16x16x32_bf16 v[6:9], v[172:175], v[212:215], v[6:9]
	v_mfma_f32_16x16x32_bf16 v[2:5], v[180:183], v[212:215], v[2:5]
	s_barrier
	s_setprio 0
	s_add_i32 s48, s48, 2
	s_add_u32 s26, s26, 0x100
	s_addc_u32 s27, s27, 0
	s_add_u32 s46, s46, 0x100
	s_addc_u32 s47, s47, 0
	s_cmp_gt_u32 s48, 61
	s_cbranch_scc0 .LBB0_728
	s_and_b64 vcc, exec, s[12:13]
	s_cbranch_vccz .LBB0_731
	s_barrier

.LBB0_860:
	ds_read_b128 v[156:159], v153
	ds_read_b128 v[160:163], v153 offset:1024
	ds_read_b128 v[164:167], v153 offset:2048
	ds_read_b128 v[168:171], v153 offset:3072
	ds_read_b128 v[172:175], v154
	ds_read_b128 v[176:179], v154 offset:1024
	ds_read_b128 v[180:183], v154 offset:2048
	ds_read_b128 v[184:187], v154 offset:3072
	s_add_u32 s28, s26, 0xfff00080
	s_addc_u32 s29, s27, -1
	s_cmp_eq_u32 s51, 60
	s_cselect_b32 s31, s19, s29
	s_cselect_b32 s30, s47, s28
	s_cselect_b32 s29, s17, s50
	s_cselect_b32 s28, s48, s49
	v_lshl_add_u64 v[146:147], s[26:27], 0, v[138:139]
	s_add_i32 m0, s25, 0xc000
	ds_read_b128 v[188:191], v155
	ds_read_b128 v[192:195], v155 offset:1024
	ds_read_b128 v[196:199], v155 offset:2048
	ds_read_b128 v[200:203], v155 offset:3072
	ds_read_b128 v[204:207], v155 offset:4096
	ds_read_b128 v[208:211], v155 offset:5120
	ds_read_b128 v[212:215], v155 offset:6144
	ds_read_b128 v[216:219], v155 offset:7168
	global_load_lds_dwordx4 v[146:147], off
	v_lshl_add_u64 v[146:147], s[26:27], 0, v[140:141]
	s_add_i32 m0, s25, 0xe000
	s_nop 0
	global_load_lds_dwordx4 v[146:147], off
	s_waitcnt vmcnt(8)
	s_waitcnt lgkmcnt(0)
	s_setprio 1
	s_barrier
	v_mfma_f32_16x16x32_bf16 v[126:129], v[156:159], v[188:191], v[126:129]
	v_mfma_f32_16x16x32_bf16 v[122:125], v[164:167], v[188:191], v[122:125]
	v_mfma_f32_16x16x32_bf16 v[110:113], v[156:159], v[196:199], v[110:113]
	v_mfma_f32_16x16x32_bf16 v[106:109], v[164:167], v[196:199], v[106:109]
	v_mfma_f32_16x16x32_bf16 v[94:97], v[156:159], v[204:207], v[94:97]
	v_mfma_f32_16x16x32_bf16 v[90:93], v[164:167], v[204:207], v[90:93]
	v_mfma_f32_16x16x32_bf16 v[78:81], v[156:159], v[212:215], v[78:81]
	v_mfma_f32_16x16x32_bf16 v[74:77], v[164:167], v[212:215], v[74:77]
	v_mfma_f32_16x16x32_bf16 v[126:129], v[160:163], v[192:195], v[126:129]
	v_mfma_f32_16x16x32_bf16 v[122:125], v[168:171], v[192:195], v[122:125]
	v_mfma_f32_16x16x32_bf16 v[110:113], v[160:163], v[200:203], v[110:113]
	v_mfma_f32_16x16x32_bf16 v[106:109], v[168:171], v[200:203], v[106:109]
	v_mfma_f32_16x16x32_bf16 v[94:97], v[160:163], v[208:211], v[94:97]
	v_mfma_f32_16x16x32_bf16 v[90:93], v[168:171], v[208:211], v[90:93]
	v_mfma_f32_16x16x32_bf16 v[78:81], v[160:163], v[216:219], v[78:81]
	v_mfma_f32_16x16x32_bf16 v[74:77], v[168:171], v[216:219], v[74:77]
	v_mfma_f32_16x16x32_bf16 v[118:121], v[172:175], v[188:191], v[118:121]
	v_mfma_f32_16x16x32_bf16 v[114:117], v[180:183], v[188:191], v[114:117]
	v_mfma_f32_16x16x32_bf16 v[102:105], v[172:175], v[196:199], v[102:105]
	v_mfma_f32_16x16x32_bf16 v[98:101], v[180:183], v[196:199], v[98:101]
	v_mfma_f32_16x16x32_bf16 v[86:89], v[172:175], v[204:207], v[86:89]
	v_mfma_f32_16x16x32_bf16 v[82:85], v[180:183], v[204:207], v[82:85]
	v_mfma_f32_16x16x32_bf16 v[70:73], v[172:175], v[212:215], v[70:73]
	v_mfma_f32_16x16x32_bf16 v[66:69], v[180:183], v[212:215], v[66:69]
	v_mfma_f32_16x16x32_bf16 v[118:121], v[176:179], v[192:195], v[118:121]
	v_mfma_f32_16x16x32_bf16 v[114:117], v[184:187], v[192:195], v[114:117]
	v_mfma_f32_16x16x32_bf16 v[102:105], v[176:179], v[200:203], v[102:105]
	v_mfma_f32_16x16x32_bf16 v[98:101], v[184:187], v[200:203], v[98:101]
	v_mfma_f32_16x16x32_bf16 v[86:89], v[176:179], v[208:211], v[86:89]
	v_mfma_f32_16x16x32_bf16 v[82:85], v[184:187], v[208:211], v[82:85]
	v_mfma_f32_16x16x32_bf16 v[70:73], v[176:179], v[216:219], v[70:73]
	v_mfma_f32_16x16x32_bf16 v[66:69], v[184:187], v[216:219], v[66:69]
	s_barrier
	s_setprio 0
	s_add_i32 s52, s44, s34
	v_lshl_add_u64 v[146:147], s[28:29], 0, v[134:135]
	s_mov_b32 m0, s52
	ds_read_b128 v[188:191], v155 offset:16384
	ds_read_b128 v[192:195], v155 offset:17408
	ds_read_b128 v[196:199], v155 offset:18432
	ds_read_b128 v[200:203], v155 offset:19456
	ds_read_b128 v[204:207], v155 offset:20480
	ds_read_b128 v[208:211], v155 offset:21504
	ds_read_b128 v[212:215], v155 offset:22528
	ds_read_b128 v[216:219], v155 offset:23552
	global_load_lds_dwordx4 v[146:147], off
	s_add_i32 m0, s52, 0x2000
	s_add_u32 s52, s28, 0x100000
	v_lshl_add_u64 v[220:221], s[28:29], 0, v[130:131]
	s_addc_u32 s53, s29, 0
	s_add_i32 s54, s45, s34
	global_load_lds_dwordx4 v[220:221], off
	v_lshl_add_u64 v[222:223], s[52:53], 0, v[134:135]
	s_mov_b32 m0, s54
	v_lshl_add_u64 v[224:225], s[30:31], 0, v[132:133]
	global_load_lds_dwordx4 v[222:223], off
	v_lshl_add_u64 v[222:223], s[52:53], 0, v[130:131]
	s_add_i32 m0, s54, 0x2000
	s_nop 0
	global_load_lds_dwordx4 v[222:223], off
	v_lshl_add_u64 v[222:223], s[30:31], 0, v[136:137]
	s_mov_b32 m0, s25
	s_nop 0
	global_load_lds_dwordx4 v[222:223], off
	s_mov_b32 m0, s37
	s_nop 0
	global_load_lds_dwordx4 v[224:225], off
	s_waitcnt vmcnt(8)
	s_waitcnt lgkmcnt(0)
	s_setprio 1
	s_barrier
	v_mfma_f32_16x16x32_bf16 v[62:65], v[156:159], v[188:191], v[62:65]
	v_mfma_f32_16x16x32_bf16 v[58:61], v[164:167], v[188:191], v[58:61]
	v_mfma_f32_16x16x32_bf16 v[46:49], v[156:159], v[196:199], v[46:49]
	v_mfma_f32_16x16x32_bf16 v[42:45], v[164:167], v[196:199], v[42:45]
	v_mfma_f32_16x16x32_bf16 v[30:33], v[156:159], v[204:207], v[30:33]
	v_mfma_f32_16x16x32_bf16 v[26:29], v[164:167], v[204:207], v[26:29]
	v_mfma_f32_16x16x32_bf16 v[14:17], v[156:159], v[212:215], v[14:17]
	v_mfma_f32_16x16x32_bf16 v[10:13], v[164:167], v[212:215], v[10:13]
	v_mfma_f32_16x16x32_bf16 v[62:65], v[160:163], v[192:195], v[62:65]
	v_mfma_f32_16x16x32_bf16 v[58:61], v[168:171], v[192:195], v[58:61]
	v_mfma_f32_16x16x32_bf16 v[46:49], v[160:163], v[200:203], v[46:49]
	v_mfma_f32_16x16x32_bf16 v[42:45], v[168:171], v[200:203], v[42:45]
	v_mfma_f32_16x16x32_bf16 v[30:33], v[160:163], v[208:211], v[30:33]
	v_mfma_f32_16x16x32_bf16 v[26:29], v[168:171], v[208:211], v[26:29]
	v_mfma_f32_16x16x32_bf16 v[14:17], v[160:163], v[216:219], v[14:17]
	v_mfma_f32_16x16x32_bf16 v[10:13], v[168:171], v[216:219], v[10:13]
	v_mfma_f32_16x16x32_bf16 v[54:57], v[172:175], v[188:191], v[54:57]
	v_mfma_f32_16x16x32_bf16 v[50:53], v[180:183], v[188:191], v[50:53]
	v_mfma_f32_16x16x32_bf16 v[38:41], v[172:175], v[196:199], v[38:41]
	v_mfma_f32_16x16x32_bf16 v[34:37], v[180:183], v[196:199], v[34:37]
	v_mfma_f32_16x16x32_bf16 v[22:25], v[172:175], v[204:207], v[22:25]
	v_mfma_f32_16x16x32_bf16 v[18:21], v[180:183], v[204:207], v[18:21]
	v_mfma_f32_16x16x32_bf16 v[6:9], v[172:175], v[212:215], v[6:9]
	v_mfma_f32_16x16x32_bf16 v[2:5], v[180:183], v[212:215], v[2:5]
	v_mfma_f32_16x16x32_bf16 v[54:57], v[176:179], v[192:195], v[54:57]
	v_mfma_f32_16x16x32_bf16 v[50:53], v[184:187], v[192:195], v[50:53]
	v_mfma_f32_16x16x32_bf16 v[38:41], v[176:179], v[200:203], v[38:41]
	v_mfma_f32_16x16x32_bf16 v[34:37], v[184:187], v[200:203], v[34:37]
	v_mfma_f32_16x16x32_bf16 v[22:25], v[176:179], v[208:211], v[22:25]
	v_mfma_f32_16x16x32_bf16 v[18:21], v[184:187], v[208:211], v[18:21]
	v_mfma_f32_16x16x32_bf16 v[6:9], v[176:179], v[216:219], v[6:9]
	v_mfma_f32_16x16x32_bf16 v[2:5], v[184:187], v[216:219], v[2:5]
	s_barrier
	s_setprio 0
	s_add_i32 s52, 0, 0x18000
	s_add_i32 s53, 0, 0x1c000
	v_add_u32_e32 v168, s52, v151
	v_add_u32_e32 v184, s53, v151
	ds_read_b128 v[156:159], v168
	ds_read_b128 v[160:163], v168 offset:1024
	ds_read_b128 v[164:167], v168 offset:2048
	ds_read_b128 v[168:171], v168 offset:3072
	ds_read_b128 v[172:175], v184
	ds_read_b128 v[176:179], v184 offset:1024
	ds_read_b128 v[180:183], v184 offset:2048
	ds_read_b128 v[184:187], v184 offset:3072
	s_add_u32 s30, s30, 0x100000
	s_addc_u32 s31, s31, 0
	s_mov_b32 m0, s38
	v_lshl_add_u64 v[226:227], s[30:31], 0, v[136:137]
	ds_read_b128 v[188:191], v155 offset:32768
	ds_read_b128 v[192:195], v155 offset:33792
	ds_read_b128 v[196:199], v155 offset:34816
	ds_read_b128 v[200:203], v155 offset:35840
	ds_read_b128 v[204:207], v155 offset:36864
	ds_read_b128 v[208:211], v155 offset:37888
	ds_read_b128 v[212:215], v155 offset:38912
	ds_read_b128 v[216:219], v155 offset:39936
	global_load_lds_dwordx4 v[226:227], off
	v_lshl_add_u64 v[226:227], s[30:31], 0, v[132:133]
	s_mov_b32 m0, s39
	s_nop 0
	global_load_lds_dwordx4 v[226:227], off
	s_waitcnt vmcnt(8)
	s_waitcnt lgkmcnt(0)
	s_setprio 1
	s_barrier
	v_mfma_f32_16x16x32_bf16 v[126:129], v[156:159], v[188:191], v[126:129]
	v_mfma_f32_16x16x32_bf16 v[122:125], v[164:167], v[188:191], v[122:125]
	v_mfma_f32_16x16x32_bf16 v[110:113], v[156:159], v[196:199], v[110:113]
	v_mfma_f32_16x16x32_bf16 v[106:109], v[164:167], v[196:199], v[106:109]
	v_mfma_f32_16x16x32_bf16 v[94:97], v[156:159], v[204:207], v[94:97]
	v_mfma_f32_16x16x32_bf16 v[90:93], v[164:167], v[204:207], v[90:93]
	v_mfma_f32_16x16x32_bf16 v[78:81], v[156:159], v[212:215], v[78:81]
	v_mfma_f32_16x16x32_bf16 v[74:77], v[164:167], v[212:215], v[74:77]
	v_mfma_f32_16x16x32_bf16 v[126:129], v[160:163], v[192:195], v[126:129]
	v_mfma_f32_16x16x32_bf16 v[122:125], v[168:171], v[192:195], v[122:125]
	v_mfma_f32_16x16x32_bf16 v[110:113], v[160:163], v[200:203], v[110:113]
	v_mfma_f32_16x16x32_bf16 v[106:109], v[168:171], v[200:203], v[106:109]
	v_mfma_f32_16x16x32_bf16 v[94:97], v[160:163], v[208:211], v[94:97]
	v_mfma_f32_16x16x32_bf16 v[90:93], v[168:171], v[208:211], v[90:93]
	v_mfma_f32_16x16x32_bf16 v[78:81], v[160:163], v[216:219], v[78:81]
	v_mfma_f32_16x16x32_bf16 v[74:77], v[168:171], v[216:219], v[74:77]
	v_mfma_f32_16x16x32_bf16 v[118:121], v[172:175], v[188:191], v[118:121]
	v_mfma_f32_16x16x32_bf16 v[114:117], v[180:183], v[188:191], v[114:117]
	v_mfma_f32_16x16x32_bf16 v[102:105], v[172:175], v[196:199], v[102:105]
	v_mfma_f32_16x16x32_bf16 v[98:101], v[180:183], v[196:199], v[98:101]
	v_mfma_f32_16x16x32_bf16 v[86:89], v[172:175], v[204:207], v[86:89]
	v_mfma_f32_16x16x32_bf16 v[82:85], v[180:183], v[204:207], v[82:85]
	v_mfma_f32_16x16x32_bf16 v[70:73], v[172:175], v[212:215], v[70:73]
	v_mfma_f32_16x16x32_bf16 v[66:69], v[180:183], v[212:215], v[66:69]
	v_mfma_f32_16x16x32_bf16 v[118:121], v[176:179], v[192:195], v[118:121]
	v_mfma_f32_16x16x32_bf16 v[114:117], v[184:187], v[192:195], v[114:117]
	v_mfma_f32_16x16x32_bf16 v[102:105], v[176:179], v[200:203], v[102:105]
	v_mfma_f32_16x16x32_bf16 v[98:101], v[184:187], v[200:203], v[98:101]
	v_mfma_f32_16x16x32_bf16 v[86:89], v[176:179], v[208:211], v[86:89]
	v_mfma_f32_16x16x32_bf16 v[82:85], v[184:187], v[208:211], v[82:85]
	v_mfma_f32_16x16x32_bf16 v[70:73], v[176:179], v[216:219], v[70:73]
	v_mfma_f32_16x16x32_bf16 v[66:69], v[184:187], v[216:219], v[66:69]
	s_barrier
	s_setprio 0
	s_add_i32 s30, s52, s34
	v_lshl_add_u64 v[146:147], v[146:147], 0, s[12:13]
	s_mov_b32 m0, s30
	ds_read_b128 v[188:191], v155 offset:49152
	ds_read_b128 v[192:195], v155 offset:50176
	ds_read_b128 v[196:199], v155 offset:51200
	ds_read_b128 v[200:203], v155 offset:52224
	ds_read_b128 v[204:207], v155 offset:53248
	ds_read_b128 v[208:211], v155 offset:54272
	ds_read_b128 v[212:215], v155 offset:55296
	ds_read_b128 v[216:219], v155 offset:56320
	global_load_lds_dwordx4 v[146:147], off
	s_add_i32 m0, s30, 0x2000
	s_add_u32 s28, s28, 0x100080
	v_lshl_add_u64 v[146:147], v[220:221], 0, s[12:13]
	s_addc_u32 s29, s29, 0
	s_add_i32 s30, s53, s34
	global_load_lds_dwordx4 v[146:147], off
	v_lshl_add_u64 v[146:147], s[28:29], 0, v[134:135]
	s_mov_b32 m0, s30
	s_nop 0
	global_load_lds_dwordx4 v[146:147], off
	v_lshl_add_u64 v[146:147], s[28:29], 0, v[130:131]
	s_add_i32 m0, s30, 0x2000
	s_nop 0
	global_load_lds_dwordx4 v[146:147], off
	v_lshl_add_u64 v[146:147], v[222:223], 0, s[12:13]
	s_mov_b32 m0, s41
	s_nop 0
	global_load_lds_dwordx4 v[146:147], off
	v_lshl_add_u64 v[146:147], v[224:225], 0, s[12:13]
	s_mov_b32 m0, s42
	s_nop 0
	global_load_lds_dwordx4 v[146:147], off
	s_waitcnt vmcnt(8)
	s_waitcnt lgkmcnt(0)
	s_setprio 1
	s_barrier
	v_mfma_f32_16x16x32_bf16 v[62:65], v[156:159], v[188:191], v[62:65]
	v_mfma_f32_16x16x32_bf16 v[58:61], v[164:167], v[188:191], v[58:61]
	v_mfma_f32_16x16x32_bf16 v[46:49], v[156:159], v[196:199], v[46:49]
	v_mfma_f32_16x16x32_bf16 v[42:45], v[164:167], v[196:199], v[42:45]
	v_mfma_f32_16x16x32_bf16 v[30:33], v[156:159], v[204:207], v[30:33]
	v_mfma_f32_16x16x32_bf16 v[26:29], v[164:167], v[204:207], v[26:29]
	v_mfma_f32_16x16x32_bf16 v[14:17], v[156:159], v[212:215], v[14:17]
	v_mfma_f32_16x16x32_bf16 v[10:13], v[164:167], v[212:215], v[10:13]
	v_mfma_f32_16x16x32_bf16 v[62:65], v[160:163], v[192:195], v[62:65]
	v_mfma_f32_16x16x32_bf16 v[58:61], v[168:171], v[192:195], v[58:61]
	v_mfma_f32_16x16x32_bf16 v[46:49], v[160:163], v[200:203], v[46:49]
	v_mfma_f32_16x16x32_bf16 v[42:45], v[168:171], v[200:203], v[42:45]
	v_mfma_f32_16x16x32_bf16 v[30:33], v[160:163], v[208:211], v[30:33]
	v_mfma_f32_16x16x32_bf16 v[26:29], v[168:171], v[208:211], v[26:29]
	v_mfma_f32_16x16x32_bf16 v[14:17], v[160:163], v[216:219], v[14:17]
	v_mfma_f32_16x16x32_bf16 v[10:13], v[168:171], v[216:219], v[10:13]
	v_mfma_f32_16x16x32_bf16 v[54:57], v[172:175], v[188:191], v[54:57]
	v_mfma_f32_16x16x32_bf16 v[50:53], v[180:183], v[188:191], v[50:53]
	v_mfma_f32_16x16x32_bf16 v[38:41], v[172:175], v[196:199], v[38:41]
	v_mfma_f32_16x16x32_bf16 v[34:37], v[180:183], v[196:199], v[34:37]
	v_mfma_f32_16x16x32_bf16 v[22:25], v[172:175], v[204:207], v[22:25]
	v_mfma_f32_16x16x32_bf16 v[18:21], v[180:183], v[204:207], v[18:21]
	v_mfma_f32_16x16x32_bf16 v[6:9], v[172:175], v[212:215], v[6:9]
	v_mfma_f32_16x16x32_bf16 v[2:5], v[180:183], v[212:215], v[2:5]
	v_mfma_f32_16x16x32_bf16 v[54:57], v[176:179], v[192:195], v[54:57]
	v_mfma_f32_16x16x32_bf16 v[50:53], v[184:187], v[192:195], v[50:53]
	v_mfma_f32_16x16x32_bf16 v[38:41], v[176:179], v[200:203], v[38:41]
	v_mfma_f32_16x16x32_bf16 v[34:37], v[184:187], v[200:203], v[34:37]
	v_mfma_f32_16x16x32_bf16 v[22:25], v[176:179], v[208:211], v[22:25]
	v_mfma_f32_16x16x32_bf16 v[18:21], v[184:187], v[208:211], v[18:21]
	v_mfma_f32_16x16x32_bf16 v[6:9], v[176:179], v[216:219], v[6:9]
	v_mfma_f32_16x16x32_bf16 v[2:5], v[184:187], v[216:219], v[2:5]
	s_barrier
	s_setprio 0
	s_add_i32 s51, s51, 2
	s_add_u32 s26, s26, 0x100
	s_addc_u32 s27, s27, 0
	s_add_u32 s49, s49, 0x100
	s_addc_u32 s50, s50, 0
	s_cmp_gt_u32 s51, 61
	s_cbranch_scc0 .LBB0_860
	s_and_b64 vcc, exec, s[14:15]
	s_cbranch_vccz .LBB0_863
	s_barrier

.LBB0_955:
	ds_read_b128 v[130:133], v199
	ds_read_b128 v[134:137], v199 offset:1024
	ds_read_b128 v[138:141], v199 offset:2048
	ds_read_b128 v[142:145], v199 offset:3072
	ds_read_b128 v[146:149], v200
	ds_read_b128 v[166:169], v200 offset:1024
	ds_read_b128 v[170:173], v200 offset:2048
	ds_read_b128 v[174:177], v200 offset:3072
	s_add_u32 s26, s24, 0xffd50080
	s_addc_u32 s27, s25, -1
	s_cmpk_eq_i32 s50, 0xa8
	s_cselect_b32 s29, s9, s27
	s_cselect_b32 s28, s8, s26
	s_cselect_b32 s27, s23, s49
	s_cselect_b32 s26, s22, s48
	v_lshl_add_u64 v[194:195], s[24:25], 0, v[158:159]
	s_add_i32 m0, s35, 0xc000
	ds_read_b128 v[178:181], v201
	ds_read_b128 v[182:185], v201 offset:1024
	ds_read_b128 v[186:189], v201 offset:2048
	ds_read_b128 v[190:193], v201 offset:3072
	ds_read_b128 v[202:205], v201 offset:4096
	ds_read_b128 v[206:209], v201 offset:5120
	ds_read_b128 v[210:213], v201 offset:6144
	ds_read_b128 v[214:217], v201 offset:7168
	global_load_lds_dwordx4 v[194:195], off
	v_lshl_add_u64 v[194:195], s[24:25], 0, v[160:161]
	s_add_i32 m0, s35, 0xe000
	s_nop 0
	global_load_lds_dwordx4 v[194:195], off
	s_waitcnt vmcnt(8)
	s_waitcnt lgkmcnt(0)
	s_setprio 1
	s_barrier
	v_mfma_f32_16x16x32_bf16 v[126:129], v[130:133], v[178:181], v[126:129]
	v_mfma_f32_16x16x32_bf16 v[122:125], v[138:141], v[178:181], v[122:125]
	v_mfma_f32_16x16x32_bf16 v[118:121], v[130:133], v[186:189], v[118:121]
	v_mfma_f32_16x16x32_bf16 v[114:117], v[138:141], v[186:189], v[114:117]
	v_mfma_f32_16x16x32_bf16 v[110:113], v[130:133], v[202:205], v[110:113]
	v_mfma_f32_16x16x32_bf16 v[106:109], v[138:141], v[202:205], v[106:109]
	v_mfma_f32_16x16x32_bf16 v[102:105], v[130:133], v[210:213], v[102:105]
	v_mfma_f32_16x16x32_bf16 v[98:101], v[138:141], v[210:213], v[98:101]
	v_mfma_f32_16x16x32_bf16 v[126:129], v[134:137], v[182:185], v[126:129]
	v_mfma_f32_16x16x32_bf16 v[122:125], v[142:145], v[182:185], v[122:125]
	v_mfma_f32_16x16x32_bf16 v[118:121], v[134:137], v[190:193], v[118:121]
	v_mfma_f32_16x16x32_bf16 v[114:117], v[142:145], v[190:193], v[114:117]
	v_mfma_f32_16x16x32_bf16 v[110:113], v[134:137], v[206:209], v[110:113]
	v_mfma_f32_16x16x32_bf16 v[106:109], v[142:145], v[206:209], v[106:109]
	v_mfma_f32_16x16x32_bf16 v[102:105], v[134:137], v[214:217], v[102:105]
	v_mfma_f32_16x16x32_bf16 v[98:101], v[142:145], v[214:217], v[98:101]
	v_mfma_f32_16x16x32_bf16 v[62:65], v[146:149], v[178:181], v[62:65]
	v_mfma_f32_16x16x32_bf16 v[58:61], v[170:173], v[178:181], v[58:61]
	v_mfma_f32_16x16x32_bf16 v[54:57], v[146:149], v[186:189], v[54:57]
	v_mfma_f32_16x16x32_bf16 v[50:53], v[170:173], v[186:189], v[50:53]
	v_mfma_f32_16x16x32_bf16 v[46:49], v[146:149], v[202:205], v[46:49]
	v_mfma_f32_16x16x32_bf16 v[42:45], v[170:173], v[202:205], v[42:45]
	v_mfma_f32_16x16x32_bf16 v[38:41], v[146:149], v[210:213], v[38:41]
	v_mfma_f32_16x16x32_bf16 v[34:37], v[170:173], v[210:213], v[34:37]
	v_mfma_f32_16x16x32_bf16 v[62:65], v[166:169], v[182:185], v[62:65]
	v_mfma_f32_16x16x32_bf16 v[58:61], v[174:177], v[182:185], v[58:61]
	v_mfma_f32_16x16x32_bf16 v[54:57], v[166:169], v[190:193], v[54:57]
	v_mfma_f32_16x16x32_bf16 v[50:53], v[174:177], v[190:193], v[50:53]
	v_mfma_f32_16x16x32_bf16 v[46:49], v[166:169], v[206:209], v[46:49]
	v_mfma_f32_16x16x32_bf16 v[42:45], v[174:177], v[206:209], v[42:45]
	v_mfma_f32_16x16x32_bf16 v[38:41], v[166:169], v[214:217], v[38:41]
	v_mfma_f32_16x16x32_bf16 v[34:37], v[174:177], v[214:217], v[34:37]
	s_barrier
	s_setprio 0
	s_add_i32 s51, s43, s34
	v_lshl_add_u64 v[194:195], s[26:27], 0, v[152:153]
	s_mov_b32 m0, s51
	ds_read_b128 v[178:181], v201 offset:16384
	ds_read_b128 v[182:185], v201 offset:17408
	ds_read_b128 v[186:189], v201 offset:18432
	ds_read_b128 v[190:193], v201 offset:19456
	ds_read_b128 v[202:205], v201 offset:20480
	ds_read_b128 v[206:209], v201 offset:21504
	ds_read_b128 v[210:213], v201 offset:22528
	ds_read_b128 v[214:217], v201 offset:23552
	global_load_lds_dwordx4 v[194:195], off
	s_add_i32 m0, s51, 0x2000
	s_add_u32 s52, s26, 0x2b0000
	v_lshl_add_u64 v[218:219], s[26:27], 0, v[156:157]
	s_addc_u32 s53, s27, 0
	s_add_i32 s51, s44, s34
	global_load_lds_dwordx4 v[218:219], off
	v_lshl_add_u64 v[220:221], s[52:53], 0, v[152:153]
	s_mov_b32 m0, s51
	v_lshl_add_u64 v[222:223], s[28:29], 0, v[154:155]
	global_load_lds_dwordx4 v[220:221], off
	v_lshl_add_u64 v[220:221], s[52:53], 0, v[156:157]
	s_add_i32 m0, s51, 0x2000
	s_nop 0
	global_load_lds_dwordx4 v[220:221], off
	v_lshl_add_u64 v[220:221], s[28:29], 0, v[150:151]
	s_mov_b32 m0, s35
	s_nop 0
	global_load_lds_dwordx4 v[220:221], off
	s_mov_b32 m0, s36
	s_nop 0
	global_load_lds_dwordx4 v[222:223], off
	s_waitcnt vmcnt(8)
	s_waitcnt lgkmcnt(0)
	s_setprio 1
	s_barrier
	v_mfma_f32_16x16x32_bf16 v[94:97], v[130:133], v[178:181], v[94:97]
	v_mfma_f32_16x16x32_bf16 v[90:93], v[138:141], v[178:181], v[90:93]
	v_mfma_f32_16x16x32_bf16 v[86:89], v[130:133], v[186:189], v[86:89]
	v_mfma_f32_16x16x32_bf16 v[82:85], v[138:141], v[186:189], v[82:85]
	v_mfma_f32_16x16x32_bf16 v[78:81], v[130:133], v[202:205], v[78:81]
	v_mfma_f32_16x16x32_bf16 v[74:77], v[138:141], v[202:205], v[74:77]
	v_mfma_f32_16x16x32_bf16 v[70:73], v[130:133], v[210:213], v[70:73]
	v_mfma_f32_16x16x32_bf16 v[66:69], v[138:141], v[210:213], v[66:69]
	v_mfma_f32_16x16x32_bf16 v[94:97], v[134:137], v[182:185], v[94:97]
	v_mfma_f32_16x16x32_bf16 v[90:93], v[142:145], v[182:185], v[90:93]
	v_mfma_f32_16x16x32_bf16 v[86:89], v[134:137], v[190:193], v[86:89]
	v_mfma_f32_16x16x32_bf16 v[82:85], v[142:145], v[190:193], v[82:85]
	v_mfma_f32_16x16x32_bf16 v[78:81], v[134:137], v[206:209], v[78:81]
	v_mfma_f32_16x16x32_bf16 v[74:77], v[142:145], v[206:209], v[74:77]
	v_mfma_f32_16x16x32_bf16 v[70:73], v[134:137], v[214:217], v[70:73]
	v_mfma_f32_16x16x32_bf16 v[66:69], v[142:145], v[214:217], v[66:69]
	v_mfma_f32_16x16x32_bf16 v[30:33], v[146:149], v[178:181], v[30:33]
	v_mfma_f32_16x16x32_bf16 v[26:29], v[170:173], v[178:181], v[26:29]
	v_mfma_f32_16x16x32_bf16 v[22:25], v[146:149], v[186:189], v[22:25]
	v_mfma_f32_16x16x32_bf16 v[18:21], v[170:173], v[186:189], v[18:21]
	v_mfma_f32_16x16x32_bf16 v[14:17], v[146:149], v[202:205], v[14:17]
	v_mfma_f32_16x16x32_bf16 v[10:13], v[170:173], v[202:205], v[10:13]
	v_mfma_f32_16x16x32_bf16 v[6:9], v[146:149], v[210:213], v[6:9]
	v_mfma_f32_16x16x32_bf16 v[2:5], v[170:173], v[210:213], v[2:5]
	v_mfma_f32_16x16x32_bf16 v[30:33], v[166:169], v[182:185], v[30:33]
	v_mfma_f32_16x16x32_bf16 v[26:29], v[174:177], v[182:185], v[26:29]
	v_mfma_f32_16x16x32_bf16 v[22:25], v[166:169], v[190:193], v[22:25]
	v_mfma_f32_16x16x32_bf16 v[18:21], v[174:177], v[190:193], v[18:21]
	v_mfma_f32_16x16x32_bf16 v[14:17], v[166:169], v[206:209], v[14:17]
	v_mfma_f32_16x16x32_bf16 v[10:13], v[174:177], v[206:209], v[10:13]
	v_mfma_f32_16x16x32_bf16 v[6:9], v[166:169], v[214:217], v[6:9]
	v_mfma_f32_16x16x32_bf16 v[2:5], v[174:177], v[214:217], v[2:5]
	s_barrier
	s_setprio 0
	s_add_i32 s51, 0, 0x18000
	s_add_i32 s52, 0, 0x1c000
	v_add_u32_e32 v142, s51, v197
	v_add_u32_e32 v174, s52, v197
	ds_read_b128 v[130:133], v142
	ds_read_b128 v[134:137], v142 offset:1024
	ds_read_b128 v[138:141], v142 offset:2048
	ds_read_b128 v[142:145], v142 offset:3072
	ds_read_b128 v[146:149], v174
	ds_read_b128 v[166:169], v174 offset:1024
	ds_read_b128 v[170:173], v174 offset:2048
	ds_read_b128 v[174:177], v174 offset:3072
	s_add_u32 s28, s28, 0x2b0000
	s_addc_u32 s29, s29, 0
	s_mov_b32 m0, s37
	v_lshl_add_u64 v[224:225], s[28:29], 0, v[150:151]
	ds_read_b128 v[178:181], v201 offset:32768
	ds_read_b128 v[182:185], v201 offset:33792
	ds_read_b128 v[186:189], v201 offset:34816
	ds_read_b128 v[190:193], v201 offset:35840
	ds_read_b128 v[202:205], v201 offset:36864
	ds_read_b128 v[206:209], v201 offset:37888
	ds_read_b128 v[210:213], v201 offset:38912
	ds_read_b128 v[214:217], v201 offset:39936
	global_load_lds_dwordx4 v[224:225], off
	v_lshl_add_u64 v[224:225], s[28:29], 0, v[154:155]
	s_mov_b32 m0, s38
	s_nop 0
	global_load_lds_dwordx4 v[224:225], off
	s_waitcnt vmcnt(8)
	s_waitcnt lgkmcnt(0)
	s_setprio 1
	s_barrier
	v_mfma_f32_16x16x32_bf16 v[126:129], v[130:133], v[178:181], v[126:129]
	v_mfma_f32_16x16x32_bf16 v[122:125], v[138:141], v[178:181], v[122:125]
	v_mfma_f32_16x16x32_bf16 v[118:121], v[130:133], v[186:189], v[118:121]
	v_mfma_f32_16x16x32_bf16 v[114:117], v[138:141], v[186:189], v[114:117]
	v_mfma_f32_16x16x32_bf16 v[110:113], v[130:133], v[202:205], v[110:113]
	v_mfma_f32_16x16x32_bf16 v[106:109], v[138:141], v[202:205], v[106:109]
	v_mfma_f32_16x16x32_bf16 v[102:105], v[130:133], v[210:213], v[102:105]
	v_mfma_f32_16x16x32_bf16 v[98:101], v[138:141], v[210:213], v[98:101]
	v_mfma_f32_16x16x32_bf16 v[126:129], v[134:137], v[182:185], v[126:129]
	v_mfma_f32_16x16x32_bf16 v[122:125], v[142:145], v[182:185], v[122:125]
	v_mfma_f32_16x16x32_bf16 v[118:121], v[134:137], v[190:193], v[118:121]
	v_mfma_f32_16x16x32_bf16 v[114:117], v[142:145], v[190:193], v[114:117]
	v_mfma_f32_16x16x32_bf16 v[110:113], v[134:137], v[206:209], v[110:113]
	v_mfma_f32_16x16x32_bf16 v[106:109], v[142:145], v[206:209], v[106:109]
	v_mfma_f32_16x16x32_bf16 v[102:105], v[134:137], v[214:217], v[102:105]
	v_mfma_f32_16x16x32_bf16 v[98:101], v[142:145], v[214:217], v[98:101]
	v_mfma_f32_16x16x32_bf16 v[62:65], v[146:149], v[178:181], v[62:65]
	v_mfma_f32_16x16x32_bf16 v[58:61], v[170:173], v[178:181], v[58:61]
	v_mfma_f32_16x16x32_bf16 v[54:57], v[146:149], v[186:189], v[54:57]
	v_mfma_f32_16x16x32_bf16 v[50:53], v[170:173], v[186:189], v[50:53]
	v_mfma_f32_16x16x32_bf16 v[46:49], v[146:149], v[202:205], v[46:49]
	v_mfma_f32_16x16x32_bf16 v[42:45], v[170:173], v[202:205], v[42:45]
	v_mfma_f32_16x16x32_bf16 v[38:41], v[146:149], v[210:213], v[38:41]
	v_mfma_f32_16x16x32_bf16 v[34:37], v[170:173], v[210:213], v[34:37]
	v_mfma_f32_16x16x32_bf16 v[62:65], v[166:169], v[182:185], v[62:65]
	v_mfma_f32_16x16x32_bf16 v[58:61], v[174:177], v[182:185], v[58:61]
	v_mfma_f32_16x16x32_bf16 v[54:57], v[166:169], v[190:193], v[54:57]
	v_mfma_f32_16x16x32_bf16 v[50:53], v[174:177], v[190:193], v[50:53]
	v_mfma_f32_16x16x32_bf16 v[46:49], v[166:169], v[206:209], v[46:49]
	v_mfma_f32_16x16x32_bf16 v[42:45], v[174:177], v[206:209], v[42:45]
	v_mfma_f32_16x16x32_bf16 v[38:41], v[166:169], v[214:217], v[38:41]
	v_mfma_f32_16x16x32_bf16 v[34:37], v[174:177], v[214:217], v[34:37]
	s_barrier
	s_setprio 0
	s_add_i32 s28, s51, s34
	v_lshl_add_u64 v[194:195], v[194:195], 0, s[16:17]
	s_mov_b32 m0, s28
	ds_read_b128 v[178:181], v201 offset:49152
	ds_read_b128 v[182:185], v201 offset:50176
	ds_read_b128 v[186:189], v201 offset:51200
	ds_read_b128 v[190:193], v201 offset:52224
	ds_read_b128 v[202:205], v201 offset:53248
	ds_read_b128 v[206:209], v201 offset:54272
	ds_read_b128 v[210:213], v201 offset:55296
	ds_read_b128 v[214:217], v201 offset:56320
	global_load_lds_dwordx4 v[194:195], off
	s_add_i32 m0, s28, 0x2000
	s_add_u32 s26, s26, 0x2b0080
	v_lshl_add_u64 v[194:195], v[218:219], 0, s[16:17]
	s_addc_u32 s27, s27, 0
	s_add_i32 s28, s52, s34
	global_load_lds_dwordx4 v[194:195], off
	v_lshl_add_u64 v[194:195], s[26:27], 0, v[152:153]
	s_mov_b32 m0, s28
	s_nop 0
	global_load_lds_dwordx4 v[194:195], off
	v_lshl_add_u64 v[194:195], s[26:27], 0, v[156:157]
	s_add_i32 m0, s28, 0x2000
	s_nop 0
	global_load_lds_dwordx4 v[194:195], off
	v_lshl_add_u64 v[194:195], v[220:221], 0, s[16:17]
	s_mov_b32 m0, s40
	s_nop 0
	global_load_lds_dwordx4 v[194:195], off
	v_lshl_add_u64 v[194:195], v[222:223], 0, s[16:17]
	s_mov_b32 m0, s41
	s_nop 0
	global_load_lds_dwordx4 v[194:195], off
	s_waitcnt vmcnt(8)
	s_waitcnt lgkmcnt(0)
	s_setprio 1
	s_barrier
	v_mfma_f32_16x16x32_bf16 v[94:97], v[130:133], v[178:181], v[94:97]
	v_mfma_f32_16x16x32_bf16 v[90:93], v[138:141], v[178:181], v[90:93]
	v_mfma_f32_16x16x32_bf16 v[86:89], v[130:133], v[186:189], v[86:89]
	v_mfma_f32_16x16x32_bf16 v[82:85], v[138:141], v[186:189], v[82:85]
	v_mfma_f32_16x16x32_bf16 v[78:81], v[130:133], v[202:205], v[78:81]
	v_mfma_f32_16x16x32_bf16 v[74:77], v[138:141], v[202:205], v[74:77]
	v_mfma_f32_16x16x32_bf16 v[70:73], v[130:133], v[210:213], v[70:73]
	v_mfma_f32_16x16x32_bf16 v[66:69], v[138:141], v[210:213], v[66:69]
	v_mfma_f32_16x16x32_bf16 v[94:97], v[134:137], v[182:185], v[94:97]
	v_mfma_f32_16x16x32_bf16 v[90:93], v[142:145], v[182:185], v[90:93]
	v_mfma_f32_16x16x32_bf16 v[86:89], v[134:137], v[190:193], v[86:89]
	v_mfma_f32_16x16x32_bf16 v[82:85], v[142:145], v[190:193], v[82:85]
	v_mfma_f32_16x16x32_bf16 v[78:81], v[134:137], v[206:209], v[78:81]
	v_mfma_f32_16x16x32_bf16 v[74:77], v[142:145], v[206:209], v[74:77]
	v_mfma_f32_16x16x32_bf16 v[70:73], v[134:137], v[214:217], v[70:73]
	v_mfma_f32_16x16x32_bf16 v[66:69], v[142:145], v[214:217], v[66:69]
	v_mfma_f32_16x16x32_bf16 v[30:33], v[146:149], v[178:181], v[30:33]
	v_mfma_f32_16x16x32_bf16 v[26:29], v[170:173], v[178:181], v[26:29]
	v_mfma_f32_16x16x32_bf16 v[22:25], v[146:149], v[186:189], v[22:25]
	v_mfma_f32_16x16x32_bf16 v[18:21], v[170:173], v[186:189], v[18:21]
	v_mfma_f32_16x16x32_bf16 v[14:17], v[146:149], v[202:205], v[14:17]
	v_mfma_f32_16x16x32_bf16 v[10:13], v[170:173], v[202:205], v[10:13]
	v_mfma_f32_16x16x32_bf16 v[6:9], v[146:149], v[210:213], v[6:9]
	v_mfma_f32_16x16x32_bf16 v[2:5], v[170:173], v[210:213], v[2:5]
	v_mfma_f32_16x16x32_bf16 v[30:33], v[166:169], v[182:185], v[30:33]
	v_mfma_f32_16x16x32_bf16 v[26:29], v[174:177], v[182:185], v[26:29]
	v_mfma_f32_16x16x32_bf16 v[22:25], v[166:169], v[190:193], v[22:25]
	v_mfma_f32_16x16x32_bf16 v[18:21], v[174:177], v[190:193], v[18:21]
	v_mfma_f32_16x16x32_bf16 v[14:17], v[166:169], v[206:209], v[14:17]
	v_mfma_f32_16x16x32_bf16 v[10:13], v[174:177], v[206:209], v[10:13]
	v_mfma_f32_16x16x32_bf16 v[6:9], v[166:169], v[214:217], v[6:9]
	v_mfma_f32_16x16x32_bf16 v[2:5], v[174:177], v[214:217], v[2:5]
	s_barrier
	s_setprio 0
	s_add_i32 s50, s50, 2
	s_add_u32 s24, s24, 0x100
	s_addc_u32 s25, s25, 0
	s_add_u32 s48, s48, 0x100
	s_addc_u32 s49, s49, 0
	s_cmpk_gt_u32 s50, 0xa9
	s_cbranch_scc0 .LBB0_955
	s_and_b64 vcc, exec, s[18:19]
	s_cbranch_vccz .LBB0_958
	s_barrier

.LBB0_1087:
	ds_read_b128 v[148:151], v156
	ds_read_b128 v[160:163], v156 offset:1024
	ds_read_b128 v[164:167], v156 offset:2048
	ds_read_b128 v[168:171], v156 offset:3072
	ds_read_b128 v[172:175], v157
	ds_read_b128 v[176:179], v157 offset:1024
	ds_read_b128 v[180:183], v157 offset:2048
	ds_read_b128 v[184:187], v157 offset:3072
	s_add_u32 s28, s26, 0xfff00080
	s_addc_u32 s29, s27, -1
	s_cmp_eq_u32 s51, 60
	s_cselect_b32 s31, s19, s29
	s_cselect_b32 s30, s47, s28
	s_cselect_b32 s29, s17, s50
	s_cselect_b32 s28, s48, s49
	v_lshl_add_u64 v[220:221], s[26:27], 0, v[138:139]
	s_add_i32 m0, s25, 0xc000
	ds_read_b128 v[188:191], v158
	ds_read_b128 v[192:195], v158 offset:1024
	ds_read_b128 v[196:199], v158 offset:2048
	ds_read_b128 v[200:203], v158 offset:3072
	ds_read_b128 v[204:207], v158 offset:4096
	ds_read_b128 v[208:211], v158 offset:5120
	ds_read_b128 v[212:215], v158 offset:6144
	ds_read_b128 v[216:219], v158 offset:7168
	global_load_lds_dwordx4 v[220:221], off
	v_lshl_add_u64 v[220:221], s[26:27], 0, v[140:141]
	s_add_i32 m0, s25, 0xe000
	s_nop 0
	global_load_lds_dwordx4 v[220:221], off
	s_waitcnt vmcnt(8)
	s_waitcnt lgkmcnt(0)
	s_setprio 1
	s_barrier
	v_mfma_f32_16x16x32_bf16 v[126:129], v[148:151], v[188:191], v[126:129]
	v_mfma_f32_16x16x32_bf16 v[122:125], v[164:167], v[188:191], v[122:125]
	v_mfma_f32_16x16x32_bf16 v[114:117], v[148:151], v[196:199], v[114:117]
	v_mfma_f32_16x16x32_bf16 v[106:109], v[164:167], v[196:199], v[106:109]
	v_mfma_f32_16x16x32_bf16 v[98:101], v[148:151], v[204:207], v[98:101]
	v_mfma_f32_16x16x32_bf16 v[90:93], v[164:167], v[204:207], v[90:93]
	v_mfma_f32_16x16x32_bf16 v[82:85], v[148:151], v[212:215], v[82:85]
	v_mfma_f32_16x16x32_bf16 v[74:77], v[164:167], v[212:215], v[74:77]
	v_mfma_f32_16x16x32_bf16 v[126:129], v[160:163], v[192:195], v[126:129]
	v_mfma_f32_16x16x32_bf16 v[122:125], v[168:171], v[192:195], v[122:125]
	v_mfma_f32_16x16x32_bf16 v[114:117], v[160:163], v[200:203], v[114:117]
	v_mfma_f32_16x16x32_bf16 v[106:109], v[168:171], v[200:203], v[106:109]
	v_mfma_f32_16x16x32_bf16 v[98:101], v[160:163], v[208:211], v[98:101]
	v_mfma_f32_16x16x32_bf16 v[90:93], v[168:171], v[208:211], v[90:93]
	v_mfma_f32_16x16x32_bf16 v[82:85], v[160:163], v[216:219], v[82:85]
	v_mfma_f32_16x16x32_bf16 v[74:77], v[168:171], v[216:219], v[74:77]
	v_mfma_f32_16x16x32_bf16 v[118:121], v[172:175], v[188:191], v[118:121]
	v_mfma_f32_16x16x32_bf16 v[110:113], v[180:183], v[188:191], v[110:113]
	v_mfma_f32_16x16x32_bf16 v[102:105], v[172:175], v[196:199], v[102:105]
	v_mfma_f32_16x16x32_bf16 v[94:97], v[180:183], v[196:199], v[94:97]
	v_mfma_f32_16x16x32_bf16 v[86:89], v[172:175], v[204:207], v[86:89]
	v_mfma_f32_16x16x32_bf16 v[78:81], v[180:183], v[204:207], v[78:81]
	v_mfma_f32_16x16x32_bf16 v[70:73], v[172:175], v[212:215], v[70:73]
	v_mfma_f32_16x16x32_bf16 v[66:69], v[180:183], v[212:215], v[66:69]
	v_mfma_f32_16x16x32_bf16 v[118:121], v[176:179], v[192:195], v[118:121]
	v_mfma_f32_16x16x32_bf16 v[110:113], v[184:187], v[192:195], v[110:113]
	v_mfma_f32_16x16x32_bf16 v[102:105], v[176:179], v[200:203], v[102:105]
	v_mfma_f32_16x16x32_bf16 v[94:97], v[184:187], v[200:203], v[94:97]
	v_mfma_f32_16x16x32_bf16 v[86:89], v[176:179], v[208:211], v[86:89]
	v_mfma_f32_16x16x32_bf16 v[78:81], v[184:187], v[208:211], v[78:81]
	v_mfma_f32_16x16x32_bf16 v[70:73], v[176:179], v[216:219], v[70:73]
	v_mfma_f32_16x16x32_bf16 v[66:69], v[184:187], v[216:219], v[66:69]
	s_barrier
	s_setprio 0
	s_add_i32 s52, s44, s34
	v_lshl_add_u64 v[220:221], s[28:29], 0, v[134:135]
	s_mov_b32 m0, s52
	ds_read_b128 v[188:191], v158 offset:16384
	ds_read_b128 v[192:195], v158 offset:17408
	ds_read_b128 v[196:199], v158 offset:18432
	ds_read_b128 v[200:203], v158 offset:19456
	ds_read_b128 v[204:207], v158 offset:20480
	ds_read_b128 v[208:211], v158 offset:21504
	ds_read_b128 v[212:215], v158 offset:22528
	ds_read_b128 v[216:219], v158 offset:23552
	global_load_lds_dwordx4 v[220:221], off
	s_add_i32 m0, s52, 0x2000
	s_add_u32 s52, s28, 0x100000
	v_lshl_add_u64 v[222:223], s[28:29], 0, v[130:131]
	s_addc_u32 s53, s29, 0
	s_add_i32 s54, s45, s34
	global_load_lds_dwordx4 v[222:223], off
	v_lshl_add_u64 v[224:225], s[52:53], 0, v[134:135]
	s_mov_b32 m0, s54
	v_lshl_add_u64 v[226:227], s[30:31], 0, v[132:133]
	global_load_lds_dwordx4 v[224:225], off
	v_lshl_add_u64 v[224:225], s[52:53], 0, v[130:131]
	s_add_i32 m0, s54, 0x2000
	s_nop 0
	global_load_lds_dwordx4 v[224:225], off
	v_lshl_add_u64 v[224:225], s[30:31], 0, v[136:137]
	s_mov_b32 m0, s25
	s_nop 0
	global_load_lds_dwordx4 v[224:225], off
	s_mov_b32 m0, s37
	s_nop 0
	global_load_lds_dwordx4 v[226:227], off
	s_waitcnt vmcnt(8)
	s_waitcnt lgkmcnt(0)
	s_setprio 1
	s_barrier
	v_mfma_f32_16x16x32_bf16 v[62:65], v[148:151], v[188:191], v[62:65]
	v_mfma_f32_16x16x32_bf16 v[58:61], v[164:167], v[188:191], v[58:61]
	v_mfma_f32_16x16x32_bf16 v[50:53], v[148:151], v[196:199], v[50:53]
	v_mfma_f32_16x16x32_bf16 v[42:45], v[164:167], v[196:199], v[42:45]
	v_mfma_f32_16x16x32_bf16 v[34:37], v[148:151], v[204:207], v[34:37]
	v_mfma_f32_16x16x32_bf16 v[26:29], v[164:167], v[204:207], v[26:29]
	v_mfma_f32_16x16x32_bf16 v[18:21], v[148:151], v[212:215], v[18:21]
	v_mfma_f32_16x16x32_bf16 v[10:13], v[164:167], v[212:215], v[10:13]
	v_mfma_f32_16x16x32_bf16 v[62:65], v[160:163], v[192:195], v[62:65]
	v_mfma_f32_16x16x32_bf16 v[58:61], v[168:171], v[192:195], v[58:61]
	v_mfma_f32_16x16x32_bf16 v[50:53], v[160:163], v[200:203], v[50:53]
	v_mfma_f32_16x16x32_bf16 v[42:45], v[168:171], v[200:203], v[42:45]
	v_mfma_f32_16x16x32_bf16 v[34:37], v[160:163], v[208:211], v[34:37]
	v_mfma_f32_16x16x32_bf16 v[26:29], v[168:171], v[208:211], v[26:29]
	v_mfma_f32_16x16x32_bf16 v[18:21], v[160:163], v[216:219], v[18:21]
	v_mfma_f32_16x16x32_bf16 v[10:13], v[168:171], v[216:219], v[10:13]
	v_mfma_f32_16x16x32_bf16 v[54:57], v[172:175], v[188:191], v[54:57]
	v_mfma_f32_16x16x32_bf16 v[46:49], v[180:183], v[188:191], v[46:49]
	v_mfma_f32_16x16x32_bf16 v[38:41], v[172:175], v[196:199], v[38:41]
	v_mfma_f32_16x16x32_bf16 v[30:33], v[180:183], v[196:199], v[30:33]
	v_mfma_f32_16x16x32_bf16 v[22:25], v[172:175], v[204:207], v[22:25]
	v_mfma_f32_16x16x32_bf16 v[14:17], v[180:183], v[204:207], v[14:17]
	v_mfma_f32_16x16x32_bf16 v[6:9], v[172:175], v[212:215], v[6:9]
	v_mfma_f32_16x16x32_bf16 v[2:5], v[180:183], v[212:215], v[2:5]
	v_mfma_f32_16x16x32_bf16 v[54:57], v[176:179], v[192:195], v[54:57]
	v_mfma_f32_16x16x32_bf16 v[46:49], v[184:187], v[192:195], v[46:49]
	v_mfma_f32_16x16x32_bf16 v[38:41], v[176:179], v[200:203], v[38:41]
	v_mfma_f32_16x16x32_bf16 v[30:33], v[184:187], v[200:203], v[30:33]
	v_mfma_f32_16x16x32_bf16 v[22:25], v[176:179], v[208:211], v[22:25]
	v_mfma_f32_16x16x32_bf16 v[14:17], v[184:187], v[208:211], v[14:17]
	v_mfma_f32_16x16x32_bf16 v[6:9], v[176:179], v[216:219], v[6:9]
	v_mfma_f32_16x16x32_bf16 v[2:5], v[184:187], v[216:219], v[2:5]
	s_barrier
	s_setprio 0
	s_add_i32 s52, 0, 0x18000
	v_add_u32_e32 v146, s52, v154
	s_add_i32 s53, 0, 0x1c000
	ds_read_b128 v[148:151], v146
	ds_read_b128 v[160:163], v146 offset:1024
	ds_read_b128 v[164:167], v146 offset:2048
	ds_read_b128 v[168:171], v146 offset:3072
	v_add_u32_e32 v146, s53, v154
	ds_read_b128 v[172:175], v146
	ds_read_b128 v[176:179], v146 offset:1024
	ds_read_b128 v[180:183], v146 offset:2048
	ds_read_b128 v[184:187], v146 offset:3072
	s_add_u32 s30, s30, 0x100000
	s_addc_u32 s31, s31, 0
	s_mov_b32 m0, s38
	v_lshl_add_u64 v[228:229], s[30:31], 0, v[136:137]
	ds_read_b128 v[188:191], v158 offset:32768
	ds_read_b128 v[192:195], v158 offset:33792
	ds_read_b128 v[196:199], v158 offset:34816
	ds_read_b128 v[200:203], v158 offset:35840
	ds_read_b128 v[204:207], v158 offset:36864
	ds_read_b128 v[208:211], v158 offset:37888
	ds_read_b128 v[212:215], v158 offset:38912
	ds_read_b128 v[216:219], v158 offset:39936
	global_load_lds_dwordx4 v[228:229], off
	v_lshl_add_u64 v[228:229], s[30:31], 0, v[132:133]
	s_mov_b32 m0, s39
	s_nop 0
	global_load_lds_dwordx4 v[228:229], off
	s_waitcnt vmcnt(8)
	s_waitcnt lgkmcnt(0)
	s_setprio 1
	s_barrier
	v_mfma_f32_16x16x32_bf16 v[126:129], v[148:151], v[188:191], v[126:129]
	v_mfma_f32_16x16x32_bf16 v[122:125], v[164:167], v[188:191], v[122:125]
	v_mfma_f32_16x16x32_bf16 v[114:117], v[148:151], v[196:199], v[114:117]
	v_mfma_f32_16x16x32_bf16 v[106:109], v[164:167], v[196:199], v[106:109]
	v_mfma_f32_16x16x32_bf16 v[98:101], v[148:151], v[204:207], v[98:101]
	v_mfma_f32_16x16x32_bf16 v[90:93], v[164:167], v[204:207], v[90:93]
	v_mfma_f32_16x16x32_bf16 v[82:85], v[148:151], v[212:215], v[82:85]
	v_mfma_f32_16x16x32_bf16 v[74:77], v[164:167], v[212:215], v[74:77]
	v_mfma_f32_16x16x32_bf16 v[126:129], v[160:163], v[192:195], v[126:129]
	v_mfma_f32_16x16x32_bf16 v[122:125], v[168:171], v[192:195], v[122:125]
	v_mfma_f32_16x16x32_bf16 v[114:117], v[160:163], v[200:203], v[114:117]
	v_mfma_f32_16x16x32_bf16 v[106:109], v[168:171], v[200:203], v[106:109]
	v_mfma_f32_16x16x32_bf16 v[98:101], v[160:163], v[208:211], v[98:101]
	v_mfma_f32_16x16x32_bf16 v[90:93], v[168:171], v[208:211], v[90:93]
	v_mfma_f32_16x16x32_bf16 v[82:85], v[160:163], v[216:219], v[82:85]
	v_mfma_f32_16x16x32_bf16 v[74:77], v[168:171], v[216:219], v[74:77]
	v_mfma_f32_16x16x32_bf16 v[118:121], v[172:175], v[188:191], v[118:121]
	v_mfma_f32_16x16x32_bf16 v[110:113], v[180:183], v[188:191], v[110:113]
	v_mfma_f32_16x16x32_bf16 v[102:105], v[172:175], v[196:199], v[102:105]
	v_mfma_f32_16x16x32_bf16 v[94:97], v[180:183], v[196:199], v[94:97]
	v_mfma_f32_16x16x32_bf16 v[86:89], v[172:175], v[204:207], v[86:89]
	v_mfma_f32_16x16x32_bf16 v[78:81], v[180:183], v[204:207], v[78:81]
	v_mfma_f32_16x16x32_bf16 v[70:73], v[172:175], v[212:215], v[70:73]
	v_mfma_f32_16x16x32_bf16 v[66:69], v[180:183], v[212:215], v[66:69]
	v_mfma_f32_16x16x32_bf16 v[118:121], v[176:179], v[192:195], v[118:121]
	v_mfma_f32_16x16x32_bf16 v[110:113], v[184:187], v[192:195], v[110:113]
	v_mfma_f32_16x16x32_bf16 v[102:105], v[176:179], v[200:203], v[102:105]
	v_mfma_f32_16x16x32_bf16 v[94:97], v[184:187], v[200:203], v[94:97]
	v_mfma_f32_16x16x32_bf16 v[86:89], v[176:179], v[208:211], v[86:89]
	v_mfma_f32_16x16x32_bf16 v[78:81], v[184:187], v[208:211], v[78:81]
	v_mfma_f32_16x16x32_bf16 v[70:73], v[176:179], v[216:219], v[70:73]
	v_mfma_f32_16x16x32_bf16 v[66:69], v[184:187], v[216:219], v[66:69]
	s_barrier
	s_setprio 0
	s_add_i32 s30, s52, s34
	v_lshl_add_u64 v[220:221], v[220:221], 0, s[12:13]
	s_mov_b32 m0, s30
	ds_read_b128 v[188:191], v158 offset:49152
	ds_read_b128 v[192:195], v158 offset:50176
	ds_read_b128 v[196:199], v158 offset:51200
	ds_read_b128 v[200:203], v158 offset:52224
	ds_read_b128 v[204:207], v158 offset:53248
	ds_read_b128 v[208:211], v158 offset:54272
	ds_read_b128 v[212:215], v158 offset:55296
	ds_read_b128 v[216:219], v158 offset:56320
	global_load_lds_dwordx4 v[220:221], off
	s_add_i32 m0, s30, 0x2000
	s_add_u32 s28, s28, 0x100080
	v_lshl_add_u64 v[220:221], v[222:223], 0, s[12:13]
	s_addc_u32 s29, s29, 0
	s_add_i32 s30, s53, s34
	global_load_lds_dwordx4 v[220:221], off
	v_lshl_add_u64 v[220:221], s[28:29], 0, v[134:135]
	s_mov_b32 m0, s30
	s_nop 0
	global_load_lds_dwordx4 v[220:221], off
	v_lshl_add_u64 v[220:221], s[28:29], 0, v[130:131]
	s_add_i32 m0, s30, 0x2000
	s_nop 0
	global_load_lds_dwordx4 v[220:221], off
	v_lshl_add_u64 v[220:221], v[224:225], 0, s[12:13]
	s_mov_b32 m0, s41
	s_nop 0
	global_load_lds_dwordx4 v[220:221], off
	v_lshl_add_u64 v[220:221], v[226:227], 0, s[12:13]
	s_mov_b32 m0, s42
	s_nop 0
	global_load_lds_dwordx4 v[220:221], off
	s_waitcnt vmcnt(8)
	s_waitcnt lgkmcnt(0)
	s_setprio 1
	s_barrier
	v_mfma_f32_16x16x32_bf16 v[62:65], v[148:151], v[188:191], v[62:65]
	v_mfma_f32_16x16x32_bf16 v[58:61], v[164:167], v[188:191], v[58:61]
	v_mfma_f32_16x16x32_bf16 v[50:53], v[148:151], v[196:199], v[50:53]
	v_mfma_f32_16x16x32_bf16 v[42:45], v[164:167], v[196:199], v[42:45]
	v_mfma_f32_16x16x32_bf16 v[34:37], v[148:151], v[204:207], v[34:37]
	v_mfma_f32_16x16x32_bf16 v[26:29], v[164:167], v[204:207], v[26:29]
	v_mfma_f32_16x16x32_bf16 v[18:21], v[148:151], v[212:215], v[18:21]
	v_mfma_f32_16x16x32_bf16 v[10:13], v[164:167], v[212:215], v[10:13]
	v_mfma_f32_16x16x32_bf16 v[62:65], v[160:163], v[192:195], v[62:65]
	v_mfma_f32_16x16x32_bf16 v[58:61], v[168:171], v[192:195], v[58:61]
	v_mfma_f32_16x16x32_bf16 v[50:53], v[160:163], v[200:203], v[50:53]
	v_mfma_f32_16x16x32_bf16 v[42:45], v[168:171], v[200:203], v[42:45]
	v_mfma_f32_16x16x32_bf16 v[34:37], v[160:163], v[208:211], v[34:37]
	v_mfma_f32_16x16x32_bf16 v[26:29], v[168:171], v[208:211], v[26:29]
	v_mfma_f32_16x16x32_bf16 v[18:21], v[160:163], v[216:219], v[18:21]
	v_mfma_f32_16x16x32_bf16 v[10:13], v[168:171], v[216:219], v[10:13]
	v_mfma_f32_16x16x32_bf16 v[54:57], v[172:175], v[188:191], v[54:57]
	v_mfma_f32_16x16x32_bf16 v[46:49], v[180:183], v[188:191], v[46:49]
	v_mfma_f32_16x16x32_bf16 v[38:41], v[172:175], v[196:199], v[38:41]
	v_mfma_f32_16x16x32_bf16 v[30:33], v[180:183], v[196:199], v[30:33]
	v_mfma_f32_16x16x32_bf16 v[22:25], v[172:175], v[204:207], v[22:25]
	v_mfma_f32_16x16x32_bf16 v[14:17], v[180:183], v[204:207], v[14:17]
	v_mfma_f32_16x16x32_bf16 v[6:9], v[172:175], v[212:215], v[6:9]
	v_mfma_f32_16x16x32_bf16 v[2:5], v[180:183], v[212:215], v[2:5]
	v_mfma_f32_16x16x32_bf16 v[54:57], v[176:179], v[192:195], v[54:57]
	v_mfma_f32_16x16x32_bf16 v[46:49], v[184:187], v[192:195], v[46:49]
	v_mfma_f32_16x16x32_bf16 v[38:41], v[176:179], v[200:203], v[38:41]
	v_mfma_f32_16x16x32_bf16 v[30:33], v[184:187], v[200:203], v[30:33]
	v_mfma_f32_16x16x32_bf16 v[22:25], v[176:179], v[208:211], v[22:25]
	v_mfma_f32_16x16x32_bf16 v[14:17], v[184:187], v[208:211], v[14:17]
	v_mfma_f32_16x16x32_bf16 v[6:9], v[176:179], v[216:219], v[6:9]
	v_mfma_f32_16x16x32_bf16 v[2:5], v[184:187], v[216:219], v[2:5]
	s_barrier
	s_setprio 0
	s_add_i32 s51, s51, 2
	s_add_u32 s26, s26, 0x100
	s_addc_u32 s27, s27, 0
	s_add_u32 s49, s49, 0x100
	s_addc_u32 s50, s50, 0
	s_cmp_gt_u32 s51, 61
	s_cbranch_scc0 .LBB0_1087
	s_and_b64 vcc, exec, s[14:15]
	s_cbranch_vccz .LBB0_1090
	s_barrier

.LBB0_1241:
	ds_read_b128 v[144:147], v162
	ds_read_b128 v[166:169], v162 offset:1024
	ds_read_b128 v[170:173], v162 offset:2048
	ds_read_b128 v[174:177], v162 offset:3072
	ds_read_b128 v[178:181], v163
	ds_read_b128 v[182:185], v163 offset:1024
	ds_read_b128 v[186:189], v163 offset:2048
	ds_read_b128 v[190:193], v163 offset:3072
	s_add_u32 s40, s38, 0xfff00080
	s_addc_u32 s41, s39, -1
	s_cmp_eq_u32 s63, 60
	s_cselect_b32 s43, s2, s41
	s_cselect_b32 s42, s29, s40
	s_cselect_b32 s41, s27, s62
	s_cselect_b32 s40, s60, s61
	v_lshl_add_u64 v[148:149], s[38:39], 0, v[138:139]
	s_add_i32 m0, s37, 0xc000
	ds_read_b128 v[194:197], v164
	ds_read_b128 v[198:201], v164 offset:1024
	ds_read_b128 v[202:205], v164 offset:2048
	ds_read_b128 v[206:209], v164 offset:3072
	ds_read_b128 v[210:213], v164 offset:4096
	ds_read_b128 v[214:217], v164 offset:5120
	ds_read_b128 v[218:221], v164 offset:6144
	ds_read_b128 v[222:225], v164 offset:7168
	global_load_lds_dwordx4 v[148:149], off
	v_lshl_add_u64 v[148:149], s[38:39], 0, v[140:141]
	s_add_i32 m0, s37, 0xe000
	s_nop 0
	global_load_lds_dwordx4 v[148:149], off
	s_waitcnt vmcnt(8)
	s_waitcnt lgkmcnt(0)
	s_setprio 1
	s_barrier
	v_mfma_f32_16x16x32_bf16 v[126:129], v[144:147], v[194:197], v[126:129]
	v_mfma_f32_16x16x32_bf16 v[122:125], v[170:173], v[194:197], v[122:125]
	v_mfma_f32_16x16x32_bf16 v[110:113], v[144:147], v[202:205], v[110:113]
	v_mfma_f32_16x16x32_bf16 v[106:109], v[170:173], v[202:205], v[106:109]
	v_mfma_f32_16x16x32_bf16 v[94:97], v[144:147], v[210:213], v[94:97]
	v_mfma_f32_16x16x32_bf16 v[90:93], v[170:173], v[210:213], v[90:93]
	v_mfma_f32_16x16x32_bf16 v[78:81], v[144:147], v[218:221], v[78:81]
	v_mfma_f32_16x16x32_bf16 v[74:77], v[170:173], v[218:221], v[74:77]
	v_mfma_f32_16x16x32_bf16 v[126:129], v[166:169], v[198:201], v[126:129]
	v_mfma_f32_16x16x32_bf16 v[122:125], v[174:177], v[198:201], v[122:125]
	v_mfma_f32_16x16x32_bf16 v[110:113], v[166:169], v[206:209], v[110:113]
	v_mfma_f32_16x16x32_bf16 v[106:109], v[174:177], v[206:209], v[106:109]
	v_mfma_f32_16x16x32_bf16 v[94:97], v[166:169], v[214:217], v[94:97]
	v_mfma_f32_16x16x32_bf16 v[90:93], v[174:177], v[214:217], v[90:93]
	v_mfma_f32_16x16x32_bf16 v[78:81], v[166:169], v[222:225], v[78:81]
	v_mfma_f32_16x16x32_bf16 v[74:77], v[174:177], v[222:225], v[74:77]
	v_mfma_f32_16x16x32_bf16 v[118:121], v[178:181], v[194:197], v[118:121]
	v_mfma_f32_16x16x32_bf16 v[114:117], v[186:189], v[194:197], v[114:117]
	v_mfma_f32_16x16x32_bf16 v[102:105], v[178:181], v[202:205], v[102:105]
	v_mfma_f32_16x16x32_bf16 v[98:101], v[186:189], v[202:205], v[98:101]
	v_mfma_f32_16x16x32_bf16 v[86:89], v[178:181], v[210:213], v[86:89]
	v_mfma_f32_16x16x32_bf16 v[82:85], v[186:189], v[210:213], v[82:85]
	v_mfma_f32_16x16x32_bf16 v[70:73], v[178:181], v[218:221], v[70:73]
	v_mfma_f32_16x16x32_bf16 v[66:69], v[186:189], v[218:221], v[66:69]
	v_mfma_f32_16x16x32_bf16 v[118:121], v[182:185], v[198:201], v[118:121]
	v_mfma_f32_16x16x32_bf16 v[114:117], v[190:193], v[198:201], v[114:117]
	v_mfma_f32_16x16x32_bf16 v[102:105], v[182:185], v[206:209], v[102:105]
	v_mfma_f32_16x16x32_bf16 v[98:101], v[190:193], v[206:209], v[98:101]
	v_mfma_f32_16x16x32_bf16 v[86:89], v[182:185], v[214:217], v[86:89]
	v_mfma_f32_16x16x32_bf16 v[82:85], v[190:193], v[214:217], v[82:85]
	v_mfma_f32_16x16x32_bf16 v[70:73], v[182:185], v[222:225], v[70:73]
	v_mfma_f32_16x16x32_bf16 v[66:69], v[190:193], v[222:225], v[66:69]
	s_barrier
	s_setprio 0
	s_add_i32 s64, s56, s45
	v_lshl_add_u64 v[148:149], s[40:41], 0, v[132:133]
	s_mov_b32 m0, s64
	ds_read_b128 v[194:197], v164 offset:16384
	ds_read_b128 v[198:201], v164 offset:17408
	ds_read_b128 v[202:205], v164 offset:18432
	ds_read_b128 v[206:209], v164 offset:19456
	ds_read_b128 v[210:213], v164 offset:20480
	ds_read_b128 v[214:217], v164 offset:21504
	ds_read_b128 v[218:221], v164 offset:22528
	ds_read_b128 v[222:225], v164 offset:23552
	global_load_lds_dwordx4 v[148:149], off
	s_add_i32 m0, s64, 0x2000
	s_add_u32 s64, s40, 0x100000
	v_lshl_add_u64 v[226:227], s[40:41], 0, v[136:137]
	s_addc_u32 s65, s41, 0
	s_add_i32 s66, s57, s45
	global_load_lds_dwordx4 v[226:227], off
	v_lshl_add_u64 v[228:229], s[64:65], 0, v[132:133]
	s_mov_b32 m0, s66
	v_lshl_add_u64 v[230:231], s[42:43], 0, v[134:135]
	global_load_lds_dwordx4 v[228:229], off
	v_lshl_add_u64 v[228:229], s[64:65], 0, v[136:137]
	s_add_i32 m0, s66, 0x2000
	s_nop 0
	global_load_lds_dwordx4 v[228:229], off
	v_lshl_add_u64 v[228:229], s[42:43], 0, v[130:131]
	s_mov_b32 m0, s37
	s_nop 0
	global_load_lds_dwordx4 v[228:229], off
	s_mov_b32 m0, s46
	s_nop 0
	global_load_lds_dwordx4 v[230:231], off
	s_waitcnt vmcnt(8)
	s_waitcnt lgkmcnt(0)
	s_setprio 1
	s_barrier
	v_mfma_f32_16x16x32_bf16 v[62:65], v[144:147], v[194:197], v[62:65]
	v_mfma_f32_16x16x32_bf16 v[58:61], v[170:173], v[194:197], v[58:61]
	v_mfma_f32_16x16x32_bf16 v[46:49], v[144:147], v[202:205], v[46:49]
	v_mfma_f32_16x16x32_bf16 v[42:45], v[170:173], v[202:205], v[42:45]
	v_mfma_f32_16x16x32_bf16 v[30:33], v[144:147], v[210:213], v[30:33]
	v_mfma_f32_16x16x32_bf16 v[26:29], v[170:173], v[210:213], v[26:29]
	v_mfma_f32_16x16x32_bf16 v[14:17], v[144:147], v[218:221], v[14:17]
	v_mfma_f32_16x16x32_bf16 v[10:13], v[170:173], v[218:221], v[10:13]
	v_mfma_f32_16x16x32_bf16 v[62:65], v[166:169], v[198:201], v[62:65]
	v_mfma_f32_16x16x32_bf16 v[58:61], v[174:177], v[198:201], v[58:61]
	v_mfma_f32_16x16x32_bf16 v[46:49], v[166:169], v[206:209], v[46:49]
	v_mfma_f32_16x16x32_bf16 v[42:45], v[174:177], v[206:209], v[42:45]
	v_mfma_f32_16x16x32_bf16 v[30:33], v[166:169], v[214:217], v[30:33]
	v_mfma_f32_16x16x32_bf16 v[26:29], v[174:177], v[214:217], v[26:29]
	v_mfma_f32_16x16x32_bf16 v[14:17], v[166:169], v[222:225], v[14:17]
	v_mfma_f32_16x16x32_bf16 v[10:13], v[174:177], v[222:225], v[10:13]
	v_mfma_f32_16x16x32_bf16 v[54:57], v[178:181], v[194:197], v[54:57]
	v_mfma_f32_16x16x32_bf16 v[50:53], v[186:189], v[194:197], v[50:53]
	v_mfma_f32_16x16x32_bf16 v[38:41], v[178:181], v[202:205], v[38:41]
	v_mfma_f32_16x16x32_bf16 v[34:37], v[186:189], v[202:205], v[34:37]
	v_mfma_f32_16x16x32_bf16 v[22:25], v[178:181], v[210:213], v[22:25]
	v_mfma_f32_16x16x32_bf16 v[18:21], v[186:189], v[210:213], v[18:21]
	v_mfma_f32_16x16x32_bf16 v[6:9], v[178:181], v[218:221], v[6:9]
	v_mfma_f32_16x16x32_bf16 v[2:5], v[186:189], v[218:221], v[2:5]
	v_mfma_f32_16x16x32_bf16 v[54:57], v[182:185], v[198:201], v[54:57]
	v_mfma_f32_16x16x32_bf16 v[50:53], v[190:193], v[198:201], v[50:53]
	v_mfma_f32_16x16x32_bf16 v[38:41], v[182:185], v[206:209], v[38:41]
	v_mfma_f32_16x16x32_bf16 v[34:37], v[190:193], v[206:209], v[34:37]
	v_mfma_f32_16x16x32_bf16 v[22:25], v[182:185], v[214:217], v[22:25]
	v_mfma_f32_16x16x32_bf16 v[18:21], v[190:193], v[214:217], v[18:21]
	v_mfma_f32_16x16x32_bf16 v[6:9], v[182:185], v[222:225], v[6:9]
	v_mfma_f32_16x16x32_bf16 v[2:5], v[190:193], v[222:225], v[2:5]
	s_barrier
	s_setprio 0
	s_add_i32 s64, 0, 0x18000
	v_add_u32_e32 v142, s64, v160
	s_add_i32 s65, 0, 0x1c000
	ds_read_b128 v[144:147], v142
	ds_read_b128 v[166:169], v142 offset:1024
	ds_read_b128 v[170:173], v142 offset:2048
	ds_read_b128 v[174:177], v142 offset:3072
	v_add_u32_e32 v142, s65, v160
	ds_read_b128 v[178:181], v142
	ds_read_b128 v[182:185], v142 offset:1024
	ds_read_b128 v[186:189], v142 offset:2048
	ds_read_b128 v[190:193], v142 offset:3072
	s_add_u32 s42, s42, 0x100000
	s_addc_u32 s43, s43, 0
	s_mov_b32 m0, s47
	v_lshl_add_u64 v[232:233], s[42:43], 0, v[130:131]
	ds_read_b128 v[194:197], v164 offset:32768
	ds_read_b128 v[198:201], v164 offset:33792
	ds_read_b128 v[202:205], v164 offset:34816
	ds_read_b128 v[206:209], v164 offset:35840
	ds_read_b128 v[210:213], v164 offset:36864
	ds_read_b128 v[214:217], v164 offset:37888
	ds_read_b128 v[218:221], v164 offset:38912
	ds_read_b128 v[222:225], v164 offset:39936
	global_load_lds_dwordx4 v[232:233], off
	v_lshl_add_u64 v[232:233], s[42:43], 0, v[134:135]
	s_mov_b32 m0, s48
	s_nop 0
	global_load_lds_dwordx4 v[232:233], off
	s_waitcnt vmcnt(8)
	s_waitcnt lgkmcnt(0)
	s_setprio 1
	s_barrier
	v_mfma_f32_16x16x32_bf16 v[126:129], v[144:147], v[194:197], v[126:129]
	v_mfma_f32_16x16x32_bf16 v[122:125], v[170:173], v[194:197], v[122:125]
	v_mfma_f32_16x16x32_bf16 v[110:113], v[144:147], v[202:205], v[110:113]
	v_mfma_f32_16x16x32_bf16 v[106:109], v[170:173], v[202:205], v[106:109]
	v_mfma_f32_16x16x32_bf16 v[94:97], v[144:147], v[210:213], v[94:97]
	v_mfma_f32_16x16x32_bf16 v[90:93], v[170:173], v[210:213], v[90:93]
	v_mfma_f32_16x16x32_bf16 v[78:81], v[144:147], v[218:221], v[78:81]
	v_mfma_f32_16x16x32_bf16 v[74:77], v[170:173], v[218:221], v[74:77]
	v_mfma_f32_16x16x32_bf16 v[126:129], v[166:169], v[198:201], v[126:129]
	v_mfma_f32_16x16x32_bf16 v[122:125], v[174:177], v[198:201], v[122:125]
	v_mfma_f32_16x16x32_bf16 v[110:113], v[166:169], v[206:209], v[110:113]
	v_mfma_f32_16x16x32_bf16 v[106:109], v[174:177], v[206:209], v[106:109]
	v_mfma_f32_16x16x32_bf16 v[94:97], v[166:169], v[214:217], v[94:97]
	v_mfma_f32_16x16x32_bf16 v[90:93], v[174:177], v[214:217], v[90:93]
	v_mfma_f32_16x16x32_bf16 v[78:81], v[166:169], v[222:225], v[78:81]
	v_mfma_f32_16x16x32_bf16 v[74:77], v[174:177], v[222:225], v[74:77]
	v_mfma_f32_16x16x32_bf16 v[118:121], v[178:181], v[194:197], v[118:121]
	v_mfma_f32_16x16x32_bf16 v[114:117], v[186:189], v[194:197], v[114:117]
	v_mfma_f32_16x16x32_bf16 v[102:105], v[178:181], v[202:205], v[102:105]
	v_mfma_f32_16x16x32_bf16 v[98:101], v[186:189], v[202:205], v[98:101]
	v_mfma_f32_16x16x32_bf16 v[86:89], v[178:181], v[210:213], v[86:89]
	v_mfma_f32_16x16x32_bf16 v[82:85], v[186:189], v[210:213], v[82:85]
	v_mfma_f32_16x16x32_bf16 v[70:73], v[178:181], v[218:221], v[70:73]
	v_mfma_f32_16x16x32_bf16 v[66:69], v[186:189], v[218:221], v[66:69]
	v_mfma_f32_16x16x32_bf16 v[118:121], v[182:185], v[198:201], v[118:121]
	v_mfma_f32_16x16x32_bf16 v[114:117], v[190:193], v[198:201], v[114:117]
	v_mfma_f32_16x16x32_bf16 v[102:105], v[182:185], v[206:209], v[102:105]
	v_mfma_f32_16x16x32_bf16 v[98:101], v[190:193], v[206:209], v[98:101]
	v_mfma_f32_16x16x32_bf16 v[86:89], v[182:185], v[214:217], v[86:89]
	v_mfma_f32_16x16x32_bf16 v[82:85], v[190:193], v[214:217], v[82:85]
	v_mfma_f32_16x16x32_bf16 v[70:73], v[182:185], v[222:225], v[70:73]
	v_mfma_f32_16x16x32_bf16 v[66:69], v[190:193], v[222:225], v[66:69]
	s_barrier
	s_setprio 0
	s_add_i32 s42, s64, s45
	v_lshl_add_u64 v[148:149], v[148:149], 0, s[12:13]
	s_mov_b32 m0, s42
	ds_read_b128 v[194:197], v164 offset:49152
	ds_read_b128 v[198:201], v164 offset:50176
	ds_read_b128 v[202:205], v164 offset:51200
	ds_read_b128 v[206:209], v164 offset:52224
	ds_read_b128 v[210:213], v164 offset:53248
	ds_read_b128 v[214:217], v164 offset:54272
	ds_read_b128 v[218:221], v164 offset:55296
	ds_read_b128 v[222:225], v164 offset:56320
	global_load_lds_dwordx4 v[148:149], off
	s_add_i32 m0, s42, 0x2000
	s_add_u32 s40, s40, 0x100080
	v_lshl_add_u64 v[148:149], v[226:227], 0, s[12:13]
	s_addc_u32 s41, s41, 0
	s_add_i32 s42, s65, s45
	global_load_lds_dwordx4 v[148:149], off
	v_lshl_add_u64 v[148:149], s[40:41], 0, v[132:133]
	s_mov_b32 m0, s42
	s_nop 0
	global_load_lds_dwordx4 v[148:149], off
	v_lshl_add_u64 v[148:149], s[40:41], 0, v[136:137]
	s_add_i32 m0, s42, 0x2000
	s_nop 0
	global_load_lds_dwordx4 v[148:149], off
	v_lshl_add_u64 v[148:149], v[228:229], 0, s[12:13]
	s_mov_b32 m0, s53
	s_nop 0
	global_load_lds_dwordx4 v[148:149], off
	v_lshl_add_u64 v[148:149], v[230:231], 0, s[12:13]
	s_mov_b32 m0, s54
	s_nop 0
	global_load_lds_dwordx4 v[148:149], off
	s_waitcnt vmcnt(8)
	s_waitcnt lgkmcnt(0)
	s_setprio 1
	s_barrier
	v_mfma_f32_16x16x32_bf16 v[62:65], v[144:147], v[194:197], v[62:65]
	v_mfma_f32_16x16x32_bf16 v[58:61], v[170:173], v[194:197], v[58:61]
	v_mfma_f32_16x16x32_bf16 v[46:49], v[144:147], v[202:205], v[46:49]
	v_mfma_f32_16x16x32_bf16 v[42:45], v[170:173], v[202:205], v[42:45]
	v_mfma_f32_16x16x32_bf16 v[30:33], v[144:147], v[210:213], v[30:33]
	v_mfma_f32_16x16x32_bf16 v[26:29], v[170:173], v[210:213], v[26:29]
	v_mfma_f32_16x16x32_bf16 v[14:17], v[144:147], v[218:221], v[14:17]
	v_mfma_f32_16x16x32_bf16 v[10:13], v[170:173], v[218:221], v[10:13]
	v_mfma_f32_16x16x32_bf16 v[62:65], v[166:169], v[198:201], v[62:65]
	v_mfma_f32_16x16x32_bf16 v[58:61], v[174:177], v[198:201], v[58:61]
	v_mfma_f32_16x16x32_bf16 v[46:49], v[166:169], v[206:209], v[46:49]
	v_mfma_f32_16x16x32_bf16 v[42:45], v[174:177], v[206:209], v[42:45]
	v_mfma_f32_16x16x32_bf16 v[30:33], v[166:169], v[214:217], v[30:33]
	v_mfma_f32_16x16x32_bf16 v[26:29], v[174:177], v[214:217], v[26:29]
	v_mfma_f32_16x16x32_bf16 v[14:17], v[166:169], v[222:225], v[14:17]
	v_mfma_f32_16x16x32_bf16 v[10:13], v[174:177], v[222:225], v[10:13]
	v_mfma_f32_16x16x32_bf16 v[54:57], v[178:181], v[194:197], v[54:57]
	v_mfma_f32_16x16x32_bf16 v[50:53], v[186:189], v[194:197], v[50:53]
	v_mfma_f32_16x16x32_bf16 v[38:41], v[178:181], v[202:205], v[38:41]
	v_mfma_f32_16x16x32_bf16 v[34:37], v[186:189], v[202:205], v[34:37]
	v_mfma_f32_16x16x32_bf16 v[22:25], v[178:181], v[210:213], v[22:25]
	v_mfma_f32_16x16x32_bf16 v[18:21], v[186:189], v[210:213], v[18:21]
	v_mfma_f32_16x16x32_bf16 v[6:9], v[178:181], v[218:221], v[6:9]
	v_mfma_f32_16x16x32_bf16 v[2:5], v[186:189], v[218:221], v[2:5]
	v_mfma_f32_16x16x32_bf16 v[54:57], v[182:185], v[198:201], v[54:57]
	v_mfma_f32_16x16x32_bf16 v[50:53], v[190:193], v[198:201], v[50:53]
	v_mfma_f32_16x16x32_bf16 v[38:41], v[182:185], v[206:209], v[38:41]
	v_mfma_f32_16x16x32_bf16 v[34:37], v[190:193], v[206:209], v[34:37]
	v_mfma_f32_16x16x32_bf16 v[22:25], v[182:185], v[214:217], v[22:25]
	v_mfma_f32_16x16x32_bf16 v[18:21], v[190:193], v[214:217], v[18:21]
	v_mfma_f32_16x16x32_bf16 v[6:9], v[182:185], v[222:225], v[6:9]
	v_mfma_f32_16x16x32_bf16 v[2:5], v[190:193], v[222:225], v[2:5]
	s_barrier
	s_setprio 0
	s_add_i32 s63, s63, 2
	s_add_u32 s38, s38, 0x100
	s_addc_u32 s39, s39, 0
	s_add_u32 s61, s61, 0x100
	s_addc_u32 s62, s62, 0
	s_cmp_gt_u32 s63, 61
	s_cbranch_scc0 .LBB0_1241
	s_and_b64 vcc, exec, s[14:15]
	s_cbranch_vccz .LBB0_1244
	s_barrier

.LBB0_1294:
	ds_read_b128 v[144:147], v151
	ds_read_b128 v[160:163], v151 offset:1024
	ds_read_b128 v[164:167], v151 offset:2048
	ds_read_b128 v[168:171], v151 offset:3072
	ds_read_b128 v[172:175], v152
	ds_read_b128 v[176:179], v152 offset:1024
	ds_read_b128 v[180:183], v152 offset:2048
	ds_read_b128 v[184:187], v152 offset:3072
	s_add_u32 s40, s38, 0xfff00080
	s_addc_u32 s41, s39, -1
	s_cmp_eq_u32 s64, 60
	s_cselect_b32 s43, s2, s41
	s_cselect_b32 s42, s29, s40
	s_cselect_b32 s41, s27, s63
	s_cselect_b32 s40, s61, s62
	v_lshl_add_u64 v[148:149], s[38:39], 0, v[138:139]
	s_add_i32 m0, s37, 0xc000
	ds_read_b128 v[188:191], v153
	ds_read_b128 v[192:195], v153 offset:1024
	ds_read_b128 v[196:199], v153 offset:2048
	ds_read_b128 v[200:203], v153 offset:3072
	ds_read_b128 v[204:207], v153 offset:4096
	ds_read_b128 v[208:211], v153 offset:5120
	ds_read_b128 v[212:215], v153 offset:6144
	ds_read_b128 v[216:219], v153 offset:7168
	global_load_lds_dwordx4 v[148:149], off
	v_lshl_add_u64 v[148:149], s[38:39], 0, v[140:141]
	s_add_i32 m0, s37, 0xe000
	s_nop 0
	global_load_lds_dwordx4 v[148:149], off
	s_waitcnt vmcnt(8)
	s_waitcnt lgkmcnt(0)
	s_setprio 1
	s_barrier
	v_mfma_f32_16x16x32_bf16 v[126:129], v[144:147], v[188:191], v[126:129]
	v_mfma_f32_16x16x32_bf16 v[122:125], v[164:167], v[188:191], v[122:125]
	v_mfma_f32_16x16x32_bf16 v[110:113], v[144:147], v[196:199], v[110:113]
	v_mfma_f32_16x16x32_bf16 v[106:109], v[164:167], v[196:199], v[106:109]
	v_mfma_f32_16x16x32_bf16 v[94:97], v[144:147], v[204:207], v[94:97]
	v_mfma_f32_16x16x32_bf16 v[90:93], v[164:167], v[204:207], v[90:93]
	v_mfma_f32_16x16x32_bf16 v[78:81], v[144:147], v[212:215], v[78:81]
	v_mfma_f32_16x16x32_bf16 v[74:77], v[164:167], v[212:215], v[74:77]
	v_mfma_f32_16x16x32_bf16 v[126:129], v[160:163], v[192:195], v[126:129]
	v_mfma_f32_16x16x32_bf16 v[122:125], v[168:171], v[192:195], v[122:125]
	v_mfma_f32_16x16x32_bf16 v[110:113], v[160:163], v[200:203], v[110:113]
	v_mfma_f32_16x16x32_bf16 v[106:109], v[168:171], v[200:203], v[106:109]
	v_mfma_f32_16x16x32_bf16 v[94:97], v[160:163], v[208:211], v[94:97]
	v_mfma_f32_16x16x32_bf16 v[90:93], v[168:171], v[208:211], v[90:93]
	v_mfma_f32_16x16x32_bf16 v[78:81], v[160:163], v[216:219], v[78:81]
	v_mfma_f32_16x16x32_bf16 v[74:77], v[168:171], v[216:219], v[74:77]
	v_mfma_f32_16x16x32_bf16 v[118:121], v[172:175], v[188:191], v[118:121]
	v_mfma_f32_16x16x32_bf16 v[114:117], v[180:183], v[188:191], v[114:117]
	v_mfma_f32_16x16x32_bf16 v[102:105], v[172:175], v[196:199], v[102:105]
	v_mfma_f32_16x16x32_bf16 v[98:101], v[180:183], v[196:199], v[98:101]
	v_mfma_f32_16x16x32_bf16 v[86:89], v[172:175], v[204:207], v[86:89]
	v_mfma_f32_16x16x32_bf16 v[82:85], v[180:183], v[204:207], v[82:85]
	v_mfma_f32_16x16x32_bf16 v[70:73], v[172:175], v[212:215], v[70:73]
	v_mfma_f32_16x16x32_bf16 v[66:69], v[180:183], v[212:215], v[66:69]
	v_mfma_f32_16x16x32_bf16 v[118:121], v[176:179], v[192:195], v[118:121]
	v_mfma_f32_16x16x32_bf16 v[114:117], v[184:187], v[192:195], v[114:117]
	v_mfma_f32_16x16x32_bf16 v[102:105], v[176:179], v[200:203], v[102:105]
	v_mfma_f32_16x16x32_bf16 v[98:101], v[184:187], v[200:203], v[98:101]
	v_mfma_f32_16x16x32_bf16 v[86:89], v[176:179], v[208:211], v[86:89]
	v_mfma_f32_16x16x32_bf16 v[82:85], v[184:187], v[208:211], v[82:85]
	v_mfma_f32_16x16x32_bf16 v[70:73], v[176:179], v[216:219], v[70:73]
	v_mfma_f32_16x16x32_bf16 v[66:69], v[184:187], v[216:219], v[66:69]
	s_barrier
	s_setprio 0
	s_add_i32 s65, s57, s46
	v_lshl_add_u64 v[148:149], s[40:41], 0, v[132:133]
	s_mov_b32 m0, s65
	ds_read_b128 v[188:191], v153 offset:16384
	ds_read_b128 v[192:195], v153 offset:17408
	ds_read_b128 v[196:199], v153 offset:18432
	ds_read_b128 v[200:203], v153 offset:19456
	ds_read_b128 v[204:207], v153 offset:20480
	ds_read_b128 v[208:211], v153 offset:21504
	ds_read_b128 v[212:215], v153 offset:22528
	ds_read_b128 v[216:219], v153 offset:23552
	global_load_lds_dwordx4 v[148:149], off
	s_add_i32 m0, s65, 0x2000
	s_add_u32 s66, s40, 0x100000
	v_lshl_add_u64 v[220:221], s[40:41], 0, v[136:137]
	s_addc_u32 s67, s41, 0
	s_add_i32 s65, s58, s46
	global_load_lds_dwordx4 v[220:221], off
	v_lshl_add_u64 v[222:223], s[66:67], 0, v[132:133]
	s_mov_b32 m0, s65
	v_lshl_add_u64 v[224:225], s[42:43], 0, v[134:135]
	global_load_lds_dwordx4 v[222:223], off
	v_lshl_add_u64 v[222:223], s[66:67], 0, v[136:137]
	s_add_i32 m0, s65, 0x2000
	s_nop 0
	global_load_lds_dwordx4 v[222:223], off
	v_lshl_add_u64 v[222:223], s[42:43], 0, v[130:131]
	s_mov_b32 m0, s37
	s_nop 0
	global_load_lds_dwordx4 v[222:223], off
	s_mov_b32 m0, s47
	s_nop 0
	global_load_lds_dwordx4 v[224:225], off
	s_waitcnt vmcnt(8)
	s_waitcnt lgkmcnt(0)
	s_setprio 1
	s_barrier
	v_mfma_f32_16x16x32_bf16 v[62:65], v[144:147], v[188:191], v[62:65]
	v_mfma_f32_16x16x32_bf16 v[58:61], v[164:167], v[188:191], v[58:61]
	v_mfma_f32_16x16x32_bf16 v[46:49], v[144:147], v[196:199], v[46:49]
	v_mfma_f32_16x16x32_bf16 v[42:45], v[164:167], v[196:199], v[42:45]
	v_mfma_f32_16x16x32_bf16 v[30:33], v[144:147], v[204:207], v[30:33]
	v_mfma_f32_16x16x32_bf16 v[26:29], v[164:167], v[204:207], v[26:29]
	v_mfma_f32_16x16x32_bf16 v[14:17], v[144:147], v[212:215], v[14:17]
	v_mfma_f32_16x16x32_bf16 v[10:13], v[164:167], v[212:215], v[10:13]
	v_mfma_f32_16x16x32_bf16 v[62:65], v[160:163], v[192:195], v[62:65]
	v_mfma_f32_16x16x32_bf16 v[58:61], v[168:171], v[192:195], v[58:61]
	v_mfma_f32_16x16x32_bf16 v[46:49], v[160:163], v[200:203], v[46:49]
	v_mfma_f32_16x16x32_bf16 v[42:45], v[168:171], v[200:203], v[42:45]
	v_mfma_f32_16x16x32_bf16 v[30:33], v[160:163], v[208:211], v[30:33]
	v_mfma_f32_16x16x32_bf16 v[26:29], v[168:171], v[208:211], v[26:29]
	v_mfma_f32_16x16x32_bf16 v[14:17], v[160:163], v[216:219], v[14:17]
	v_mfma_f32_16x16x32_bf16 v[10:13], v[168:171], v[216:219], v[10:13]
	v_mfma_f32_16x16x32_bf16 v[54:57], v[172:175], v[188:191], v[54:57]
	v_mfma_f32_16x16x32_bf16 v[50:53], v[180:183], v[188:191], v[50:53]
	v_mfma_f32_16x16x32_bf16 v[38:41], v[172:175], v[196:199], v[38:41]
	v_mfma_f32_16x16x32_bf16 v[34:37], v[180:183], v[196:199], v[34:37]
	v_mfma_f32_16x16x32_bf16 v[22:25], v[172:175], v[204:207], v[22:25]
	v_mfma_f32_16x16x32_bf16 v[18:21], v[180:183], v[204:207], v[18:21]
	v_mfma_f32_16x16x32_bf16 v[6:9], v[172:175], v[212:215], v[6:9]
	v_mfma_f32_16x16x32_bf16 v[2:5], v[180:183], v[212:215], v[2:5]
	v_mfma_f32_16x16x32_bf16 v[54:57], v[176:179], v[192:195], v[54:57]
	v_mfma_f32_16x16x32_bf16 v[50:53], v[184:187], v[192:195], v[50:53]
	v_mfma_f32_16x16x32_bf16 v[38:41], v[176:179], v[200:203], v[38:41]
	v_mfma_f32_16x16x32_bf16 v[34:37], v[184:187], v[200:203], v[34:37]
	v_mfma_f32_16x16x32_bf16 v[22:25], v[176:179], v[208:211], v[22:25]
	v_mfma_f32_16x16x32_bf16 v[18:21], v[184:187], v[208:211], v[18:21]
	v_mfma_f32_16x16x32_bf16 v[6:9], v[176:179], v[216:219], v[6:9]
	v_mfma_f32_16x16x32_bf16 v[2:5], v[184:187], v[216:219], v[2:5]
	s_barrier
	s_setprio 0
	s_add_i32 s65, 0, 0x18000
	v_add_u32_e32 v142, s65, v156
	s_add_i32 s66, 0, 0x1c000
	ds_read_b128 v[144:147], v142
	ds_read_b128 v[160:163], v142 offset:1024
	ds_read_b128 v[164:167], v142 offset:2048
	ds_read_b128 v[168:171], v142 offset:3072
	v_add_u32_e32 v142, s66, v156
	ds_read_b128 v[172:175], v142
	ds_read_b128 v[176:179], v142 offset:1024
	ds_read_b128 v[180:183], v142 offset:2048
	ds_read_b128 v[184:187], v142 offset:3072
	s_add_u32 s42, s42, 0x100000
	s_addc_u32 s43, s43, 0
	s_mov_b32 m0, s48
	v_lshl_add_u64 v[226:227], s[42:43], 0, v[130:131]
	ds_read_b128 v[188:191], v153 offset:32768
	ds_read_b128 v[192:195], v153 offset:33792
	ds_read_b128 v[196:199], v153 offset:34816
	ds_read_b128 v[200:203], v153 offset:35840
	ds_read_b128 v[204:207], v153 offset:36864
	ds_read_b128 v[208:211], v153 offset:37888
	ds_read_b128 v[212:215], v153 offset:38912
	ds_read_b128 v[216:219], v153 offset:39936
	global_load_lds_dwordx4 v[226:227], off
	v_lshl_add_u64 v[226:227], s[42:43], 0, v[134:135]
	s_mov_b32 m0, s49
	s_nop 0
	global_load_lds_dwordx4 v[226:227], off
	s_waitcnt vmcnt(8)
	s_waitcnt lgkmcnt(0)
	s_setprio 1
	s_barrier
	v_mfma_f32_16x16x32_bf16 v[126:129], v[144:147], v[188:191], v[126:129]
	v_mfma_f32_16x16x32_bf16 v[122:125], v[164:167], v[188:191], v[122:125]
	v_mfma_f32_16x16x32_bf16 v[110:113], v[144:147], v[196:199], v[110:113]
	v_mfma_f32_16x16x32_bf16 v[106:109], v[164:167], v[196:199], v[106:109]
	v_mfma_f32_16x16x32_bf16 v[94:97], v[144:147], v[204:207], v[94:97]
	v_mfma_f32_16x16x32_bf16 v[90:93], v[164:167], v[204:207], v[90:93]
	v_mfma_f32_16x16x32_bf16 v[78:81], v[144:147], v[212:215], v[78:81]
	v_mfma_f32_16x16x32_bf16 v[74:77], v[164:167], v[212:215], v[74:77]
	v_mfma_f32_16x16x32_bf16 v[126:129], v[160:163], v[192:195], v[126:129]
	v_mfma_f32_16x16x32_bf16 v[122:125], v[168:171], v[192:195], v[122:125]
	v_mfma_f32_16x16x32_bf16 v[110:113], v[160:163], v[200:203], v[110:113]
	v_mfma_f32_16x16x32_bf16 v[106:109], v[168:171], v[200:203], v[106:109]
	v_mfma_f32_16x16x32_bf16 v[94:97], v[160:163], v[208:211], v[94:97]
	v_mfma_f32_16x16x32_bf16 v[90:93], v[168:171], v[208:211], v[90:93]
	v_mfma_f32_16x16x32_bf16 v[78:81], v[160:163], v[216:219], v[78:81]
	v_mfma_f32_16x16x32_bf16 v[74:77], v[168:171], v[216:219], v[74:77]
	v_mfma_f32_16x16x32_bf16 v[118:121], v[172:175], v[188:191], v[118:121]
	v_mfma_f32_16x16x32_bf16 v[114:117], v[180:183], v[188:191], v[114:117]
	v_mfma_f32_16x16x32_bf16 v[102:105], v[172:175], v[196:199], v[102:105]
	v_mfma_f32_16x16x32_bf16 v[98:101], v[180:183], v[196:199], v[98:101]
	v_mfma_f32_16x16x32_bf16 v[86:89], v[172:175], v[204:207], v[86:89]
	v_mfma_f32_16x16x32_bf16 v[82:85], v[180:183], v[204:207], v[82:85]
	v_mfma_f32_16x16x32_bf16 v[70:73], v[172:175], v[212:215], v[70:73]
	v_mfma_f32_16x16x32_bf16 v[66:69], v[180:183], v[212:215], v[66:69]
	v_mfma_f32_16x16x32_bf16 v[118:121], v[176:179], v[192:195], v[118:121]
	v_mfma_f32_16x16x32_bf16 v[114:117], v[184:187], v[192:195], v[114:117]
	v_mfma_f32_16x16x32_bf16 v[102:105], v[176:179], v[200:203], v[102:105]
	v_mfma_f32_16x16x32_bf16 v[98:101], v[184:187], v[200:203], v[98:101]
	v_mfma_f32_16x16x32_bf16 v[86:89], v[176:179], v[208:211], v[86:89]
	v_mfma_f32_16x16x32_bf16 v[82:85], v[184:187], v[208:211], v[82:85]
	v_mfma_f32_16x16x32_bf16 v[70:73], v[176:179], v[216:219], v[70:73]
	v_mfma_f32_16x16x32_bf16 v[66:69], v[184:187], v[216:219], v[66:69]
	s_barrier
	s_setprio 0
	s_add_i32 s42, s65, s46
	v_lshl_add_u64 v[148:149], v[148:149], 0, s[12:13]
	s_mov_b32 m0, s42
	ds_read_b128 v[188:191], v153 offset:49152
	ds_read_b128 v[192:195], v153 offset:50176
	ds_read_b128 v[196:199], v153 offset:51200
	ds_read_b128 v[200:203], v153 offset:52224
	ds_read_b128 v[204:207], v153 offset:53248
	ds_read_b128 v[208:211], v153 offset:54272
	ds_read_b128 v[212:215], v153 offset:55296
	ds_read_b128 v[216:219], v153 offset:56320
	global_load_lds_dwordx4 v[148:149], off
	s_add_i32 m0, s42, 0x2000
	s_add_u32 s40, s40, 0x100080
	v_lshl_add_u64 v[148:149], v[220:221], 0, s[12:13]
	s_addc_u32 s41, s41, 0
	s_add_i32 s42, s66, s46
	global_load_lds_dwordx4 v[148:149], off
	v_lshl_add_u64 v[148:149], s[40:41], 0, v[132:133]
	s_mov_b32 m0, s42
	s_nop 0
	global_load_lds_dwordx4 v[148:149], off
	v_lshl_add_u64 v[148:149], s[40:41], 0, v[136:137]
	s_add_i32 m0, s42, 0x2000
	s_nop 0
	global_load_lds_dwordx4 v[148:149], off
	v_lshl_add_u64 v[148:149], v[222:223], 0, s[12:13]
	s_mov_b32 m0, s54
	s_nop 0
	global_load_lds_dwordx4 v[148:149], off
	v_lshl_add_u64 v[148:149], v[224:225], 0, s[12:13]
	s_mov_b32 m0, s55
	s_nop 0
	global_load_lds_dwordx4 v[148:149], off
	s_waitcnt vmcnt(8)
	s_waitcnt lgkmcnt(0)
	s_setprio 1
	s_barrier
	v_mfma_f32_16x16x32_bf16 v[62:65], v[144:147], v[188:191], v[62:65]
	v_mfma_f32_16x16x32_bf16 v[58:61], v[164:167], v[188:191], v[58:61]
	v_mfma_f32_16x16x32_bf16 v[46:49], v[144:147], v[196:199], v[46:49]
	v_mfma_f32_16x16x32_bf16 v[42:45], v[164:167], v[196:199], v[42:45]
	v_mfma_f32_16x16x32_bf16 v[30:33], v[144:147], v[204:207], v[30:33]
	v_mfma_f32_16x16x32_bf16 v[26:29], v[164:167], v[204:207], v[26:29]
	v_mfma_f32_16x16x32_bf16 v[14:17], v[144:147], v[212:215], v[14:17]
	v_mfma_f32_16x16x32_bf16 v[10:13], v[164:167], v[212:215], v[10:13]
	v_mfma_f32_16x16x32_bf16 v[62:65], v[160:163], v[192:195], v[62:65]
	v_mfma_f32_16x16x32_bf16 v[58:61], v[168:171], v[192:195], v[58:61]
	v_mfma_f32_16x16x32_bf16 v[46:49], v[160:163], v[200:203], v[46:49]
	v_mfma_f32_16x16x32_bf16 v[42:45], v[168:171], v[200:203], v[42:45]
	v_mfma_f32_16x16x32_bf16 v[30:33], v[160:163], v[208:211], v[30:33]
	v_mfma_f32_16x16x32_bf16 v[26:29], v[168:171], v[208:211], v[26:29]
	v_mfma_f32_16x16x32_bf16 v[14:17], v[160:163], v[216:219], v[14:17]
	v_mfma_f32_16x16x32_bf16 v[10:13], v[168:171], v[216:219], v[10:13]
	v_mfma_f32_16x16x32_bf16 v[54:57], v[172:175], v[188:191], v[54:57]
	v_mfma_f32_16x16x32_bf16 v[50:53], v[180:183], v[188:191], v[50:53]
	v_mfma_f32_16x16x32_bf16 v[38:41], v[172:175], v[196:199], v[38:41]
	v_mfma_f32_16x16x32_bf16 v[34:37], v[180:183], v[196:199], v[34:37]
	v_mfma_f32_16x16x32_bf16 v[22:25], v[172:175], v[204:207], v[22:25]
	v_mfma_f32_16x16x32_bf16 v[18:21], v[180:183], v[204:207], v[18:21]
	v_mfma_f32_16x16x32_bf16 v[6:9], v[172:175], v[212:215], v[6:9]
	v_mfma_f32_16x16x32_bf16 v[2:5], v[180:183], v[212:215], v[2:5]
	v_mfma_f32_16x16x32_bf16 v[54:57], v[176:179], v[192:195], v[54:57]
	v_mfma_f32_16x16x32_bf16 v[50:53], v[184:187], v[192:195], v[50:53]
	v_mfma_f32_16x16x32_bf16 v[38:41], v[176:179], v[200:203], v[38:41]
	v_mfma_f32_16x16x32_bf16 v[34:37], v[184:187], v[200:203], v[34:37]
	v_mfma_f32_16x16x32_bf16 v[22:25], v[176:179], v[208:211], v[22:25]
	v_mfma_f32_16x16x32_bf16 v[18:21], v[184:187], v[208:211], v[18:21]
	v_mfma_f32_16x16x32_bf16 v[6:9], v[176:179], v[216:219], v[6:9]
	v_mfma_f32_16x16x32_bf16 v[2:5], v[184:187], v[216:219], v[2:5]
	s_barrier
	s_setprio 0
	s_add_i32 s64, s64, 2
	s_add_u32 s38, s38, 0x100
	s_addc_u32 s39, s39, 0
	s_add_u32 s62, s62, 0x100
	s_addc_u32 s63, s63, 0
	s_cmp_gt_u32 s64, 61
	s_cbranch_scc0 .LBB0_1294
	s_and_b64 vcc, exec, s[14:15]
	s_cbranch_vccz .LBB0_1297
	s_barrier

.LBB0_1386:
	s_add_u32 s47, s38, s46
	s_addc_u32 s52, s39, 0
	s_add_u32 s50, s47, 0x100
	s_addc_u32 s51, s52, 0
	s_and_b64 s[48:49], s[44:45], exec
	s_cselect_b32 s49, s2, s51
	s_cselect_b32 s48, s29, s50
	s_add_u32 s46, s40, s46
	s_addc_u32 s50, s41, 0
	s_add_u32 s46, s46, 0x100
	s_addc_u32 s50, s50, 0
	s_and_b64 s[44:45], s[44:45], exec
	s_cselect_b32 s51, s27, s50
	s_cselect_b32 s50, s70, s46
	s_add_u32 s54, s47, 0x10080
	ds_read_b128 v[152:155], v148
	ds_read_b128 v[156:159], v148 offset:1024
	ds_read_b128 v[160:163], v148 offset:2048
	ds_read_b128 v[164:167], v148 offset:3072
	ds_read_b128 v[168:171], v149
	ds_read_b128 v[172:175], v149 offset:1024
	ds_read_b128 v[176:179], v149 offset:2048
	ds_read_b128 v[180:183], v149 offset:3072
	s_addc_u32 s55, s52, 0
	s_add_i32 s83, s66, s57
	s_add_i32 m0, s37, 0xc000
	s_add_i32 s84, s37, 0xe000
	s_add_i32 s79, s83, 0x2000
	s_add_u32 s52, s50, 0x10000
	s_addc_u32 s53, s51, 0
	s_add_i32 s82, s67, s57
	s_add_i32 s81, s82, 0x2000
	s_add_i32 s78, 0, 0x18000
	s_add_i32 s77, 0, 0x1c000
	s_add_u32 s46, s48, 0x10000
	s_addc_u32 s47, s49, 0
	s_add_i32 s76, s78, s57
	s_add_i32 s72, s76, 0x2000
	s_add_u32 s44, s50, 0x10080
	s_addc_u32 s45, s51, 0
	s_add_i32 s73, s77, s57
	s_add_i32 s71, s73, 0x2000
	v_lshl_add_u64 v[140:141], s[54:55], 0, v[130:131]
	ds_read_b128 v[184:187], v150
	ds_read_b128 v[188:191], v150 offset:1024
	ds_read_b128 v[192:195], v150 offset:2048
	ds_read_b128 v[196:199], v150 offset:3072
	ds_read_b128 v[200:203], v150 offset:4096
	ds_read_b128 v[204:207], v150 offset:5120
	ds_read_b128 v[208:211], v150 offset:6144
	ds_read_b128 v[212:215], v150 offset:7168
	global_load_lds_dwordx4 v[140:141], off
	v_lshl_add_u64 v[140:141], s[54:55], 0, v[134:135]
	s_mov_b32 m0, s84
	s_nop 0
	global_load_lds_dwordx4 v[140:141], off
	s_waitcnt vmcnt(8)
	s_waitcnt lgkmcnt(0)
	s_setprio 1
	s_barrier
	v_mfma_f32_16x16x32_bf16 v[126:129], v[152:155], v[184:187], v[126:129]
	v_mfma_f32_16x16x32_bf16 v[122:125], v[160:163], v[184:187], v[122:125]
	v_mfma_f32_16x16x32_bf16 v[114:117], v[152:155], v[192:195], v[114:117]
	v_mfma_f32_16x16x32_bf16 v[106:109], v[160:163], v[192:195], v[106:109]
	v_mfma_f32_16x16x32_bf16 v[98:101], v[152:155], v[200:203], v[98:101]
	v_mfma_f32_16x16x32_bf16 v[90:93], v[160:163], v[200:203], v[90:93]
	v_mfma_f32_16x16x32_bf16 v[82:85], v[152:155], v[208:211], v[82:85]
	v_mfma_f32_16x16x32_bf16 v[74:77], v[160:163], v[208:211], v[74:77]
	v_mfma_f32_16x16x32_bf16 v[126:129], v[156:159], v[188:191], v[126:129]
	v_mfma_f32_16x16x32_bf16 v[122:125], v[164:167], v[188:191], v[122:125]
	v_mfma_f32_16x16x32_bf16 v[114:117], v[156:159], v[196:199], v[114:117]
	v_mfma_f32_16x16x32_bf16 v[106:109], v[164:167], v[196:199], v[106:109]
	v_mfma_f32_16x16x32_bf16 v[98:101], v[156:159], v[204:207], v[98:101]
	v_mfma_f32_16x16x32_bf16 v[90:93], v[164:167], v[204:207], v[90:93]
	v_mfma_f32_16x16x32_bf16 v[82:85], v[156:159], v[212:215], v[82:85]
	v_mfma_f32_16x16x32_bf16 v[74:77], v[164:167], v[212:215], v[74:77]
	v_mfma_f32_16x16x32_bf16 v[118:121], v[168:171], v[184:187], v[118:121]
	v_mfma_f32_16x16x32_bf16 v[110:113], v[176:179], v[184:187], v[110:113]
	v_mfma_f32_16x16x32_bf16 v[102:105], v[168:171], v[192:195], v[102:105]
	v_mfma_f32_16x16x32_bf16 v[94:97], v[176:179], v[192:195], v[94:97]
	v_mfma_f32_16x16x32_bf16 v[86:89], v[168:171], v[200:203], v[86:89]
	v_mfma_f32_16x16x32_bf16 v[78:81], v[176:179], v[200:203], v[78:81]
	v_mfma_f32_16x16x32_bf16 v[70:73], v[168:171], v[208:211], v[70:73]
	v_mfma_f32_16x16x32_bf16 v[66:69], v[176:179], v[208:211], v[66:69]
	v_mfma_f32_16x16x32_bf16 v[118:121], v[172:175], v[188:191], v[118:121]
	v_mfma_f32_16x16x32_bf16 v[110:113], v[180:183], v[188:191], v[110:113]
	v_mfma_f32_16x16x32_bf16 v[102:105], v[172:175], v[196:199], v[102:105]
	v_mfma_f32_16x16x32_bf16 v[94:97], v[180:183], v[196:199], v[94:97]
	v_mfma_f32_16x16x32_bf16 v[86:89], v[172:175], v[204:207], v[86:89]
	v_mfma_f32_16x16x32_bf16 v[78:81], v[180:183], v[204:207], v[78:81]
	v_mfma_f32_16x16x32_bf16 v[70:73], v[172:175], v[212:215], v[70:73]
	v_mfma_f32_16x16x32_bf16 v[66:69], v[180:183], v[212:215], v[66:69]
	s_barrier
	s_setprio 0
	s_mov_b32 m0, s83
	v_lshl_add_u64 v[140:141], s[50:51], 0, v[132:133]
	ds_read_b128 v[184:187], v150 offset:16384
	ds_read_b128 v[188:191], v150 offset:17408
	ds_read_b128 v[192:195], v150 offset:18432
	ds_read_b128 v[196:199], v150 offset:19456
	ds_read_b128 v[200:203], v150 offset:20480
	ds_read_b128 v[204:207], v150 offset:21504
	ds_read_b128 v[208:211], v150 offset:22528
	ds_read_b128 v[212:215], v150 offset:23552
	global_load_lds_dwordx4 v[140:141], off
	v_lshl_add_u64 v[216:217], s[50:51], 0, v[136:137]
	s_mov_b32 m0, s79
	v_lshl_add_u64 v[218:219], s[52:53], 0, v[132:133]
	global_load_lds_dwordx4 v[216:217], off
	s_mov_b32 m0, s82
	v_lshl_add_u64 v[220:221], s[48:49], 0, v[134:135]
	global_load_lds_dwordx4 v[218:219], off
	v_lshl_add_u64 v[218:219], s[52:53], 0, v[136:137]
	s_mov_b32 m0, s81
	s_nop 0
	global_load_lds_dwordx4 v[218:219], off
	v_lshl_add_u64 v[218:219], s[48:49], 0, v[130:131]
	s_mov_b32 m0, s37
	s_nop 0
	global_load_lds_dwordx4 v[218:219], off
	s_mov_b32 m0, s58
	s_nop 0
	global_load_lds_dwordx4 v[220:221], off
	s_waitcnt vmcnt(8)
	s_waitcnt lgkmcnt(0)
	s_setprio 1
	s_barrier
	v_mfma_f32_16x16x32_bf16 v[62:65], v[152:155], v[184:187], v[62:65]
	v_mfma_f32_16x16x32_bf16 v[58:61], v[160:163], v[184:187], v[58:61]
	v_mfma_f32_16x16x32_bf16 v[50:53], v[152:155], v[192:195], v[50:53]
	v_mfma_f32_16x16x32_bf16 v[42:45], v[160:163], v[192:195], v[42:45]
	v_mfma_f32_16x16x32_bf16 v[34:37], v[152:155], v[200:203], v[34:37]
	v_mfma_f32_16x16x32_bf16 v[26:29], v[160:163], v[200:203], v[26:29]
	v_mfma_f32_16x16x32_bf16 v[18:21], v[152:155], v[208:211], v[18:21]
	v_mfma_f32_16x16x32_bf16 v[10:13], v[160:163], v[208:211], v[10:13]
	v_mfma_f32_16x16x32_bf16 v[62:65], v[156:159], v[188:191], v[62:65]
	v_mfma_f32_16x16x32_bf16 v[58:61], v[164:167], v[188:191], v[58:61]
	v_mfma_f32_16x16x32_bf16 v[50:53], v[156:159], v[196:199], v[50:53]
	v_mfma_f32_16x16x32_bf16 v[42:45], v[164:167], v[196:199], v[42:45]
	v_mfma_f32_16x16x32_bf16 v[34:37], v[156:159], v[204:207], v[34:37]
	v_mfma_f32_16x16x32_bf16 v[26:29], v[164:167], v[204:207], v[26:29]
	v_mfma_f32_16x16x32_bf16 v[18:21], v[156:159], v[212:215], v[18:21]
	v_mfma_f32_16x16x32_bf16 v[10:13], v[164:167], v[212:215], v[10:13]
	v_mfma_f32_16x16x32_bf16 v[54:57], v[168:171], v[184:187], v[54:57]
	v_mfma_f32_16x16x32_bf16 v[46:49], v[176:179], v[184:187], v[46:49]
	v_mfma_f32_16x16x32_bf16 v[38:41], v[168:171], v[192:195], v[38:41]
	v_mfma_f32_16x16x32_bf16 v[30:33], v[176:179], v[192:195], v[30:33]
	v_mfma_f32_16x16x32_bf16 v[22:25], v[168:171], v[200:203], v[22:25]
	v_mfma_f32_16x16x32_bf16 v[14:17], v[176:179], v[200:203], v[14:17]
	v_mfma_f32_16x16x32_bf16 v[6:9], v[168:171], v[208:211], v[6:9]
	v_mfma_f32_16x16x32_bf16 v[2:5], v[176:179], v[208:211], v[2:5]
	v_mfma_f32_16x16x32_bf16 v[54:57], v[172:175], v[188:191], v[54:57]
	v_mfma_f32_16x16x32_bf16 v[46:49], v[180:183], v[188:191], v[46:49]
	v_mfma_f32_16x16x32_bf16 v[38:41], v[172:175], v[196:199], v[38:41]
	v_mfma_f32_16x16x32_bf16 v[30:33], v[180:183], v[196:199], v[30:33]
	v_mfma_f32_16x16x32_bf16 v[22:25], v[172:175], v[204:207], v[22:25]
	v_mfma_f32_16x16x32_bf16 v[14:17], v[180:183], v[204:207], v[14:17]
	v_mfma_f32_16x16x32_bf16 v[6:9], v[172:175], v[212:215], v[6:9]
	v_mfma_f32_16x16x32_bf16 v[2:5], v[180:183], v[212:215], v[2:5]
	s_barrier
	s_setprio 0
	v_add_u32_e32 v138, s78, v146
	ds_read_b128 v[152:155], v138
	ds_read_b128 v[156:159], v138 offset:1024
	ds_read_b128 v[160:163], v138 offset:2048
	ds_read_b128 v[164:167], v138 offset:3072
	v_add_u32_e32 v138, s77, v146
	ds_read_b128 v[168:171], v138
	ds_read_b128 v[172:175], v138 offset:1024
	ds_read_b128 v[176:179], v138 offset:2048
	ds_read_b128 v[180:183], v138 offset:3072
	s_mov_b32 m0, s59
	v_lshl_add_u64 v[222:223], s[46:47], 0, v[130:131]
	ds_read_b128 v[184:187], v150 offset:32768
	ds_read_b128 v[188:191], v150 offset:33792
	ds_read_b128 v[192:195], v150 offset:34816
	ds_read_b128 v[196:199], v150 offset:35840
	ds_read_b128 v[200:203], v150 offset:36864
	ds_read_b128 v[204:207], v150 offset:37888
	ds_read_b128 v[208:211], v150 offset:38912
	ds_read_b128 v[212:215], v150 offset:39936
	global_load_lds_dwordx4 v[222:223], off
	v_lshl_add_u64 v[222:223], s[46:47], 0, v[134:135]
	s_mov_b32 m0, s60
	s_nop 0
	global_load_lds_dwordx4 v[222:223], off
	s_waitcnt vmcnt(8)
	s_waitcnt lgkmcnt(0)
	s_setprio 1
	s_barrier
	v_mfma_f32_16x16x32_bf16 v[126:129], v[152:155], v[184:187], v[126:129]
	v_mfma_f32_16x16x32_bf16 v[122:125], v[160:163], v[184:187], v[122:125]
	v_mfma_f32_16x16x32_bf16 v[114:117], v[152:155], v[192:195], v[114:117]
	v_mfma_f32_16x16x32_bf16 v[106:109], v[160:163], v[192:195], v[106:109]
	v_mfma_f32_16x16x32_bf16 v[98:101], v[152:155], v[200:203], v[98:101]
	v_mfma_f32_16x16x32_bf16 v[90:93], v[160:163], v[200:203], v[90:93]
	v_mfma_f32_16x16x32_bf16 v[82:85], v[152:155], v[208:211], v[82:85]
	v_mfma_f32_16x16x32_bf16 v[74:77], v[160:163], v[208:211], v[74:77]
	v_mfma_f32_16x16x32_bf16 v[126:129], v[156:159], v[188:191], v[126:129]
	v_mfma_f32_16x16x32_bf16 v[122:125], v[164:167], v[188:191], v[122:125]
	v_mfma_f32_16x16x32_bf16 v[114:117], v[156:159], v[196:199], v[114:117]
	v_mfma_f32_16x16x32_bf16 v[106:109], v[164:167], v[196:199], v[106:109]
	v_mfma_f32_16x16x32_bf16 v[98:101], v[156:159], v[204:207], v[98:101]
	v_mfma_f32_16x16x32_bf16 v[90:93], v[164:167], v[204:207], v[90:93]
	v_mfma_f32_16x16x32_bf16 v[82:85], v[156:159], v[212:215], v[82:85]
	v_mfma_f32_16x16x32_bf16 v[74:77], v[164:167], v[212:215], v[74:77]
	v_mfma_f32_16x16x32_bf16 v[118:121], v[168:171], v[184:187], v[118:121]
	v_mfma_f32_16x16x32_bf16 v[110:113], v[176:179], v[184:187], v[110:113]
	v_mfma_f32_16x16x32_bf16 v[102:105], v[168:171], v[192:195], v[102:105]
	v_mfma_f32_16x16x32_bf16 v[94:97], v[176:179], v[192:195], v[94:97]
	v_mfma_f32_16x16x32_bf16 v[86:89], v[168:171], v[200:203], v[86:89]
	v_mfma_f32_16x16x32_bf16 v[78:81], v[176:179], v[200:203], v[78:81]
	v_mfma_f32_16x16x32_bf16 v[70:73], v[168:171], v[208:211], v[70:73]
	v_mfma_f32_16x16x32_bf16 v[66:69], v[176:179], v[208:211], v[66:69]
	v_mfma_f32_16x16x32_bf16 v[118:121], v[172:175], v[188:191], v[118:121]
	v_mfma_f32_16x16x32_bf16 v[110:113], v[180:183], v[188:191], v[110:113]
	v_mfma_f32_16x16x32_bf16 v[102:105], v[172:175], v[196:199], v[102:105]
	v_mfma_f32_16x16x32_bf16 v[94:97], v[180:183], v[196:199], v[94:97]
	v_mfma_f32_16x16x32_bf16 v[86:89], v[172:175], v[204:207], v[86:89]
	v_mfma_f32_16x16x32_bf16 v[78:81], v[180:183], v[204:207], v[78:81]
	v_mfma_f32_16x16x32_bf16 v[70:73], v[172:175], v[212:215], v[70:73]
	v_mfma_f32_16x16x32_bf16 v[66:69], v[180:183], v[212:215], v[66:69]
	s_barrier
	s_setprio 0
	s_mov_b32 m0, s76
	v_lshl_add_u64 v[140:141], v[140:141], 0, s[14:15]
	ds_read_b128 v[184:187], v150 offset:49152
	ds_read_b128 v[188:191], v150 offset:50176
	ds_read_b128 v[192:195], v150 offset:51200
	ds_read_b128 v[196:199], v150 offset:52224
	ds_read_b128 v[200:203], v150 offset:53248
	ds_read_b128 v[204:207], v150 offset:54272
	ds_read_b128 v[208:211], v150 offset:55296
	ds_read_b128 v[212:215], v150 offset:56320
	global_load_lds_dwordx4 v[140:141], off
	v_lshl_add_u64 v[140:141], v[216:217], 0, s[14:15]
	s_mov_b32 m0, s72
	s_nop 0
	global_load_lds_dwordx4 v[140:141], off
	v_lshl_add_u64 v[140:141], s[44:45], 0, v[132:133]
	s_mov_b32 m0, s73
	s_nop 0
	global_load_lds_dwordx4 v[140:141], off
	v_lshl_add_u64 v[140:141], s[44:45], 0, v[136:137]
	s_mov_b32 m0, s71
	s_nop 0
	global_load_lds_dwordx4 v[140:141], off
	v_lshl_add_u64 v[140:141], v[218:219], 0, s[14:15]
	s_mov_b32 m0, s63
	s_nop 0
	global_load_lds_dwordx4 v[140:141], off
	v_lshl_add_u64 v[140:141], v[220:221], 0, s[14:15]
	s_mov_b32 m0, s64
	s_nop 0
	global_load_lds_dwordx4 v[140:141], off
	s_waitcnt vmcnt(8)
	s_waitcnt lgkmcnt(0)
	s_setprio 1
	s_barrier
	v_mfma_f32_16x16x32_bf16 v[62:65], v[152:155], v[184:187], v[62:65]
	v_mfma_f32_16x16x32_bf16 v[58:61], v[160:163], v[184:187], v[58:61]
	v_mfma_f32_16x16x32_bf16 v[50:53], v[152:155], v[192:195], v[50:53]
	v_mfma_f32_16x16x32_bf16 v[42:45], v[160:163], v[192:195], v[42:45]
	v_mfma_f32_16x16x32_bf16 v[34:37], v[152:155], v[200:203], v[34:37]
	v_mfma_f32_16x16x32_bf16 v[26:29], v[160:163], v[200:203], v[26:29]
	v_mfma_f32_16x16x32_bf16 v[18:21], v[152:155], v[208:211], v[18:21]
	v_mfma_f32_16x16x32_bf16 v[10:13], v[160:163], v[208:211], v[10:13]
	v_mfma_f32_16x16x32_bf16 v[62:65], v[156:159], v[188:191], v[62:65]
	v_mfma_f32_16x16x32_bf16 v[58:61], v[164:167], v[188:191], v[58:61]
	v_mfma_f32_16x16x32_bf16 v[50:53], v[156:159], v[196:199], v[50:53]
	v_mfma_f32_16x16x32_bf16 v[42:45], v[164:167], v[196:199], v[42:45]
	v_mfma_f32_16x16x32_bf16 v[34:37], v[156:159], v[204:207], v[34:37]
	v_mfma_f32_16x16x32_bf16 v[26:29], v[164:167], v[204:207], v[26:29]
	v_mfma_f32_16x16x32_bf16 v[18:21], v[156:159], v[212:215], v[18:21]
	v_mfma_f32_16x16x32_bf16 v[10:13], v[164:167], v[212:215], v[10:13]
	v_mfma_f32_16x16x32_bf16 v[54:57], v[168:171], v[184:187], v[54:57]
	v_mfma_f32_16x16x32_bf16 v[46:49], v[176:179], v[184:187], v[46:49]
	v_mfma_f32_16x16x32_bf16 v[38:41], v[168:171], v[192:195], v[38:41]
	v_mfma_f32_16x16x32_bf16 v[30:33], v[176:179], v[192:195], v[30:33]
	v_mfma_f32_16x16x32_bf16 v[22:25], v[168:171], v[200:203], v[22:25]
	v_mfma_f32_16x16x32_bf16 v[14:17], v[176:179], v[200:203], v[14:17]
	v_mfma_f32_16x16x32_bf16 v[6:9], v[168:171], v[208:211], v[6:9]
	v_mfma_f32_16x16x32_bf16 v[2:5], v[176:179], v[208:211], v[2:5]
	v_mfma_f32_16x16x32_bf16 v[54:57], v[172:175], v[188:191], v[54:57]
	v_mfma_f32_16x16x32_bf16 v[46:49], v[180:183], v[188:191], v[46:49]
	v_mfma_f32_16x16x32_bf16 v[38:41], v[172:175], v[196:199], v[38:41]
	v_mfma_f32_16x16x32_bf16 v[30:33], v[180:183], v[196:199], v[30:33]
	v_mfma_f32_16x16x32_bf16 v[22:25], v[172:175], v[204:207], v[22:25]
	v_mfma_f32_16x16x32_bf16 v[14:17], v[180:183], v[204:207], v[14:17]
	v_mfma_f32_16x16x32_bf16 v[6:9], v[172:175], v[212:215], v[6:9]
	v_mfma_f32_16x16x32_bf16 v[2:5], v[180:183], v[212:215], v[2:5]
	s_barrier
	s_setprio 0
	s_movk_i32 s46, 0x100
	s_andn2_b64 vcc, exec, s[42:43]
	s_mov_b64 s[44:45], -1
	s_mov_b64 s[42:43], 0
	s_cbranch_vccz .LBB0_1386
	s_and_b64 vcc, exec, s[16:17]
	s_cbranch_vccz .LBB0_1389
	s_barrier

.LBB0_1410:
	s_add_u32 s47, s38, s46
	s_addc_u32 s52, s39, 0
	s_add_u32 s50, s47, 0x100
	s_addc_u32 s51, s52, 0
	s_and_b64 s[48:49], s[44:45], exec
	s_cselect_b32 s49, s2, s51
	s_cselect_b32 s48, s29, s50
	s_add_u32 s46, s40, s46
	s_addc_u32 s50, s41, 0
	s_add_u32 s46, s46, 0x100
	s_addc_u32 s50, s50, 0
	s_and_b64 s[44:45], s[44:45], exec
	s_cselect_b32 s51, s27, s50
	s_cselect_b32 s50, s70, s46
	s_add_u32 s54, s47, 0x10080
	ds_read_b128 v[148:151], v143
	ds_read_b128 v[152:155], v143 offset:1024
	ds_read_b128 v[156:159], v143 offset:2048
	ds_read_b128 v[160:163], v143 offset:3072
	ds_read_b128 v[164:167], v144
	ds_read_b128 v[168:171], v144 offset:1024
	ds_read_b128 v[172:175], v144 offset:2048
	ds_read_b128 v[176:179], v144 offset:3072
	s_addc_u32 s55, s52, 0
	s_add_i32 s83, s66, s58
	s_add_i32 m0, s37, 0xc000
	s_add_i32 s84, s37, 0xe000
	s_add_i32 s79, s83, 0x2000
	s_add_u32 s52, s50, 0x10000
	s_addc_u32 s53, s51, 0
	s_add_i32 s82, s67, s58
	s_add_i32 s81, s82, 0x2000
	s_add_i32 s78, 0, 0x18000
	s_add_i32 s77, 0, 0x1c000
	s_add_u32 s46, s48, 0x10000
	s_addc_u32 s47, s49, 0
	s_add_i32 s76, s78, s58
	s_add_i32 s72, s76, 0x2000
	s_add_u32 s44, s50, 0x10080
	s_addc_u32 s45, s51, 0
	s_add_i32 s73, s77, s58
	s_add_i32 s71, s73, 0x2000
	v_lshl_add_u64 v[140:141], s[54:55], 0, v[130:131]
	ds_read_b128 v[180:183], v146
	ds_read_b128 v[184:187], v146 offset:1024
	ds_read_b128 v[188:191], v146 offset:2048
	ds_read_b128 v[192:195], v146 offset:3072
	ds_read_b128 v[196:199], v146 offset:4096
	ds_read_b128 v[200:203], v146 offset:5120
	ds_read_b128 v[204:207], v146 offset:6144
	ds_read_b128 v[208:211], v146 offset:7168
	global_load_lds_dwordx4 v[140:141], off
	v_lshl_add_u64 v[140:141], s[54:55], 0, v[134:135]
	s_mov_b32 m0, s84
	s_nop 0
	global_load_lds_dwordx4 v[140:141], off
	s_waitcnt vmcnt(8)
	s_waitcnt lgkmcnt(0)
	s_setprio 1
	s_barrier
	v_mfma_f32_16x16x32_bf16 v[126:129], v[148:151], v[180:183], v[126:129]
	v_mfma_f32_16x16x32_bf16 v[122:125], v[156:159], v[180:183], v[122:125]
	v_mfma_f32_16x16x32_bf16 v[114:117], v[148:151], v[188:191], v[114:117]
	v_mfma_f32_16x16x32_bf16 v[106:109], v[156:159], v[188:191], v[106:109]
	v_mfma_f32_16x16x32_bf16 v[98:101], v[148:151], v[196:199], v[98:101]
	v_mfma_f32_16x16x32_bf16 v[90:93], v[156:159], v[196:199], v[90:93]
	v_mfma_f32_16x16x32_bf16 v[82:85], v[148:151], v[204:207], v[82:85]
	v_mfma_f32_16x16x32_bf16 v[74:77], v[156:159], v[204:207], v[74:77]
	v_mfma_f32_16x16x32_bf16 v[126:129], v[152:155], v[184:187], v[126:129]
	v_mfma_f32_16x16x32_bf16 v[122:125], v[160:163], v[184:187], v[122:125]
	v_mfma_f32_16x16x32_bf16 v[114:117], v[152:155], v[192:195], v[114:117]
	v_mfma_f32_16x16x32_bf16 v[106:109], v[160:163], v[192:195], v[106:109]
	v_mfma_f32_16x16x32_bf16 v[98:101], v[152:155], v[200:203], v[98:101]
	v_mfma_f32_16x16x32_bf16 v[90:93], v[160:163], v[200:203], v[90:93]
	v_mfma_f32_16x16x32_bf16 v[82:85], v[152:155], v[208:211], v[82:85]
	v_mfma_f32_16x16x32_bf16 v[74:77], v[160:163], v[208:211], v[74:77]
	v_mfma_f32_16x16x32_bf16 v[118:121], v[164:167], v[180:183], v[118:121]
	v_mfma_f32_16x16x32_bf16 v[110:113], v[172:175], v[180:183], v[110:113]
	v_mfma_f32_16x16x32_bf16 v[102:105], v[164:167], v[188:191], v[102:105]
	v_mfma_f32_16x16x32_bf16 v[94:97], v[172:175], v[188:191], v[94:97]
	v_mfma_f32_16x16x32_bf16 v[86:89], v[164:167], v[196:199], v[86:89]
	v_mfma_f32_16x16x32_bf16 v[78:81], v[172:175], v[196:199], v[78:81]
	v_mfma_f32_16x16x32_bf16 v[70:73], v[164:167], v[204:207], v[70:73]
	v_mfma_f32_16x16x32_bf16 v[66:69], v[172:175], v[204:207], v[66:69]
	v_mfma_f32_16x16x32_bf16 v[118:121], v[168:171], v[184:187], v[118:121]
	v_mfma_f32_16x16x32_bf16 v[110:113], v[176:179], v[184:187], v[110:113]
	v_mfma_f32_16x16x32_bf16 v[102:105], v[168:171], v[192:195], v[102:105]
	v_mfma_f32_16x16x32_bf16 v[94:97], v[176:179], v[192:195], v[94:97]
	v_mfma_f32_16x16x32_bf16 v[86:89], v[168:171], v[200:203], v[86:89]
	v_mfma_f32_16x16x32_bf16 v[78:81], v[176:179], v[200:203], v[78:81]
	v_mfma_f32_16x16x32_bf16 v[70:73], v[168:171], v[208:211], v[70:73]
	v_mfma_f32_16x16x32_bf16 v[66:69], v[176:179], v[208:211], v[66:69]
	s_barrier
	s_setprio 0
	s_mov_b32 m0, s83
	v_lshl_add_u64 v[140:141], s[50:51], 0, v[132:133]
	ds_read_b128 v[180:183], v146 offset:16384
	ds_read_b128 v[184:187], v146 offset:17408
	ds_read_b128 v[188:191], v146 offset:18432
	ds_read_b128 v[192:195], v146 offset:19456
	ds_read_b128 v[196:199], v146 offset:20480
	ds_read_b128 v[200:203], v146 offset:21504
	ds_read_b128 v[204:207], v146 offset:22528
	ds_read_b128 v[208:211], v146 offset:23552
	global_load_lds_dwordx4 v[140:141], off
	v_lshl_add_u64 v[212:213], s[50:51], 0, v[136:137]
	s_mov_b32 m0, s79
	v_lshl_add_u64 v[214:215], s[52:53], 0, v[132:133]
	global_load_lds_dwordx4 v[212:213], off
	s_mov_b32 m0, s82
	v_lshl_add_u64 v[216:217], s[48:49], 0, v[134:135]
	global_load_lds_dwordx4 v[214:215], off
	v_lshl_add_u64 v[214:215], s[52:53], 0, v[136:137]
	s_mov_b32 m0, s81
	s_nop 0
	global_load_lds_dwordx4 v[214:215], off
	v_lshl_add_u64 v[214:215], s[48:49], 0, v[130:131]
	s_mov_b32 m0, s37
	s_nop 0
	global_load_lds_dwordx4 v[214:215], off
	s_mov_b32 m0, s59
	s_nop 0
	global_load_lds_dwordx4 v[216:217], off
	s_waitcnt vmcnt(8)
	s_waitcnt lgkmcnt(0)
	s_setprio 1
	s_barrier
	v_mfma_f32_16x16x32_bf16 v[62:65], v[148:151], v[180:183], v[62:65]
	v_mfma_f32_16x16x32_bf16 v[58:61], v[156:159], v[180:183], v[58:61]
	v_mfma_f32_16x16x32_bf16 v[50:53], v[148:151], v[188:191], v[50:53]
	v_mfma_f32_16x16x32_bf16 v[42:45], v[156:159], v[188:191], v[42:45]
	v_mfma_f32_16x16x32_bf16 v[34:37], v[148:151], v[196:199], v[34:37]
	v_mfma_f32_16x16x32_bf16 v[26:29], v[156:159], v[196:199], v[26:29]
	v_mfma_f32_16x16x32_bf16 v[18:21], v[148:151], v[204:207], v[18:21]
	v_mfma_f32_16x16x32_bf16 v[10:13], v[156:159], v[204:207], v[10:13]
	v_mfma_f32_16x16x32_bf16 v[62:65], v[152:155], v[184:187], v[62:65]
	v_mfma_f32_16x16x32_bf16 v[58:61], v[160:163], v[184:187], v[58:61]
	v_mfma_f32_16x16x32_bf16 v[50:53], v[152:155], v[192:195], v[50:53]
	v_mfma_f32_16x16x32_bf16 v[42:45], v[160:163], v[192:195], v[42:45]
	v_mfma_f32_16x16x32_bf16 v[34:37], v[152:155], v[200:203], v[34:37]
	v_mfma_f32_16x16x32_bf16 v[26:29], v[160:163], v[200:203], v[26:29]
	v_mfma_f32_16x16x32_bf16 v[18:21], v[152:155], v[208:211], v[18:21]
	v_mfma_f32_16x16x32_bf16 v[10:13], v[160:163], v[208:211], v[10:13]
	v_mfma_f32_16x16x32_bf16 v[54:57], v[164:167], v[180:183], v[54:57]
	v_mfma_f32_16x16x32_bf16 v[46:49], v[172:175], v[180:183], v[46:49]
	v_mfma_f32_16x16x32_bf16 v[38:41], v[164:167], v[188:191], v[38:41]
	v_mfma_f32_16x16x32_bf16 v[30:33], v[172:175], v[188:191], v[30:33]
	v_mfma_f32_16x16x32_bf16 v[22:25], v[164:167], v[196:199], v[22:25]
	v_mfma_f32_16x16x32_bf16 v[14:17], v[172:175], v[196:199], v[14:17]
	v_mfma_f32_16x16x32_bf16 v[6:9], v[164:167], v[204:207], v[6:9]
	v_mfma_f32_16x16x32_bf16 v[2:5], v[172:175], v[204:207], v[2:5]
	v_mfma_f32_16x16x32_bf16 v[54:57], v[168:171], v[184:187], v[54:57]
	v_mfma_f32_16x16x32_bf16 v[46:49], v[176:179], v[184:187], v[46:49]
	v_mfma_f32_16x16x32_bf16 v[38:41], v[168:171], v[192:195], v[38:41]
	v_mfma_f32_16x16x32_bf16 v[30:33], v[176:179], v[192:195], v[30:33]
	v_mfma_f32_16x16x32_bf16 v[22:25], v[168:171], v[200:203], v[22:25]
	v_mfma_f32_16x16x32_bf16 v[14:17], v[176:179], v[200:203], v[14:17]
	v_mfma_f32_16x16x32_bf16 v[6:9], v[168:171], v[208:211], v[6:9]
	v_mfma_f32_16x16x32_bf16 v[2:5], v[176:179], v[208:211], v[2:5]
	s_barrier
	s_setprio 0
	v_add_u32_e32 v138, s78, v142
	ds_read_b128 v[148:151], v138
	ds_read_b128 v[152:155], v138 offset:1024
	ds_read_b128 v[156:159], v138 offset:2048
	ds_read_b128 v[160:163], v138 offset:3072
	v_add_u32_e32 v138, s77, v142
	ds_read_b128 v[164:167], v138
	ds_read_b128 v[168:171], v138 offset:1024
	ds_read_b128 v[172:175], v138 offset:2048
	ds_read_b128 v[176:179], v138 offset:3072
	s_mov_b32 m0, s60
	v_lshl_add_u64 v[218:219], s[46:47], 0, v[130:131]
	ds_read_b128 v[180:183], v146 offset:32768
	ds_read_b128 v[184:187], v146 offset:33792
	ds_read_b128 v[188:191], v146 offset:34816
	ds_read_b128 v[192:195], v146 offset:35840
	ds_read_b128 v[196:199], v146 offset:36864
	ds_read_b128 v[200:203], v146 offset:37888
	ds_read_b128 v[204:207], v146 offset:38912
	ds_read_b128 v[208:211], v146 offset:39936
	global_load_lds_dwordx4 v[218:219], off
	v_lshl_add_u64 v[218:219], s[46:47], 0, v[134:135]
	s_mov_b32 m0, s61
	s_nop 0
	global_load_lds_dwordx4 v[218:219], off
	s_waitcnt vmcnt(8)
	s_waitcnt lgkmcnt(0)
	s_setprio 1
	s_barrier
	v_mfma_f32_16x16x32_bf16 v[126:129], v[148:151], v[180:183], v[126:129]
	v_mfma_f32_16x16x32_bf16 v[122:125], v[156:159], v[180:183], v[122:125]
	v_mfma_f32_16x16x32_bf16 v[114:117], v[148:151], v[188:191], v[114:117]
	v_mfma_f32_16x16x32_bf16 v[106:109], v[156:159], v[188:191], v[106:109]
	v_mfma_f32_16x16x32_bf16 v[98:101], v[148:151], v[196:199], v[98:101]
	v_mfma_f32_16x16x32_bf16 v[90:93], v[156:159], v[196:199], v[90:93]
	v_mfma_f32_16x16x32_bf16 v[82:85], v[148:151], v[204:207], v[82:85]
	v_mfma_f32_16x16x32_bf16 v[74:77], v[156:159], v[204:207], v[74:77]
	v_mfma_f32_16x16x32_bf16 v[126:129], v[152:155], v[184:187], v[126:129]
	v_mfma_f32_16x16x32_bf16 v[122:125], v[160:163], v[184:187], v[122:125]
	v_mfma_f32_16x16x32_bf16 v[114:117], v[152:155], v[192:195], v[114:117]
	v_mfma_f32_16x16x32_bf16 v[106:109], v[160:163], v[192:195], v[106:109]
	v_mfma_f32_16x16x32_bf16 v[98:101], v[152:155], v[200:203], v[98:101]
	v_mfma_f32_16x16x32_bf16 v[90:93], v[160:163], v[200:203], v[90:93]
	v_mfma_f32_16x16x32_bf16 v[82:85], v[152:155], v[208:211], v[82:85]
	v_mfma_f32_16x16x32_bf16 v[74:77], v[160:163], v[208:211], v[74:77]
	v_mfma_f32_16x16x32_bf16 v[118:121], v[164:167], v[180:183], v[118:121]
	v_mfma_f32_16x16x32_bf16 v[110:113], v[172:175], v[180:183], v[110:113]
	v_mfma_f32_16x16x32_bf16 v[102:105], v[164:167], v[188:191], v[102:105]
	v_mfma_f32_16x16x32_bf16 v[94:97], v[172:175], v[188:191], v[94:97]
	v_mfma_f32_16x16x32_bf16 v[86:89], v[164:167], v[196:199], v[86:89]
	v_mfma_f32_16x16x32_bf16 v[78:81], v[172:175], v[196:199], v[78:81]
	v_mfma_f32_16x16x32_bf16 v[70:73], v[164:167], v[204:207], v[70:73]
	v_mfma_f32_16x16x32_bf16 v[66:69], v[172:175], v[204:207], v[66:69]
	v_mfma_f32_16x16x32_bf16 v[118:121], v[168:171], v[184:187], v[118:121]
	v_mfma_f32_16x16x32_bf16 v[110:113], v[176:179], v[184:187], v[110:113]
	v_mfma_f32_16x16x32_bf16 v[102:105], v[168:171], v[192:195], v[102:105]
	v_mfma_f32_16x16x32_bf16 v[94:97], v[176:179], v[192:195], v[94:97]
	v_mfma_f32_16x16x32_bf16 v[86:89], v[168:171], v[200:203], v[86:89]
	v_mfma_f32_16x16x32_bf16 v[78:81], v[176:179], v[200:203], v[78:81]
	v_mfma_f32_16x16x32_bf16 v[70:73], v[168:171], v[208:211], v[70:73]
	v_mfma_f32_16x16x32_bf16 v[66:69], v[176:179], v[208:211], v[66:69]
	s_barrier
	s_setprio 0
	s_mov_b32 m0, s76
	v_lshl_add_u64 v[140:141], v[140:141], 0, s[14:15]
	ds_read_b128 v[180:183], v146 offset:49152
	ds_read_b128 v[184:187], v146 offset:50176
	ds_read_b128 v[188:191], v146 offset:51200
	ds_read_b128 v[192:195], v146 offset:52224
	ds_read_b128 v[196:199], v146 offset:53248
	ds_read_b128 v[200:203], v146 offset:54272
	ds_read_b128 v[204:207], v146 offset:55296
	ds_read_b128 v[208:211], v146 offset:56320
	global_load_lds_dwordx4 v[140:141], off
	v_lshl_add_u64 v[140:141], v[212:213], 0, s[14:15]
	s_mov_b32 m0, s72
	s_nop 0
	global_load_lds_dwordx4 v[140:141], off
	v_lshl_add_u64 v[140:141], s[44:45], 0, v[132:133]
	s_mov_b32 m0, s73
	s_nop 0
	global_load_lds_dwordx4 v[140:141], off
	v_lshl_add_u64 v[140:141], s[44:45], 0, v[136:137]
	s_mov_b32 m0, s71
	s_nop 0
	global_load_lds_dwordx4 v[140:141], off
	v_lshl_add_u64 v[140:141], v[214:215], 0, s[14:15]
	s_mov_b32 m0, s63
	s_nop 0
	global_load_lds_dwordx4 v[140:141], off
	v_lshl_add_u64 v[140:141], v[216:217], 0, s[14:15]
	s_mov_b32 m0, s64
	s_nop 0
	global_load_lds_dwordx4 v[140:141], off
	s_waitcnt vmcnt(8)
	s_waitcnt lgkmcnt(0)
	s_setprio 1
	s_barrier
	v_mfma_f32_16x16x32_bf16 v[62:65], v[148:151], v[180:183], v[62:65]
	v_mfma_f32_16x16x32_bf16 v[58:61], v[156:159], v[180:183], v[58:61]
	v_mfma_f32_16x16x32_bf16 v[50:53], v[148:151], v[188:191], v[50:53]
	v_mfma_f32_16x16x32_bf16 v[42:45], v[156:159], v[188:191], v[42:45]
	v_mfma_f32_16x16x32_bf16 v[34:37], v[148:151], v[196:199], v[34:37]
	v_mfma_f32_16x16x32_bf16 v[26:29], v[156:159], v[196:199], v[26:29]
	v_mfma_f32_16x16x32_bf16 v[18:21], v[148:151], v[204:207], v[18:21]
	v_mfma_f32_16x16x32_bf16 v[10:13], v[156:159], v[204:207], v[10:13]
	v_mfma_f32_16x16x32_bf16 v[62:65], v[152:155], v[184:187], v[62:65]
	v_mfma_f32_16x16x32_bf16 v[58:61], v[160:163], v[184:187], v[58:61]
	v_mfma_f32_16x16x32_bf16 v[50:53], v[152:155], v[192:195], v[50:53]
	v_mfma_f32_16x16x32_bf16 v[42:45], v[160:163], v[192:195], v[42:45]
	v_mfma_f32_16x16x32_bf16 v[34:37], v[152:155], v[200:203], v[34:37]
	v_mfma_f32_16x16x32_bf16 v[26:29], v[160:163], v[200:203], v[26:29]
	v_mfma_f32_16x16x32_bf16 v[18:21], v[152:155], v[208:211], v[18:21]
	v_mfma_f32_16x16x32_bf16 v[10:13], v[160:163], v[208:211], v[10:13]
	v_mfma_f32_16x16x32_bf16 v[54:57], v[164:167], v[180:183], v[54:57]
	v_mfma_f32_16x16x32_bf16 v[46:49], v[172:175], v[180:183], v[46:49]
	v_mfma_f32_16x16x32_bf16 v[38:41], v[164:167], v[188:191], v[38:41]
	v_mfma_f32_16x16x32_bf16 v[30:33], v[172:175], v[188:191], v[30:33]
	v_mfma_f32_16x16x32_bf16 v[22:25], v[164:167], v[196:199], v[22:25]
	v_mfma_f32_16x16x32_bf16 v[14:17], v[172:175], v[196:199], v[14:17]
	v_mfma_f32_16x16x32_bf16 v[6:9], v[164:167], v[204:207], v[6:9]
	v_mfma_f32_16x16x32_bf16 v[2:5], v[172:175], v[204:207], v[2:5]
	v_mfma_f32_16x16x32_bf16 v[54:57], v[168:171], v[184:187], v[54:57]
	v_mfma_f32_16x16x32_bf16 v[46:49], v[176:179], v[184:187], v[46:49]
	v_mfma_f32_16x16x32_bf16 v[38:41], v[168:171], v[192:195], v[38:41]
	v_mfma_f32_16x16x32_bf16 v[30:33], v[176:179], v[192:195], v[30:33]
	v_mfma_f32_16x16x32_bf16 v[22:25], v[168:171], v[200:203], v[22:25]
	v_mfma_f32_16x16x32_bf16 v[14:17], v[176:179], v[200:203], v[14:17]
	v_mfma_f32_16x16x32_bf16 v[6:9], v[168:171], v[208:211], v[6:9]
	v_mfma_f32_16x16x32_bf16 v[2:5], v[176:179], v[208:211], v[2:5]
	s_barrier
	s_setprio 0
	s_movk_i32 s46, 0x100
	s_andn2_b64 vcc, exec, s[42:43]
	s_mov_b64 s[44:45], -1
	s_mov_b64 s[42:43], 0
	s_cbranch_vccz .LBB0_1410
	s_and_b64 vcc, exec, s[16:17]
	s_cbranch_vccz .LBB0_1413
	s_barrier

.LBB0_2142:
	ds_read_b128 v[130:133], v199
	ds_read_b128 v[134:137], v199 offset:1024
	ds_read_b128 v[138:141], v199 offset:2048
	ds_read_b128 v[142:145], v199 offset:3072
	ds_read_b128 v[146:149], v200
	ds_read_b128 v[166:169], v200 offset:1024
	ds_read_b128 v[170:173], v200 offset:2048
	ds_read_b128 v[174:177], v200 offset:3072
	s_add_u32 s34, s30, 0xfff00080
	s_addc_u32 s35, s31, -1
	s_cmp_eq_u32 s52, 60
	s_cselect_b32 s37, s23, s35
	s_cselect_b32 s36, s48, s34
	s_cselect_b32 s35, s21, s51
	s_cselect_b32 s34, s49, s50
	v_lshl_add_u64 v[194:195], s[30:31], 0, v[158:159]
	s_add_i32 m0, s29, 0xc000
	ds_read_b128 v[178:181], v201
	ds_read_b128 v[182:185], v201 offset:1024
	ds_read_b128 v[186:189], v201 offset:2048
	ds_read_b128 v[190:193], v201 offset:3072
	ds_read_b128 v[202:205], v201 offset:4096
	ds_read_b128 v[206:209], v201 offset:5120
	ds_read_b128 v[210:213], v201 offset:6144
	ds_read_b128 v[214:217], v201 offset:7168
	global_load_lds_dwordx4 v[194:195], off
	v_lshl_add_u64 v[194:195], s[30:31], 0, v[160:161]
	s_add_i32 m0, s29, 0xe000
	s_nop 0
	global_load_lds_dwordx4 v[194:195], off
	s_waitcnt vmcnt(8)
	s_waitcnt lgkmcnt(0)
	s_setprio 1
	s_barrier
	v_mfma_f32_16x16x32_bf16 v[126:129], v[130:133], v[178:181], v[126:129]
	v_mfma_f32_16x16x32_bf16 v[122:125], v[138:141], v[178:181], v[122:125]
	v_mfma_f32_16x16x32_bf16 v[118:121], v[130:133], v[186:189], v[118:121]
	v_mfma_f32_16x16x32_bf16 v[114:117], v[138:141], v[186:189], v[114:117]
	v_mfma_f32_16x16x32_bf16 v[110:113], v[130:133], v[202:205], v[110:113]
	v_mfma_f32_16x16x32_bf16 v[106:109], v[138:141], v[202:205], v[106:109]
	v_mfma_f32_16x16x32_bf16 v[102:105], v[130:133], v[210:213], v[102:105]
	v_mfma_f32_16x16x32_bf16 v[98:101], v[138:141], v[210:213], v[98:101]
	v_mfma_f32_16x16x32_bf16 v[126:129], v[134:137], v[182:185], v[126:129]
	v_mfma_f32_16x16x32_bf16 v[122:125], v[142:145], v[182:185], v[122:125]
	v_mfma_f32_16x16x32_bf16 v[118:121], v[134:137], v[190:193], v[118:121]
	v_mfma_f32_16x16x32_bf16 v[114:117], v[142:145], v[190:193], v[114:117]
	v_mfma_f32_16x16x32_bf16 v[110:113], v[134:137], v[206:209], v[110:113]
	v_mfma_f32_16x16x32_bf16 v[106:109], v[142:145], v[206:209], v[106:109]
	v_mfma_f32_16x16x32_bf16 v[102:105], v[134:137], v[214:217], v[102:105]
	v_mfma_f32_16x16x32_bf16 v[98:101], v[142:145], v[214:217], v[98:101]
	v_mfma_f32_16x16x32_bf16 v[62:65], v[146:149], v[178:181], v[62:65]
	v_mfma_f32_16x16x32_bf16 v[58:61], v[170:173], v[178:181], v[58:61]
	v_mfma_f32_16x16x32_bf16 v[54:57], v[146:149], v[186:189], v[54:57]
	v_mfma_f32_16x16x32_bf16 v[50:53], v[170:173], v[186:189], v[50:53]
	v_mfma_f32_16x16x32_bf16 v[46:49], v[146:149], v[202:205], v[46:49]
	v_mfma_f32_16x16x32_bf16 v[42:45], v[170:173], v[202:205], v[42:45]
	v_mfma_f32_16x16x32_bf16 v[38:41], v[146:149], v[210:213], v[38:41]
	v_mfma_f32_16x16x32_bf16 v[34:37], v[170:173], v[210:213], v[34:37]
	v_mfma_f32_16x16x32_bf16 v[62:65], v[166:169], v[182:185], v[62:65]
	v_mfma_f32_16x16x32_bf16 v[58:61], v[174:177], v[182:185], v[58:61]
	v_mfma_f32_16x16x32_bf16 v[54:57], v[166:169], v[190:193], v[54:57]
	v_mfma_f32_16x16x32_bf16 v[50:53], v[174:177], v[190:193], v[50:53]
	v_mfma_f32_16x16x32_bf16 v[46:49], v[166:169], v[206:209], v[46:49]
	v_mfma_f32_16x16x32_bf16 v[42:45], v[174:177], v[206:209], v[42:45]
	v_mfma_f32_16x16x32_bf16 v[38:41], v[166:169], v[214:217], v[38:41]
	v_mfma_f32_16x16x32_bf16 v[34:37], v[174:177], v[214:217], v[34:37]
	s_barrier
	s_setprio 0
	s_add_i32 s53, s46, s38
	v_lshl_add_u64 v[194:195], s[34:35], 0, v[152:153]
	s_mov_b32 m0, s53
	ds_read_b128 v[178:181], v201 offset:16384
	ds_read_b128 v[182:185], v201 offset:17408
	ds_read_b128 v[186:189], v201 offset:18432
	ds_read_b128 v[190:193], v201 offset:19456
	ds_read_b128 v[202:205], v201 offset:20480
	ds_read_b128 v[206:209], v201 offset:21504
	ds_read_b128 v[210:213], v201 offset:22528
	ds_read_b128 v[214:217], v201 offset:23552
	global_load_lds_dwordx4 v[194:195], off
	s_add_i32 m0, s53, 0x2000
	s_add_u32 s54, s34, 0x100000
	v_lshl_add_u64 v[218:219], s[34:35], 0, v[156:157]
	s_addc_u32 s55, s35, 0
	s_add_i32 s53, s47, s38
	global_load_lds_dwordx4 v[218:219], off
	v_lshl_add_u64 v[220:221], s[54:55], 0, v[152:153]
	s_mov_b32 m0, s53
	v_lshl_add_u64 v[222:223], s[36:37], 0, v[154:155]
	global_load_lds_dwordx4 v[220:221], off
	v_lshl_add_u64 v[220:221], s[54:55], 0, v[156:157]
	s_add_i32 m0, s53, 0x2000
	s_nop 0
	global_load_lds_dwordx4 v[220:221], off
	v_lshl_add_u64 v[220:221], s[36:37], 0, v[150:151]
	s_mov_b32 m0, s29
	s_nop 0
	global_load_lds_dwordx4 v[220:221], off
	s_mov_b32 m0, s39
	s_nop 0
	global_load_lds_dwordx4 v[222:223], off
	s_waitcnt vmcnt(8)
	s_waitcnt lgkmcnt(0)
	s_setprio 1
	s_barrier
	v_mfma_f32_16x16x32_bf16 v[94:97], v[130:133], v[178:181], v[94:97]
	v_mfma_f32_16x16x32_bf16 v[90:93], v[138:141], v[178:181], v[90:93]
	v_mfma_f32_16x16x32_bf16 v[86:89], v[130:133], v[186:189], v[86:89]
	v_mfma_f32_16x16x32_bf16 v[82:85], v[138:141], v[186:189], v[82:85]
	v_mfma_f32_16x16x32_bf16 v[78:81], v[130:133], v[202:205], v[78:81]
	v_mfma_f32_16x16x32_bf16 v[74:77], v[138:141], v[202:205], v[74:77]
	v_mfma_f32_16x16x32_bf16 v[70:73], v[130:133], v[210:213], v[70:73]
	v_mfma_f32_16x16x32_bf16 v[66:69], v[138:141], v[210:213], v[66:69]
	v_mfma_f32_16x16x32_bf16 v[94:97], v[134:137], v[182:185], v[94:97]
	v_mfma_f32_16x16x32_bf16 v[90:93], v[142:145], v[182:185], v[90:93]
	v_mfma_f32_16x16x32_bf16 v[86:89], v[134:137], v[190:193], v[86:89]
	v_mfma_f32_16x16x32_bf16 v[82:85], v[142:145], v[190:193], v[82:85]
	v_mfma_f32_16x16x32_bf16 v[78:81], v[134:137], v[206:209], v[78:81]
	v_mfma_f32_16x16x32_bf16 v[74:77], v[142:145], v[206:209], v[74:77]
	v_mfma_f32_16x16x32_bf16 v[70:73], v[134:137], v[214:217], v[70:73]
	v_mfma_f32_16x16x32_bf16 v[66:69], v[142:145], v[214:217], v[66:69]
	v_mfma_f32_16x16x32_bf16 v[30:33], v[146:149], v[178:181], v[30:33]
	v_mfma_f32_16x16x32_bf16 v[26:29], v[170:173], v[178:181], v[26:29]
	v_mfma_f32_16x16x32_bf16 v[22:25], v[146:149], v[186:189], v[22:25]
	v_mfma_f32_16x16x32_bf16 v[18:21], v[170:173], v[186:189], v[18:21]
	v_mfma_f32_16x16x32_bf16 v[14:17], v[146:149], v[202:205], v[14:17]
	v_mfma_f32_16x16x32_bf16 v[10:13], v[170:173], v[202:205], v[10:13]
	v_mfma_f32_16x16x32_bf16 v[6:9], v[146:149], v[210:213], v[6:9]
	v_mfma_f32_16x16x32_bf16 v[2:5], v[170:173], v[210:213], v[2:5]
	v_mfma_f32_16x16x32_bf16 v[30:33], v[166:169], v[182:185], v[30:33]
	v_mfma_f32_16x16x32_bf16 v[26:29], v[174:177], v[182:185], v[26:29]
	v_mfma_f32_16x16x32_bf16 v[22:25], v[166:169], v[190:193], v[22:25]
	v_mfma_f32_16x16x32_bf16 v[18:21], v[174:177], v[190:193], v[18:21]
	v_mfma_f32_16x16x32_bf16 v[14:17], v[166:169], v[206:209], v[14:17]
	v_mfma_f32_16x16x32_bf16 v[10:13], v[174:177], v[206:209], v[10:13]
	v_mfma_f32_16x16x32_bf16 v[6:9], v[166:169], v[214:217], v[6:9]
	v_mfma_f32_16x16x32_bf16 v[2:5], v[174:177], v[214:217], v[2:5]
	s_barrier
	s_setprio 0
	s_add_i32 s53, 0, 0x18000
	s_add_i32 s54, 0, 0x1c000
	v_add_u32_e32 v142, s53, v197
	v_add_u32_e32 v174, s54, v197
	ds_read_b128 v[130:133], v142
	ds_read_b128 v[134:137], v142 offset:1024
	ds_read_b128 v[138:141], v142 offset:2048
	ds_read_b128 v[142:145], v142 offset:3072
	ds_read_b128 v[146:149], v174
	ds_read_b128 v[166:169], v174 offset:1024
	ds_read_b128 v[170:173], v174 offset:2048
	ds_read_b128 v[174:177], v174 offset:3072
	s_add_u32 s36, s36, 0x100000
	s_addc_u32 s37, s37, 0
	s_mov_b32 m0, s40
	v_lshl_add_u64 v[224:225], s[36:37], 0, v[150:151]
	ds_read_b128 v[178:181], v201 offset:32768
	ds_read_b128 v[182:185], v201 offset:33792
	ds_read_b128 v[186:189], v201 offset:34816
	ds_read_b128 v[190:193], v201 offset:35840
	ds_read_b128 v[202:205], v201 offset:36864
	ds_read_b128 v[206:209], v201 offset:37888
	ds_read_b128 v[210:213], v201 offset:38912
	ds_read_b128 v[214:217], v201 offset:39936
	global_load_lds_dwordx4 v[224:225], off
	v_lshl_add_u64 v[224:225], s[36:37], 0, v[154:155]
	s_mov_b32 m0, s41
	s_nop 0
	global_load_lds_dwordx4 v[224:225], off
	s_waitcnt vmcnt(8)
	s_waitcnt lgkmcnt(0)
	s_setprio 1
	s_barrier
	v_mfma_f32_16x16x32_bf16 v[126:129], v[130:133], v[178:181], v[126:129]
	v_mfma_f32_16x16x32_bf16 v[122:125], v[138:141], v[178:181], v[122:125]
	v_mfma_f32_16x16x32_bf16 v[118:121], v[130:133], v[186:189], v[118:121]
	v_mfma_f32_16x16x32_bf16 v[114:117], v[138:141], v[186:189], v[114:117]
	v_mfma_f32_16x16x32_bf16 v[110:113], v[130:133], v[202:205], v[110:113]
	v_mfma_f32_16x16x32_bf16 v[106:109], v[138:141], v[202:205], v[106:109]
	v_mfma_f32_16x16x32_bf16 v[102:105], v[130:133], v[210:213], v[102:105]
	v_mfma_f32_16x16x32_bf16 v[98:101], v[138:141], v[210:213], v[98:101]
	v_mfma_f32_16x16x32_bf16 v[126:129], v[134:137], v[182:185], v[126:129]
	v_mfma_f32_16x16x32_bf16 v[122:125], v[142:145], v[182:185], v[122:125]
	v_mfma_f32_16x16x32_bf16 v[118:121], v[134:137], v[190:193], v[118:121]
	v_mfma_f32_16x16x32_bf16 v[114:117], v[142:145], v[190:193], v[114:117]
	v_mfma_f32_16x16x32_bf16 v[110:113], v[134:137], v[206:209], v[110:113]
	v_mfma_f32_16x16x32_bf16 v[106:109], v[142:145], v[206:209], v[106:109]
	v_mfma_f32_16x16x32_bf16 v[102:105], v[134:137], v[214:217], v[102:105]
	v_mfma_f32_16x16x32_bf16 v[98:101], v[142:145], v[214:217], v[98:101]
	v_mfma_f32_16x16x32_bf16 v[62:65], v[146:149], v[178:181], v[62:65]
	v_mfma_f32_16x16x32_bf16 v[58:61], v[170:173], v[178:181], v[58:61]
	v_mfma_f32_16x16x32_bf16 v[54:57], v[146:149], v[186:189], v[54:57]
	v_mfma_f32_16x16x32_bf16 v[50:53], v[170:173], v[186:189], v[50:53]
	v_mfma_f32_16x16x32_bf16 v[46:49], v[146:149], v[202:205], v[46:49]
	v_mfma_f32_16x16x32_bf16 v[42:45], v[170:173], v[202:205], v[42:45]
	v_mfma_f32_16x16x32_bf16 v[38:41], v[146:149], v[210:213], v[38:41]
	v_mfma_f32_16x16x32_bf16 v[34:37], v[170:173], v[210:213], v[34:37]
	v_mfma_f32_16x16x32_bf16 v[62:65], v[166:169], v[182:185], v[62:65]
	v_mfma_f32_16x16x32_bf16 v[58:61], v[174:177], v[182:185], v[58:61]
	v_mfma_f32_16x16x32_bf16 v[54:57], v[166:169], v[190:193], v[54:57]
	v_mfma_f32_16x16x32_bf16 v[50:53], v[174:177], v[190:193], v[50:53]
	v_mfma_f32_16x16x32_bf16 v[46:49], v[166:169], v[206:209], v[46:49]
	v_mfma_f32_16x16x32_bf16 v[42:45], v[174:177], v[206:209], v[42:45]
	v_mfma_f32_16x16x32_bf16 v[38:41], v[166:169], v[214:217], v[38:41]
	v_mfma_f32_16x16x32_bf16 v[34:37], v[174:177], v[214:217], v[34:37]
	s_barrier
	s_setprio 0
	s_add_i32 s36, s53, s38
	v_lshl_add_u64 v[194:195], v[194:195], 0, s[14:15]
	s_mov_b32 m0, s36
	ds_read_b128 v[178:181], v201 offset:49152
	ds_read_b128 v[182:185], v201 offset:50176
	ds_read_b128 v[186:189], v201 offset:51200
	ds_read_b128 v[190:193], v201 offset:52224
	ds_read_b128 v[202:205], v201 offset:53248
	ds_read_b128 v[206:209], v201 offset:54272
	ds_read_b128 v[210:213], v201 offset:55296
	ds_read_b128 v[214:217], v201 offset:56320
	global_load_lds_dwordx4 v[194:195], off
	s_add_i32 m0, s36, 0x2000
	s_add_u32 s34, s34, 0x100080
	v_lshl_add_u64 v[194:195], v[218:219], 0, s[14:15]
	s_addc_u32 s35, s35, 0
	s_add_i32 s36, s54, s38
	global_load_lds_dwordx4 v[194:195], off
	v_lshl_add_u64 v[194:195], s[34:35], 0, v[152:153]
	s_mov_b32 m0, s36
	s_nop 0
	global_load_lds_dwordx4 v[194:195], off
	v_lshl_add_u64 v[194:195], s[34:35], 0, v[156:157]
	s_add_i32 m0, s36, 0x2000
	s_nop 0
	global_load_lds_dwordx4 v[194:195], off
	v_lshl_add_u64 v[194:195], v[220:221], 0, s[14:15]
	s_mov_b32 m0, s43
	s_nop 0
	global_load_lds_dwordx4 v[194:195], off
	v_lshl_add_u64 v[194:195], v[222:223], 0, s[14:15]
	s_mov_b32 m0, s44
	s_nop 0
	global_load_lds_dwordx4 v[194:195], off
	s_waitcnt vmcnt(8)
	s_waitcnt lgkmcnt(0)
	s_setprio 1
	s_barrier
	v_mfma_f32_16x16x32_bf16 v[94:97], v[130:133], v[178:181], v[94:97]
	v_mfma_f32_16x16x32_bf16 v[90:93], v[138:141], v[178:181], v[90:93]
	v_mfma_f32_16x16x32_bf16 v[86:89], v[130:133], v[186:189], v[86:89]
	v_mfma_f32_16x16x32_bf16 v[82:85], v[138:141], v[186:189], v[82:85]
	v_mfma_f32_16x16x32_bf16 v[78:81], v[130:133], v[202:205], v[78:81]
	v_mfma_f32_16x16x32_bf16 v[74:77], v[138:141], v[202:205], v[74:77]
	v_mfma_f32_16x16x32_bf16 v[70:73], v[130:133], v[210:213], v[70:73]
	v_mfma_f32_16x16x32_bf16 v[66:69], v[138:141], v[210:213], v[66:69]
	v_mfma_f32_16x16x32_bf16 v[94:97], v[134:137], v[182:185], v[94:97]
	v_mfma_f32_16x16x32_bf16 v[90:93], v[142:145], v[182:185], v[90:93]
	v_mfma_f32_16x16x32_bf16 v[86:89], v[134:137], v[190:193], v[86:89]
	v_mfma_f32_16x16x32_bf16 v[82:85], v[142:145], v[190:193], v[82:85]
	v_mfma_f32_16x16x32_bf16 v[78:81], v[134:137], v[206:209], v[78:81]
	v_mfma_f32_16x16x32_bf16 v[74:77], v[142:145], v[206:209], v[74:77]
	v_mfma_f32_16x16x32_bf16 v[70:73], v[134:137], v[214:217], v[70:73]
	v_mfma_f32_16x16x32_bf16 v[66:69], v[142:145], v[214:217], v[66:69]
	v_mfma_f32_16x16x32_bf16 v[30:33], v[146:149], v[178:181], v[30:33]
	v_mfma_f32_16x16x32_bf16 v[26:29], v[170:173], v[178:181], v[26:29]
	v_mfma_f32_16x16x32_bf16 v[22:25], v[146:149], v[186:189], v[22:25]
	v_mfma_f32_16x16x32_bf16 v[18:21], v[170:173], v[186:189], v[18:21]
	v_mfma_f32_16x16x32_bf16 v[14:17], v[146:149], v[202:205], v[14:17]
	v_mfma_f32_16x16x32_bf16 v[10:13], v[170:173], v[202:205], v[10:13]
	v_mfma_f32_16x16x32_bf16 v[6:9], v[146:149], v[210:213], v[6:9]
	v_mfma_f32_16x16x32_bf16 v[2:5], v[170:173], v[210:213], v[2:5]
	v_mfma_f32_16x16x32_bf16 v[30:33], v[166:169], v[182:185], v[30:33]
	v_mfma_f32_16x16x32_bf16 v[26:29], v[174:177], v[182:185], v[26:29]
	v_mfma_f32_16x16x32_bf16 v[22:25], v[166:169], v[190:193], v[22:25]
	v_mfma_f32_16x16x32_bf16 v[18:21], v[174:177], v[190:193], v[18:21]
	v_mfma_f32_16x16x32_bf16 v[14:17], v[166:169], v[206:209], v[14:17]
	v_mfma_f32_16x16x32_bf16 v[10:13], v[174:177], v[206:209], v[10:13]
	v_mfma_f32_16x16x32_bf16 v[6:9], v[166:169], v[214:217], v[6:9]
	v_mfma_f32_16x16x32_bf16 v[2:5], v[174:177], v[214:217], v[2:5]
	s_barrier
	s_setprio 0
	s_add_i32 s52, s52, 2
	s_add_u32 s30, s30, 0x100
	s_addc_u32 s31, s31, 0
	s_add_u32 s50, s50, 0x100
	s_addc_u32 s51, s51, 0
	s_cmp_gt_u32 s52, 61
	s_cbranch_scc0 .LBB0_2142
	s_and_b64 vcc, exec, s[16:17]
	s_cbranch_vccz .LBB0_2145
	s_barrier

.LBB0_2369:
	ds_read_b128 v[130:133], v197
	ds_read_b128 v[134:137], v197 offset:1024
	ds_read_b128 v[138:141], v197 offset:2048
	ds_read_b128 v[142:145], v197 offset:3072
	ds_read_b128 v[146:149], v198
	ds_read_b128 v[166:169], v198 offset:1024
	ds_read_b128 v[170:173], v198 offset:2048
	ds_read_b128 v[174:177], v198 offset:3072
	s_add_u32 s28, s26, 0xffd50080
	s_addc_u32 s29, s27, -1
	s_cmpk_eq_i32 s52, 0xa8
	s_cselect_b32 s31, s9, s29
	s_cselect_b32 s30, s8, s28
	s_cselect_b32 s29, s25, s51
	s_cselect_b32 s28, s24, s50
	v_lshl_add_u64 v[216:217], s[26:27], 0, v[158:159]
	s_add_i32 m0, s37, 0xc000
	ds_read_b128 v[178:181], v199
	ds_read_b128 v[182:185], v199 offset:1024
	ds_read_b128 v[186:189], v199 offset:2048
	ds_read_b128 v[190:193], v199 offset:3072
	ds_read_b128 v[200:203], v199 offset:4096
	ds_read_b128 v[204:207], v199 offset:5120
	ds_read_b128 v[208:211], v199 offset:6144
	ds_read_b128 v[212:215], v199 offset:7168
	global_load_lds_dwordx4 v[216:217], off
	v_lshl_add_u64 v[216:217], s[26:27], 0, v[160:161]
	s_add_i32 m0, s37, 0xe000
	s_nop 0
	global_load_lds_dwordx4 v[216:217], off
	s_waitcnt vmcnt(8)
	s_waitcnt lgkmcnt(0)
	s_setprio 1
	s_barrier
	v_mfma_f32_16x16x32_bf16 v[126:129], v[130:133], v[178:181], v[126:129]
	v_mfma_f32_16x16x32_bf16 v[122:125], v[138:141], v[178:181], v[122:125]
	v_mfma_f32_16x16x32_bf16 v[118:121], v[130:133], v[186:189], v[118:121]
	v_mfma_f32_16x16x32_bf16 v[114:117], v[138:141], v[186:189], v[114:117]
	v_mfma_f32_16x16x32_bf16 v[110:113], v[130:133], v[200:203], v[110:113]
	v_mfma_f32_16x16x32_bf16 v[106:109], v[138:141], v[200:203], v[106:109]
	v_mfma_f32_16x16x32_bf16 v[102:105], v[130:133], v[208:211], v[102:105]
	v_mfma_f32_16x16x32_bf16 v[98:101], v[138:141], v[208:211], v[98:101]
	v_mfma_f32_16x16x32_bf16 v[126:129], v[134:137], v[182:185], v[126:129]
	v_mfma_f32_16x16x32_bf16 v[122:125], v[142:145], v[182:185], v[122:125]
	v_mfma_f32_16x16x32_bf16 v[118:121], v[134:137], v[190:193], v[118:121]
	v_mfma_f32_16x16x32_bf16 v[114:117], v[142:145], v[190:193], v[114:117]
	v_mfma_f32_16x16x32_bf16 v[110:113], v[134:137], v[204:207], v[110:113]
	v_mfma_f32_16x16x32_bf16 v[106:109], v[142:145], v[204:207], v[106:109]
	v_mfma_f32_16x16x32_bf16 v[102:105], v[134:137], v[212:215], v[102:105]
	v_mfma_f32_16x16x32_bf16 v[98:101], v[142:145], v[212:215], v[98:101]
	v_mfma_f32_16x16x32_bf16 v[62:65], v[146:149], v[178:181], v[62:65]
	v_mfma_f32_16x16x32_bf16 v[58:61], v[170:173], v[178:181], v[58:61]
	v_mfma_f32_16x16x32_bf16 v[54:57], v[146:149], v[186:189], v[54:57]
	v_mfma_f32_16x16x32_bf16 v[50:53], v[170:173], v[186:189], v[50:53]
	v_mfma_f32_16x16x32_bf16 v[46:49], v[146:149], v[200:203], v[46:49]
	v_mfma_f32_16x16x32_bf16 v[42:45], v[170:173], v[200:203], v[42:45]
	v_mfma_f32_16x16x32_bf16 v[38:41], v[146:149], v[208:211], v[38:41]
	v_mfma_f32_16x16x32_bf16 v[34:37], v[170:173], v[208:211], v[34:37]
	v_mfma_f32_16x16x32_bf16 v[62:65], v[166:169], v[182:185], v[62:65]
	v_mfma_f32_16x16x32_bf16 v[58:61], v[174:177], v[182:185], v[58:61]
	v_mfma_f32_16x16x32_bf16 v[54:57], v[166:169], v[190:193], v[54:57]
	v_mfma_f32_16x16x32_bf16 v[50:53], v[174:177], v[190:193], v[50:53]
	v_mfma_f32_16x16x32_bf16 v[46:49], v[166:169], v[204:207], v[46:49]
	v_mfma_f32_16x16x32_bf16 v[42:45], v[174:177], v[204:207], v[42:45]
	v_mfma_f32_16x16x32_bf16 v[38:41], v[166:169], v[212:215], v[38:41]
	v_mfma_f32_16x16x32_bf16 v[34:37], v[174:177], v[212:215], v[34:37]
	s_barrier
	s_setprio 0
	s_add_i32 s53, s45, s36
	v_lshl_add_u64 v[216:217], s[28:29], 0, v[152:153]
	s_mov_b32 m0, s53
	ds_read_b128 v[178:181], v199 offset:16384
	ds_read_b128 v[182:185], v199 offset:17408
	ds_read_b128 v[186:189], v199 offset:18432
	ds_read_b128 v[190:193], v199 offset:19456
	ds_read_b128 v[200:203], v199 offset:20480
	ds_read_b128 v[204:207], v199 offset:21504
	ds_read_b128 v[208:211], v199 offset:22528
	ds_read_b128 v[212:215], v199 offset:23552
	global_load_lds_dwordx4 v[216:217], off
	s_add_i32 m0, s53, 0x2000
	s_add_u32 s54, s28, 0x2b0000
	v_lshl_add_u64 v[218:219], s[28:29], 0, v[156:157]
	s_addc_u32 s55, s29, 0
	s_add_i32 s53, s46, s36
	global_load_lds_dwordx4 v[218:219], off
	v_lshl_add_u64 v[220:221], s[54:55], 0, v[152:153]
	s_mov_b32 m0, s53
	v_lshl_add_u64 v[222:223], s[30:31], 0, v[154:155]
	global_load_lds_dwordx4 v[220:221], off
	v_lshl_add_u64 v[220:221], s[54:55], 0, v[156:157]
	s_add_i32 m0, s53, 0x2000
	s_nop 0
	global_load_lds_dwordx4 v[220:221], off
	v_lshl_add_u64 v[220:221], s[30:31], 0, v[150:151]
	s_mov_b32 m0, s37
	s_nop 0
	global_load_lds_dwordx4 v[220:221], off
	s_mov_b32 m0, s38
	s_nop 0
	global_load_lds_dwordx4 v[222:223], off
	s_waitcnt vmcnt(8)
	s_waitcnt lgkmcnt(0)
	s_setprio 1
	s_barrier
	v_mfma_f32_16x16x32_bf16 v[94:97], v[130:133], v[178:181], v[94:97]
	v_mfma_f32_16x16x32_bf16 v[90:93], v[138:141], v[178:181], v[90:93]
	v_mfma_f32_16x16x32_bf16 v[86:89], v[130:133], v[186:189], v[86:89]
	v_mfma_f32_16x16x32_bf16 v[82:85], v[138:141], v[186:189], v[82:85]
	v_mfma_f32_16x16x32_bf16 v[78:81], v[130:133], v[200:203], v[78:81]
	v_mfma_f32_16x16x32_bf16 v[74:77], v[138:141], v[200:203], v[74:77]
	v_mfma_f32_16x16x32_bf16 v[70:73], v[130:133], v[208:211], v[70:73]
	v_mfma_f32_16x16x32_bf16 v[66:69], v[138:141], v[208:211], v[66:69]
	v_mfma_f32_16x16x32_bf16 v[94:97], v[134:137], v[182:185], v[94:97]
	v_mfma_f32_16x16x32_bf16 v[90:93], v[142:145], v[182:185], v[90:93]
	v_mfma_f32_16x16x32_bf16 v[86:89], v[134:137], v[190:193], v[86:89]
	v_mfma_f32_16x16x32_bf16 v[82:85], v[142:145], v[190:193], v[82:85]
	v_mfma_f32_16x16x32_bf16 v[78:81], v[134:137], v[204:207], v[78:81]
	v_mfma_f32_16x16x32_bf16 v[74:77], v[142:145], v[204:207], v[74:77]
	v_mfma_f32_16x16x32_bf16 v[70:73], v[134:137], v[212:215], v[70:73]
	v_mfma_f32_16x16x32_bf16 v[66:69], v[142:145], v[212:215], v[66:69]
	v_mfma_f32_16x16x32_bf16 v[30:33], v[146:149], v[178:181], v[30:33]
	v_mfma_f32_16x16x32_bf16 v[26:29], v[170:173], v[178:181], v[26:29]
	v_mfma_f32_16x16x32_bf16 v[22:25], v[146:149], v[186:189], v[22:25]
	v_mfma_f32_16x16x32_bf16 v[18:21], v[170:173], v[186:189], v[18:21]
	v_mfma_f32_16x16x32_bf16 v[14:17], v[146:149], v[200:203], v[14:17]
	v_mfma_f32_16x16x32_bf16 v[10:13], v[170:173], v[200:203], v[10:13]
	v_mfma_f32_16x16x32_bf16 v[6:9], v[146:149], v[208:211], v[6:9]
	v_mfma_f32_16x16x32_bf16 v[2:5], v[170:173], v[208:211], v[2:5]
	v_mfma_f32_16x16x32_bf16 v[30:33], v[166:169], v[182:185], v[30:33]
	v_mfma_f32_16x16x32_bf16 v[26:29], v[174:177], v[182:185], v[26:29]
	v_mfma_f32_16x16x32_bf16 v[22:25], v[166:169], v[190:193], v[22:25]
	v_mfma_f32_16x16x32_bf16 v[18:21], v[174:177], v[190:193], v[18:21]
	v_mfma_f32_16x16x32_bf16 v[14:17], v[166:169], v[204:207], v[14:17]
	v_mfma_f32_16x16x32_bf16 v[10:13], v[174:177], v[204:207], v[10:13]
	v_mfma_f32_16x16x32_bf16 v[6:9], v[166:169], v[212:215], v[6:9]
	v_mfma_f32_16x16x32_bf16 v[2:5], v[174:177], v[212:215], v[2:5]
	s_barrier
	s_setprio 0
	s_add_i32 s53, 0, 0x18000
	s_add_i32 s54, 0, 0x1c000
	v_add_u32_e32 v142, s53, v195
	v_add_u32_e32 v174, s54, v195
	ds_read_b128 v[130:133], v142
	ds_read_b128 v[134:137], v142 offset:1024
	ds_read_b128 v[138:141], v142 offset:2048
	ds_read_b128 v[142:145], v142 offset:3072
	ds_read_b128 v[146:149], v174
	ds_read_b128 v[166:169], v174 offset:1024
	ds_read_b128 v[170:173], v174 offset:2048
	ds_read_b128 v[174:177], v174 offset:3072
	s_add_u32 s30, s30, 0x2b0000
	s_addc_u32 s31, s31, 0
	s_mov_b32 m0, s39
	v_lshl_add_u64 v[224:225], s[30:31], 0, v[150:151]
	ds_read_b128 v[178:181], v199 offset:32768
	ds_read_b128 v[182:185], v199 offset:33792
	ds_read_b128 v[186:189], v199 offset:34816
	ds_read_b128 v[190:193], v199 offset:35840
	ds_read_b128 v[200:203], v199 offset:36864
	ds_read_b128 v[204:207], v199 offset:37888
	ds_read_b128 v[208:211], v199 offset:38912
	ds_read_b128 v[212:215], v199 offset:39936
	global_load_lds_dwordx4 v[224:225], off
	v_lshl_add_u64 v[224:225], s[30:31], 0, v[154:155]
	s_mov_b32 m0, s40
	s_nop 0
	global_load_lds_dwordx4 v[224:225], off
	s_waitcnt vmcnt(8)
	s_waitcnt lgkmcnt(0)
	s_setprio 1
	s_barrier
	v_mfma_f32_16x16x32_bf16 v[126:129], v[130:133], v[178:181], v[126:129]
	v_mfma_f32_16x16x32_bf16 v[122:125], v[138:141], v[178:181], v[122:125]
	v_mfma_f32_16x16x32_bf16 v[118:121], v[130:133], v[186:189], v[118:121]
	v_mfma_f32_16x16x32_bf16 v[114:117], v[138:141], v[186:189], v[114:117]
	v_mfma_f32_16x16x32_bf16 v[110:113], v[130:133], v[200:203], v[110:113]
	v_mfma_f32_16x16x32_bf16 v[106:109], v[138:141], v[200:203], v[106:109]
	v_mfma_f32_16x16x32_bf16 v[102:105], v[130:133], v[208:211], v[102:105]
	v_mfma_f32_16x16x32_bf16 v[98:101], v[138:141], v[208:211], v[98:101]
	v_mfma_f32_16x16x32_bf16 v[126:129], v[134:137], v[182:185], v[126:129]
	v_mfma_f32_16x16x32_bf16 v[122:125], v[142:145], v[182:185], v[122:125]
	v_mfma_f32_16x16x32_bf16 v[118:121], v[134:137], v[190:193], v[118:121]
	v_mfma_f32_16x16x32_bf16 v[114:117], v[142:145], v[190:193], v[114:117]
	v_mfma_f32_16x16x32_bf16 v[110:113], v[134:137], v[204:207], v[110:113]
	v_mfma_f32_16x16x32_bf16 v[106:109], v[142:145], v[204:207], v[106:109]
	v_mfma_f32_16x16x32_bf16 v[102:105], v[134:137], v[212:215], v[102:105]
	v_mfma_f32_16x16x32_bf16 v[98:101], v[142:145], v[212:215], v[98:101]
	v_mfma_f32_16x16x32_bf16 v[62:65], v[146:149], v[178:181], v[62:65]
	v_mfma_f32_16x16x32_bf16 v[58:61], v[170:173], v[178:181], v[58:61]
	v_mfma_f32_16x16x32_bf16 v[54:57], v[146:149], v[186:189], v[54:57]
	v_mfma_f32_16x16x32_bf16 v[50:53], v[170:173], v[186:189], v[50:53]
	v_mfma_f32_16x16x32_bf16 v[46:49], v[146:149], v[200:203], v[46:49]
	v_mfma_f32_16x16x32_bf16 v[42:45], v[170:173], v[200:203], v[42:45]
	v_mfma_f32_16x16x32_bf16 v[38:41], v[146:149], v[208:211], v[38:41]
	v_mfma_f32_16x16x32_bf16 v[34:37], v[170:173], v[208:211], v[34:37]
	v_mfma_f32_16x16x32_bf16 v[62:65], v[166:169], v[182:185], v[62:65]
	v_mfma_f32_16x16x32_bf16 v[58:61], v[174:177], v[182:185], v[58:61]
	v_mfma_f32_16x16x32_bf16 v[54:57], v[166:169], v[190:193], v[54:57]
	v_mfma_f32_16x16x32_bf16 v[50:53], v[174:177], v[190:193], v[50:53]
	v_mfma_f32_16x16x32_bf16 v[46:49], v[166:169], v[204:207], v[46:49]
	v_mfma_f32_16x16x32_bf16 v[42:45], v[174:177], v[204:207], v[42:45]
	v_mfma_f32_16x16x32_bf16 v[38:41], v[166:169], v[212:215], v[38:41]
	v_mfma_f32_16x16x32_bf16 v[34:37], v[174:177], v[212:215], v[34:37]
	s_barrier
	s_setprio 0
	s_add_i32 s30, s53, s36
	v_lshl_add_u64 v[216:217], v[216:217], 0, s[18:19]
	s_mov_b32 m0, s30
	ds_read_b128 v[178:181], v199 offset:49152
	ds_read_b128 v[182:185], v199 offset:50176
	ds_read_b128 v[186:189], v199 offset:51200
	ds_read_b128 v[190:193], v199 offset:52224
	ds_read_b128 v[200:203], v199 offset:53248
	ds_read_b128 v[204:207], v199 offset:54272
	ds_read_b128 v[208:211], v199 offset:55296
	ds_read_b128 v[212:215], v199 offset:56320
	global_load_lds_dwordx4 v[216:217], off
	s_add_i32 m0, s30, 0x2000
	s_add_u32 s28, s28, 0x2b0080
	v_lshl_add_u64 v[216:217], v[218:219], 0, s[18:19]
	s_addc_u32 s29, s29, 0
	s_add_i32 s30, s54, s36
	global_load_lds_dwordx4 v[216:217], off
	v_lshl_add_u64 v[216:217], s[28:29], 0, v[152:153]
	s_mov_b32 m0, s30
	s_nop 0
	global_load_lds_dwordx4 v[216:217], off
	v_lshl_add_u64 v[216:217], s[28:29], 0, v[156:157]
	s_add_i32 m0, s30, 0x2000
	s_nop 0
	global_load_lds_dwordx4 v[216:217], off
	v_lshl_add_u64 v[216:217], v[220:221], 0, s[18:19]
	s_mov_b32 m0, s42
	s_nop 0
	global_load_lds_dwordx4 v[216:217], off
	v_lshl_add_u64 v[216:217], v[222:223], 0, s[18:19]
	s_mov_b32 m0, s43
	s_nop 0
	global_load_lds_dwordx4 v[216:217], off
	s_waitcnt vmcnt(8)
	s_waitcnt lgkmcnt(0)
	s_setprio 1
	s_barrier
	v_mfma_f32_16x16x32_bf16 v[94:97], v[130:133], v[178:181], v[94:97]
	v_mfma_f32_16x16x32_bf16 v[90:93], v[138:141], v[178:181], v[90:93]
	v_mfma_f32_16x16x32_bf16 v[86:89], v[130:133], v[186:189], v[86:89]
	v_mfma_f32_16x16x32_bf16 v[82:85], v[138:141], v[186:189], v[82:85]
	v_mfma_f32_16x16x32_bf16 v[78:81], v[130:133], v[200:203], v[78:81]
	v_mfma_f32_16x16x32_bf16 v[74:77], v[138:141], v[200:203], v[74:77]
	v_mfma_f32_16x16x32_bf16 v[70:73], v[130:133], v[208:211], v[70:73]
	v_mfma_f32_16x16x32_bf16 v[66:69], v[138:141], v[208:211], v[66:69]
	v_mfma_f32_16x16x32_bf16 v[94:97], v[134:137], v[182:185], v[94:97]
	v_mfma_f32_16x16x32_bf16 v[90:93], v[142:145], v[182:185], v[90:93]
	v_mfma_f32_16x16x32_bf16 v[86:89], v[134:137], v[190:193], v[86:89]
	v_mfma_f32_16x16x32_bf16 v[82:85], v[142:145], v[190:193], v[82:85]
	v_mfma_f32_16x16x32_bf16 v[78:81], v[134:137], v[204:207], v[78:81]
	v_mfma_f32_16x16x32_bf16 v[74:77], v[142:145], v[204:207], v[74:77]
	v_mfma_f32_16x16x32_bf16 v[70:73], v[134:137], v[212:215], v[70:73]
	v_mfma_f32_16x16x32_bf16 v[66:69], v[142:145], v[212:215], v[66:69]
	v_mfma_f32_16x16x32_bf16 v[30:33], v[146:149], v[178:181], v[30:33]
	v_mfma_f32_16x16x32_bf16 v[26:29], v[170:173], v[178:181], v[26:29]
	v_mfma_f32_16x16x32_bf16 v[22:25], v[146:149], v[186:189], v[22:25]
	v_mfma_f32_16x16x32_bf16 v[18:21], v[170:173], v[186:189], v[18:21]
	v_mfma_f32_16x16x32_bf16 v[14:17], v[146:149], v[200:203], v[14:17]
	v_mfma_f32_16x16x32_bf16 v[10:13], v[170:173], v[200:203], v[10:13]
	v_mfma_f32_16x16x32_bf16 v[6:9], v[146:149], v[208:211], v[6:9]
	v_mfma_f32_16x16x32_bf16 v[2:5], v[170:173], v[208:211], v[2:5]
	v_mfma_f32_16x16x32_bf16 v[30:33], v[166:169], v[182:185], v[30:33]
	v_mfma_f32_16x16x32_bf16 v[26:29], v[174:177], v[182:185], v[26:29]
	v_mfma_f32_16x16x32_bf16 v[22:25], v[166:169], v[190:193], v[22:25]
	v_mfma_f32_16x16x32_bf16 v[18:21], v[174:177], v[190:193], v[18:21]
	v_mfma_f32_16x16x32_bf16 v[14:17], v[166:169], v[204:207], v[14:17]
	v_mfma_f32_16x16x32_bf16 v[10:13], v[174:177], v[204:207], v[10:13]
	v_mfma_f32_16x16x32_bf16 v[6:9], v[166:169], v[212:215], v[6:9]
	v_mfma_f32_16x16x32_bf16 v[2:5], v[174:177], v[212:215], v[2:5]
	s_barrier
	s_setprio 0
	s_add_i32 s52, s52, 2
	s_add_u32 s26, s26, 0x100
	s_addc_u32 s27, s27, 0
	s_add_u32 s50, s50, 0x100
	s_addc_u32 s51, s51, 0
	s_cmpk_gt_u32 s52, 0xa9
	s_cbranch_scc0 .LBB0_2369
	s_and_b64 vcc, exec, s[20:21]
	s_cbranch_vccz .LBB0_2372
	s_barrier
